# scan: mid-chunk barrier lets the consumer prefetch the next chunk's first token before the end barrier; per-item address registers
# baseline (speedup 1.0000x reference)
; #define LAS __attribute__((address_space(3)))
; template <int CTRL> __device__ __forceinline__ float dpp_f(float x) { return __int_as_float(__builtin_amdgcn_update_dpp(0, __float_as_int(x), CTRL, 0xf, 0xf, false)); }
; __device__ __forceinline__ void p8_scan(const Args& a, LAS unsigned char* lds) {
;     ...
;             for (int c = 0; c < T / TC; ++c) {
;                 const int cur = c & 1;
;                 const LAS float* bt = buf + cur * TC * SPITCH;
;                 LAS float* yd = holds_y ? (ybuf + cur * TC * 64 + 4 * (4 * w + (lane >> 4)) + ((lane & 15) >> 2)) : (dump + lane);
;                 ScanOps o; scan_ld(o, bt, jq4, myrow);
; #pragma unroll 16
;                 for (int tt = 0; tt < TC; ++tt) {
;                     ScanOps n; scan_ld(n, bt + (tt + 1 < TC ? tt + 1 : tt) * SPITCH, jq4, myrow);
;                     __builtin_amdgcn_sched_barrier(0);
;                     f32x2 ta = S01 * o.al.lo, ty = S01 * o.wr.lo; ta = S23 * o.al.hi + ta; ty = S23 * o.wr.hi + ty;
;                     float pa = ta.x + ta.y, py = ty.x + ty.y;
;                     f32x2 kv01 = o.kv.lo * o.vi, kv23 = o.kv.hi * o.vi;
;     ...
;                     asm volatile("" : "+v"(kv01), "+v"(kv23), "+v"(vc));
;                     pa += dpp_f<0x121>(pa); py += dpp_f<0x121>(py); pa += dpp_f<0x122>(pa); py += dpp_f<0x122>(py);
;                     pa += dpp_f<0x124>(pa); pa += dpp_f<0x128>(pa);
;                     S01 = S01 * o.wv.lo + (o.be.lo * pa + kv01);
;                     S23 = S23 * o.wv.hi + (o.be.hi * pa + kv23);
;     ...
;                     __builtin_amdgcn_sched_barrier(0);
;                     o = n;
;                 }
.LBB0_1090:
	v_lshlrev_b32_e32 v38, 2, v27
	v_lshlrev_b32_e32 v39, 2, v1
	v_cndmask_b32_e64 v41, v124, v123, s[2:3]
	v_add_u32_e32 v68, 0xc400, v38
	v_add_u32_e32 v69, 0xc400, v39
	v_add_u32_e32 v71, 0x2000, v123
	v_cndmask_b32_e64 v71, v124, v71, s[2:3]
	ds_read_b128 v[10:13], v38 offset:512
	ds_read_b128 v[6:9], v38 offset:256
	ds_read_b32 v28, v39 offset:1280
	ds_read_b128 v[2:5], v38 offset:0
	ds_read_b128 v[14:17], v38 offset:768
	ds_read_b128 v[18:21], v38 offset:1024
	s_waitcnt lgkmcnt(0)
.Lscan_chunk_pair:
	v_pk_mul_f32 v[34:35], v[22:23], v[10:11]
	v_pk_fma_f32 v[34:35], v[24:25], v[12:13], v[34:35]
	ds_read_b128 v[50:53], v38 offset:2080
	ds_read_b128 v[46:49], v38 offset:1824
	ds_read_b32 v62, v39 offset:2848
	ds_read_b128 v[42:45], v38 offset:1568
	ds_read_b128 v[54:57], v38 offset:2336
	ds_read_b128 v[58:61], v38 offset:2592
	v_add_f32_e32 v34, v34, v35
	v_pk_mul_f32 v[6:7], v[6:7], v[28:29] op_sel_hi:[1,0]
	v_pk_mul_f32 v[8:9], v[8:9], v[28:29] op_sel_hi:[1,0]
	v_add_f32_dpp v34, v34, v34 row_ror:1 row_mask:0xf bank_mask:0xf bound_ctrl:1
	v_pk_fma_f32 v[6:7], v[22:23], v[2:3], v[6:7]
	v_pk_fma_f32 v[8:9], v[24:25], v[4:5], v[8:9]
	v_add_f32_dpp v34, v34, v34 row_ror:2 row_mask:0xf bank_mask:0xf bound_ctrl:1
	s_nop 0
	s_nop 0
	v_add_f32_dpp v34, v34, v34 row_ror:4 row_mask:0xf bank_mask:0xf bound_ctrl:1
	s_nop 0
	s_nop 0
	v_add_f32_dpp v34, v34, v34 row_ror:8 row_mask:0xf bank_mask:0xf bound_ctrl:1
	v_pk_fma_f32 v[22:23], v[14:15], v[34:35], v[6:7] op_sel_hi:[1,0,1]
	v_pk_fma_f32 v[24:25], v[16:17], v[34:35], v[8:9] op_sel_hi:[1,0,1]
	s_waitcnt lgkmcnt(3)
	v_pk_mul_f32 v[34:35], v[22:23], v[50:51]
	v_pk_mul_f32 v[36:37], v[22:23], v[18:19]
	v_pk_fma_f32 v[34:35], v[24:25], v[52:53], v[34:35]
	v_pk_fma_f32 v[36:37], v[24:25], v[20:21], v[36:37]
	ds_read_b128 v[10:13], v38 offset:3648
	ds_read_b128 v[6:9], v38 offset:3392
	ds_read_b32 v28, v39 offset:4416
	ds_read_b128 v[2:5], v38 offset:3136
	ds_read_b128 v[14:17], v38 offset:3904
	ds_read_b128 v[18:21], v38 offset:4160
	v_add_f32_e32 v34, v34, v35
	v_add_f32_e32 v36, v36, v37
	v_pk_mul_f32 v[46:47], v[46:47], v[62:63] op_sel_hi:[1,0]
	v_add_f32_dpp v34, v34, v34 row_ror:1 row_mask:0xf bank_mask:0xf bound_ctrl:1
	v_add_f32_dpp v36, v36, v36 row_ror:1 row_mask:0xf bank_mask:0xf bound_ctrl:1
	s_waitcnt lgkmcnt(7)
	v_pk_fma_f32 v[46:47], v[22:23], v[42:43], v[46:47]
	v_add_f32_dpp v34, v34, v34 row_ror:2 row_mask:0xf bank_mask:0xf bound_ctrl:1
	v_add_f32_dpp v36, v36, v36 row_ror:2 row_mask:0xf bank_mask:0xf bound_ctrl:1
	v_pk_mul_f32 v[48:49], v[48:49], v[62:63] op_sel_hi:[1,0]
	v_add_f32_dpp v34, v34, v34 row_ror:4 row_mask:0xf bank_mask:0xf bound_ctrl:1
	v_pk_fma_f32 v[48:49], v[24:25], v[44:45], v[48:49]
	s_nop 0
	v_add_f32_dpp v34, v34, v34 row_ror:8 row_mask:0xf bank_mask:0xf bound_ctrl:1
	v_pk_fma_f32 v[22:23], v[54:55], v[34:35], v[46:47] op_sel_hi:[1,0,1]
	v_pk_fma_f32 v[24:25], v[56:57], v[34:35], v[48:49] op_sel_hi:[1,0,1]
	s_waitcnt lgkmcnt(3)
	v_pk_mul_f32 v[34:35], v[22:23], v[10:11]
	v_pk_mul_f32 v[66:67], v[22:23], v[58:59]
	v_pk_fma_f32 v[34:35], v[24:25], v[12:13], v[34:35]
	v_pk_fma_f32 v[66:67], v[24:25], v[60:61], v[66:67]
	ds_read_b128 v[50:53], v38 offset:5216
	ds_read_b128 v[46:49], v38 offset:4960
	ds_read_b32 v62, v39 offset:5984
	ds_read_b128 v[42:45], v38 offset:4704
	ds_read_b128 v[54:57], v38 offset:5472
	ds_read_b128 v[58:61], v38 offset:5728
	v_add_f32_e32 v34, v34, v35
	v_add_f32_e32 v66, v66, v67
	v_pk_mul_f32 v[6:7], v[6:7], v[28:29] op_sel_hi:[1,0]
	v_add_f32_dpp v34, v34, v34 row_ror:1 row_mask:0xf bank_mask:0xf bound_ctrl:1
	v_add_f32_dpp v66, v66, v66 row_ror:1 row_mask:0xf bank_mask:0xf bound_ctrl:1
	s_waitcnt lgkmcnt(7)
	v_pk_fma_f32 v[6:7], v[22:23], v[2:3], v[6:7]
	v_add_f32_dpp v34, v34, v34 row_ror:2 row_mask:0xf bank_mask:0xf bound_ctrl:1
	v_add_f32_dpp v66, v66, v66 row_ror:2 row_mask:0xf bank_mask:0xf bound_ctrl:1
	v_pk_mul_f32 v[8:9], v[8:9], v[28:29] op_sel_hi:[1,0]
	v_add_f32_dpp v34, v34, v34 row_ror:4 row_mask:0xf bank_mask:0xf bound_ctrl:1
	v_pk_fma_f32 v[8:9], v[24:25], v[4:5], v[8:9]
	ds_write2st64_b32 v41, v36, v66 offset0:0 offset1:1
	v_add_f32_dpp v34, v34, v34 row_ror:8 row_mask:0xf bank_mask:0xf bound_ctrl:1
	v_pk_fma_f32 v[22:23], v[14:15], v[34:35], v[6:7] op_sel_hi:[1,0,1]
	v_pk_fma_f32 v[24:25], v[16:17], v[34:35], v[8:9] op_sel_hi:[1,0,1]
	s_waitcnt lgkmcnt(4)
	v_pk_mul_f32 v[34:35], v[22:23], v[50:51]
	v_pk_mul_f32 v[36:37], v[22:23], v[18:19]
	v_pk_fma_f32 v[34:35], v[24:25], v[52:53], v[34:35]
	v_pk_fma_f32 v[36:37], v[24:25], v[20:21], v[36:37]
	ds_read_b128 v[10:13], v38 offset:6784
	ds_read_b128 v[6:9], v38 offset:6528
	ds_read_b32 v28, v39 offset:7552
	ds_read_b128 v[2:5], v38 offset:6272
	ds_read_b128 v[14:17], v38 offset:7040
	ds_read_b128 v[18:21], v38 offset:7296
	v_add_f32_e32 v34, v34, v35
	v_add_f32_e32 v36, v36, v37
	v_pk_mul_f32 v[46:47], v[46:47], v[62:63] op_sel_hi:[1,0]
	v_add_f32_dpp v34, v34, v34 row_ror:1 row_mask:0xf bank_mask:0xf bound_ctrl:1
	v_add_f32_dpp v36, v36, v36 row_ror:1 row_mask:0xf bank_mask:0xf bound_ctrl:1
	s_waitcnt lgkmcnt(8)
	v_pk_fma_f32 v[46:47], v[22:23], v[42:43], v[46:47]
	v_add_f32_dpp v34, v34, v34 row_ror:2 row_mask:0xf bank_mask:0xf bound_ctrl:1
	v_add_f32_dpp v36, v36, v36 row_ror:2 row_mask:0xf bank_mask:0xf bound_ctrl:1
	v_pk_mul_f32 v[48:49], v[48:49], v[62:63] op_sel_hi:[1,0]
	v_add_f32_dpp v34, v34, v34 row_ror:4 row_mask:0xf bank_mask:0xf bound_ctrl:1
	v_pk_fma_f32 v[48:49], v[24:25], v[44:45], v[48:49]
	s_nop 0
	v_add_f32_dpp v34, v34, v34 row_ror:8 row_mask:0xf bank_mask:0xf bound_ctrl:1
	v_pk_fma_f32 v[22:23], v[54:55], v[34:35], v[46:47] op_sel_hi:[1,0,1]
	v_pk_fma_f32 v[24:25], v[56:57], v[34:35], v[48:49] op_sel_hi:[1,0,1]
	s_waitcnt lgkmcnt(3)
; template <int CTRL> __device__ __forceinline__ float dpp_f(float x) { return __int_as_float(__builtin_amdgcn_update_dpp(0, __float_as_int(x), CTRL, 0xf, 0xf, false)); }
; __device__ __forceinline__ void p8_scan(const Args& a, LAS unsigned char* lds) {
;     ...
;                 for (int tt = 0; tt < TC; ++tt) {
;                     ScanOps n; scan_ld(n, bt + (tt + 1 < TC ? tt + 1 : tt) * SPITCH, jq4, myrow);
;                     __builtin_amdgcn_sched_barrier(0);
;                     f32x2 ta = S01 * o.al.lo, ty = S01 * o.wr.lo; ta = S23 * o.al.hi + ta; ty = S23 * o.wr.hi + ty;
;                     float pa = ta.x + ta.y, py = ty.x + ty.y;
;                     f32x2 kv01 = o.kv.lo * o.vi, kv23 = o.kv.hi * o.vi;
;     ...
;                     asm volatile("" : "+v"(kv01), "+v"(kv23), "+v"(vc));
;                     pa += dpp_f<0x121>(pa); py += dpp_f<0x121>(py); pa += dpp_f<0x122>(pa); py += dpp_f<0x122>(py);
;                     pa += dpp_f<0x124>(pa); pa += dpp_f<0x128>(pa);
;                     S01 = S01 * o.wv.lo + (o.be.lo * pa + kv01);
;                     S23 = S23 * o.wv.hi + (o.be.hi * pa + kv23);
;     ...
;                     __builtin_amdgcn_sched_barrier(0);
;                     o = n;
;                 }
	v_pk_mul_f32 v[34:35], v[22:23], v[10:11]
	v_pk_mul_f32 v[66:67], v[22:23], v[58:59]
	v_pk_fma_f32 v[34:35], v[24:25], v[12:13], v[34:35]
	v_pk_fma_f32 v[66:67], v[24:25], v[60:61], v[66:67]
	ds_read_b128 v[50:53], v38 offset:8352
	ds_read_b128 v[46:49], v38 offset:8096
	ds_read_b32 v62, v39 offset:9120
	ds_read_b128 v[42:45], v38 offset:7840
	ds_read_b128 v[54:57], v38 offset:8608
	ds_read_b128 v[58:61], v38 offset:8864
	v_add_f32_e32 v34, v34, v35
	v_add_f32_e32 v66, v66, v67
	v_pk_mul_f32 v[6:7], v[6:7], v[28:29] op_sel_hi:[1,0]
	v_add_f32_dpp v34, v34, v34 row_ror:1 row_mask:0xf bank_mask:0xf bound_ctrl:1
	v_add_f32_dpp v66, v66, v66 row_ror:1 row_mask:0xf bank_mask:0xf bound_ctrl:1
	s_waitcnt lgkmcnt(7)
	v_pk_fma_f32 v[6:7], v[22:23], v[2:3], v[6:7]
	v_add_f32_dpp v34, v34, v34 row_ror:2 row_mask:0xf bank_mask:0xf bound_ctrl:1
	v_add_f32_dpp v66, v66, v66 row_ror:2 row_mask:0xf bank_mask:0xf bound_ctrl:1
	v_pk_mul_f32 v[8:9], v[8:9], v[28:29] op_sel_hi:[1,0]
	v_add_f32_dpp v34, v34, v34 row_ror:4 row_mask:0xf bank_mask:0xf bound_ctrl:1
	v_pk_fma_f32 v[8:9], v[24:25], v[4:5], v[8:9]
	ds_write2st64_b32 v41, v36, v66 offset0:2 offset1:3
	v_add_f32_dpp v34, v34, v34 row_ror:8 row_mask:0xf bank_mask:0xf bound_ctrl:1
	v_pk_fma_f32 v[22:23], v[14:15], v[34:35], v[6:7] op_sel_hi:[1,0,1]
	v_pk_fma_f32 v[24:25], v[16:17], v[34:35], v[8:9] op_sel_hi:[1,0,1]
	s_waitcnt lgkmcnt(4)
	v_pk_mul_f32 v[34:35], v[22:23], v[50:51]
	v_pk_mul_f32 v[36:37], v[22:23], v[18:19]
	v_pk_fma_f32 v[34:35], v[24:25], v[52:53], v[34:35]
	v_pk_fma_f32 v[36:37], v[24:25], v[20:21], v[36:37]
	ds_read_b128 v[10:13], v38 offset:9920
	ds_read_b128 v[6:9], v38 offset:9664
	ds_read_b32 v28, v39 offset:10688
	ds_read_b128 v[2:5], v38 offset:9408
	ds_read_b128 v[14:17], v38 offset:10176
	ds_read_b128 v[18:21], v38 offset:10432
	v_add_f32_e32 v34, v34, v35
	v_add_f32_e32 v36, v36, v37
	v_pk_mul_f32 v[46:47], v[46:47], v[62:63] op_sel_hi:[1,0]
	v_add_f32_dpp v34, v34, v34 row_ror:1 row_mask:0xf bank_mask:0xf bound_ctrl:1
	v_add_f32_dpp v36, v36, v36 row_ror:1 row_mask:0xf bank_mask:0xf bound_ctrl:1
	s_waitcnt lgkmcnt(8)
	v_pk_fma_f32 v[46:47], v[22:23], v[42:43], v[46:47]
	v_add_f32_dpp v34, v34, v34 row_ror:2 row_mask:0xf bank_mask:0xf bound_ctrl:1
	v_add_f32_dpp v36, v36, v36 row_ror:2 row_mask:0xf bank_mask:0xf bound_ctrl:1
	v_pk_mul_f32 v[48:49], v[48:49], v[62:63] op_sel_hi:[1,0]
	v_add_f32_dpp v34, v34, v34 row_ror:4 row_mask:0xf bank_mask:0xf bound_ctrl:1
	v_pk_fma_f32 v[48:49], v[24:25], v[44:45], v[48:49]
	s_nop 0
	v_add_f32_dpp v34, v34, v34 row_ror:8 row_mask:0xf bank_mask:0xf bound_ctrl:1
	v_pk_fma_f32 v[22:23], v[54:55], v[34:35], v[46:47] op_sel_hi:[1,0,1]
	v_pk_fma_f32 v[24:25], v[56:57], v[34:35], v[48:49] op_sel_hi:[1,0,1]
	s_waitcnt lgkmcnt(3)
	v_pk_mul_f32 v[34:35], v[22:23], v[10:11]
	v_pk_mul_f32 v[66:67], v[22:23], v[58:59]
	v_pk_fma_f32 v[34:35], v[24:25], v[12:13], v[34:35]
	v_pk_fma_f32 v[66:67], v[24:25], v[60:61], v[66:67]
	ds_read_b128 v[50:53], v38 offset:11488
	ds_read_b128 v[46:49], v38 offset:11232
	ds_read_b32 v62, v39 offset:12256
	ds_read_b128 v[42:45], v38 offset:10976
	ds_read_b128 v[54:57], v38 offset:11744
	ds_read_b128 v[58:61], v38 offset:12000
	v_add_f32_e32 v34, v34, v35
	v_add_f32_e32 v66, v66, v67
	v_pk_mul_f32 v[6:7], v[6:7], v[28:29] op_sel_hi:[1,0]
	v_add_f32_dpp v34, v34, v34 row_ror:1 row_mask:0xf bank_mask:0xf bound_ctrl:1
	v_add_f32_dpp v66, v66, v66 row_ror:1 row_mask:0xf bank_mask:0xf bound_ctrl:1
	s_waitcnt lgkmcnt(7)
	v_pk_fma_f32 v[6:7], v[22:23], v[2:3], v[6:7]
	v_add_f32_dpp v34, v34, v34 row_ror:2 row_mask:0xf bank_mask:0xf bound_ctrl:1
	v_add_f32_dpp v66, v66, v66 row_ror:2 row_mask:0xf bank_mask:0xf bound_ctrl:1
	v_pk_mul_f32 v[8:9], v[8:9], v[28:29] op_sel_hi:[1,0]
	v_add_f32_dpp v34, v34, v34 row_ror:4 row_mask:0xf bank_mask:0xf bound_ctrl:1
	v_pk_fma_f32 v[8:9], v[24:25], v[4:5], v[8:9]
	ds_write2st64_b32 v41, v36, v66 offset0:4 offset1:5
	v_add_f32_dpp v34, v34, v34 row_ror:8 row_mask:0xf bank_mask:0xf bound_ctrl:1
	v_pk_fma_f32 v[22:23], v[14:15], v[34:35], v[6:7] op_sel_hi:[1,0,1]
	v_pk_fma_f32 v[24:25], v[16:17], v[34:35], v[8:9] op_sel_hi:[1,0,1]
	s_waitcnt lgkmcnt(4)
	v_pk_mul_f32 v[34:35], v[22:23], v[50:51]
	v_pk_mul_f32 v[36:37], v[22:23], v[18:19]
	v_pk_fma_f32 v[34:35], v[24:25], v[52:53], v[34:35]
	v_pk_fma_f32 v[36:37], v[24:25], v[20:21], v[36:37]
	ds_read_b128 v[10:13], v38 offset:13056
	ds_read_b128 v[6:9], v38 offset:12800
	ds_read_b32 v28, v39 offset:13824
	ds_read_b128 v[2:5], v38 offset:12544
	ds_read_b128 v[14:17], v38 offset:13312
	ds_read_b128 v[18:21], v38 offset:13568
	v_add_f32_e32 v34, v34, v35
	v_add_f32_e32 v36, v36, v37
	v_pk_mul_f32 v[46:47], v[46:47], v[62:63] op_sel_hi:[1,0]
	v_add_f32_dpp v34, v34, v34 row_ror:1 row_mask:0xf bank_mask:0xf bound_ctrl:1
	v_add_f32_dpp v36, v36, v36 row_ror:1 row_mask:0xf bank_mask:0xf bound_ctrl:1
	s_waitcnt lgkmcnt(8)
	v_pk_fma_f32 v[46:47], v[22:23], v[42:43], v[46:47]
	v_add_f32_dpp v34, v34, v34 row_ror:2 row_mask:0xf bank_mask:0xf bound_ctrl:1
	v_add_f32_dpp v36, v36, v36 row_ror:2 row_mask:0xf bank_mask:0xf bound_ctrl:1
	v_pk_mul_f32 v[48:49], v[48:49], v[62:63] op_sel_hi:[1,0]
	v_add_f32_dpp v34, v34, v34 row_ror:4 row_mask:0xf bank_mask:0xf bound_ctrl:1
	v_pk_fma_f32 v[48:49], v[24:25], v[44:45], v[48:49]
	s_nop 0
	v_add_f32_dpp v34, v34, v34 row_ror:8 row_mask:0xf bank_mask:0xf bound_ctrl:1
	v_pk_fma_f32 v[22:23], v[54:55], v[34:35], v[46:47] op_sel_hi:[1,0,1]
	v_pk_fma_f32 v[24:25], v[56:57], v[34:35], v[48:49] op_sel_hi:[1,0,1]
	s_waitcnt lgkmcnt(3)
; template <int CTRL> __device__ __forceinline__ float dpp_f(float x) { return __int_as_float(__builtin_amdgcn_update_dpp(0, __float_as_int(x), CTRL, 0xf, 0xf, false)); }
; __device__ __forceinline__ void p8_scan(const Args& a, LAS unsigned char* lds) {
;     ...
;                 for (int tt = 0; tt < TC; ++tt) {
;                     ScanOps n; scan_ld(n, bt + (tt + 1 < TC ? tt + 1 : tt) * SPITCH, jq4, myrow);
;                     __builtin_amdgcn_sched_barrier(0);
;                     f32x2 ta = S01 * o.al.lo, ty = S01 * o.wr.lo; ta = S23 * o.al.hi + ta; ty = S23 * o.wr.hi + ty;
;                     float pa = ta.x + ta.y, py = ty.x + ty.y;
;                     f32x2 kv01 = o.kv.lo * o.vi, kv23 = o.kv.hi * o.vi;
;     ...
;                     asm volatile("" : "+v"(kv01), "+v"(kv23), "+v"(vc));
;                     pa += dpp_f<0x121>(pa); py += dpp_f<0x121>(py); pa += dpp_f<0x122>(pa); py += dpp_f<0x122>(py);
;                     pa += dpp_f<0x124>(pa); pa += dpp_f<0x128>(pa);
;                     S01 = S01 * o.wv.lo + (o.be.lo * pa + kv01);
;                     S23 = S23 * o.wv.hi + (o.be.hi * pa + kv23);
;     ...
;                     __builtin_amdgcn_sched_barrier(0);
;                     o = n;
	v_pk_mul_f32 v[34:35], v[22:23], v[10:11]
	v_pk_mul_f32 v[66:67], v[22:23], v[58:59]
	v_pk_fma_f32 v[34:35], v[24:25], v[12:13], v[34:35]
	v_pk_fma_f32 v[66:67], v[24:25], v[60:61], v[66:67]
	ds_read_b128 v[50:53], v38 offset:14624
	ds_read_b128 v[46:49], v38 offset:14368
	ds_read_b32 v62, v39 offset:15392
	ds_read_b128 v[42:45], v38 offset:14112
	ds_read_b128 v[54:57], v38 offset:14880
	ds_read_b128 v[58:61], v38 offset:15136
	v_add_f32_e32 v34, v34, v35
	v_add_f32_e32 v66, v66, v67
	v_pk_mul_f32 v[6:7], v[6:7], v[28:29] op_sel_hi:[1,0]
	v_add_f32_dpp v34, v34, v34 row_ror:1 row_mask:0xf bank_mask:0xf bound_ctrl:1
	v_add_f32_dpp v66, v66, v66 row_ror:1 row_mask:0xf bank_mask:0xf bound_ctrl:1
	s_waitcnt lgkmcnt(7)
	v_pk_fma_f32 v[6:7], v[22:23], v[2:3], v[6:7]
	v_add_f32_dpp v34, v34, v34 row_ror:2 row_mask:0xf bank_mask:0xf bound_ctrl:1
	v_add_f32_dpp v66, v66, v66 row_ror:2 row_mask:0xf bank_mask:0xf bound_ctrl:1
	v_pk_mul_f32 v[8:9], v[8:9], v[28:29] op_sel_hi:[1,0]
	v_add_f32_dpp v34, v34, v34 row_ror:4 row_mask:0xf bank_mask:0xf bound_ctrl:1
	v_pk_fma_f32 v[8:9], v[24:25], v[4:5], v[8:9]
	ds_write2st64_b32 v41, v36, v66 offset0:6 offset1:7
	v_add_f32_dpp v34, v34, v34 row_ror:8 row_mask:0xf bank_mask:0xf bound_ctrl:1
	v_pk_fma_f32 v[22:23], v[14:15], v[34:35], v[6:7] op_sel_hi:[1,0,1]
	v_pk_fma_f32 v[24:25], v[16:17], v[34:35], v[8:9] op_sel_hi:[1,0,1]
	s_waitcnt lgkmcnt(4)
	v_pk_mul_f32 v[34:35], v[22:23], v[50:51]
	v_pk_mul_f32 v[36:37], v[22:23], v[18:19]
	v_pk_fma_f32 v[34:35], v[24:25], v[52:53], v[34:35]
	v_pk_fma_f32 v[36:37], v[24:25], v[20:21], v[36:37]
	ds_read_b128 v[10:13], v38 offset:16192
	ds_read_b128 v[6:9], v38 offset:15936
	ds_read_b32 v28, v39 offset:16960
	ds_read_b128 v[2:5], v38 offset:15680
	ds_read_b128 v[14:17], v38 offset:16448
	ds_read_b128 v[18:21], v38 offset:16704
	v_add_f32_e32 v34, v34, v35
	v_add_f32_e32 v36, v36, v37
	v_pk_mul_f32 v[46:47], v[46:47], v[62:63] op_sel_hi:[1,0]
	v_add_f32_dpp v34, v34, v34 row_ror:1 row_mask:0xf bank_mask:0xf bound_ctrl:1
	v_add_f32_dpp v36, v36, v36 row_ror:1 row_mask:0xf bank_mask:0xf bound_ctrl:1
	s_waitcnt lgkmcnt(8)
	v_pk_fma_f32 v[46:47], v[22:23], v[42:43], v[46:47]
	v_add_f32_dpp v34, v34, v34 row_ror:2 row_mask:0xf bank_mask:0xf bound_ctrl:1
	v_add_f32_dpp v36, v36, v36 row_ror:2 row_mask:0xf bank_mask:0xf bound_ctrl:1
	v_pk_mul_f32 v[48:49], v[48:49], v[62:63] op_sel_hi:[1,0]
	v_add_f32_dpp v34, v34, v34 row_ror:4 row_mask:0xf bank_mask:0xf bound_ctrl:1
	v_pk_fma_f32 v[48:49], v[24:25], v[44:45], v[48:49]
	s_nop 0
	v_add_f32_dpp v34, v34, v34 row_ror:8 row_mask:0xf bank_mask:0xf bound_ctrl:1
	v_pk_fma_f32 v[22:23], v[54:55], v[34:35], v[46:47] op_sel_hi:[1,0,1]
	v_pk_fma_f32 v[24:25], v[56:57], v[34:35], v[48:49] op_sel_hi:[1,0,1]
	s_waitcnt lgkmcnt(3)
	v_pk_mul_f32 v[34:35], v[22:23], v[10:11]
	v_pk_mul_f32 v[66:67], v[22:23], v[58:59]
	v_pk_fma_f32 v[34:35], v[24:25], v[12:13], v[34:35]
	v_pk_fma_f32 v[66:67], v[24:25], v[60:61], v[66:67]
	ds_read_b128 v[50:53], v38 offset:17760
	ds_read_b128 v[46:49], v38 offset:17504
	ds_read_b32 v62, v39 offset:18528
	ds_read_b128 v[42:45], v38 offset:17248
	ds_read_b128 v[54:57], v38 offset:18016
	ds_read_b128 v[58:61], v38 offset:18272
	v_add_f32_e32 v34, v34, v35
	v_add_f32_e32 v66, v66, v67
	v_pk_mul_f32 v[6:7], v[6:7], v[28:29] op_sel_hi:[1,0]
	v_add_f32_dpp v34, v34, v34 row_ror:1 row_mask:0xf bank_mask:0xf bound_ctrl:1
	v_add_f32_dpp v66, v66, v66 row_ror:1 row_mask:0xf bank_mask:0xf bound_ctrl:1
	s_waitcnt lgkmcnt(7)
	v_pk_fma_f32 v[6:7], v[22:23], v[2:3], v[6:7]
	v_add_f32_dpp v34, v34, v34 row_ror:2 row_mask:0xf bank_mask:0xf bound_ctrl:1
	v_add_f32_dpp v66, v66, v66 row_ror:2 row_mask:0xf bank_mask:0xf bound_ctrl:1
	v_pk_mul_f32 v[8:9], v[8:9], v[28:29] op_sel_hi:[1,0]
	v_add_f32_dpp v34, v34, v34 row_ror:4 row_mask:0xf bank_mask:0xf bound_ctrl:1
	v_pk_fma_f32 v[8:9], v[24:25], v[4:5], v[8:9]
	ds_write2st64_b32 v41, v36, v66 offset0:8 offset1:9
	v_add_f32_dpp v34, v34, v34 row_ror:8 row_mask:0xf bank_mask:0xf bound_ctrl:1
	v_pk_fma_f32 v[22:23], v[14:15], v[34:35], v[6:7] op_sel_hi:[1,0,1]
	v_pk_fma_f32 v[24:25], v[16:17], v[34:35], v[8:9] op_sel_hi:[1,0,1]
	s_waitcnt lgkmcnt(4)
	v_pk_mul_f32 v[34:35], v[22:23], v[50:51]
	v_pk_mul_f32 v[36:37], v[22:23], v[18:19]
	v_pk_fma_f32 v[34:35], v[24:25], v[52:53], v[34:35]
	v_pk_fma_f32 v[36:37], v[24:25], v[20:21], v[36:37]
	ds_read_b128 v[10:13], v38 offset:19328
	ds_read_b128 v[6:9], v38 offset:19072
	ds_read_b32 v28, v39 offset:20096
	ds_read_b128 v[2:5], v38 offset:18816
	ds_read_b128 v[14:17], v38 offset:19584
	ds_read_b128 v[18:21], v38 offset:19840
	v_add_f32_e32 v34, v34, v35
	v_add_f32_e32 v36, v36, v37
	v_pk_mul_f32 v[46:47], v[46:47], v[62:63] op_sel_hi:[1,0]
	v_add_f32_dpp v34, v34, v34 row_ror:1 row_mask:0xf bank_mask:0xf bound_ctrl:1
	v_add_f32_dpp v36, v36, v36 row_ror:1 row_mask:0xf bank_mask:0xf bound_ctrl:1
	s_waitcnt lgkmcnt(8)
	v_pk_fma_f32 v[46:47], v[22:23], v[42:43], v[46:47]
	v_add_f32_dpp v34, v34, v34 row_ror:2 row_mask:0xf bank_mask:0xf bound_ctrl:1
	v_add_f32_dpp v36, v36, v36 row_ror:2 row_mask:0xf bank_mask:0xf bound_ctrl:1
	v_pk_mul_f32 v[48:49], v[48:49], v[62:63] op_sel_hi:[1,0]
	v_add_f32_dpp v34, v34, v34 row_ror:4 row_mask:0xf bank_mask:0xf bound_ctrl:1
	v_pk_fma_f32 v[48:49], v[24:25], v[44:45], v[48:49]
	s_nop 0
	v_add_f32_dpp v34, v34, v34 row_ror:8 row_mask:0xf bank_mask:0xf bound_ctrl:1
	v_pk_fma_f32 v[22:23], v[54:55], v[34:35], v[46:47] op_sel_hi:[1,0,1]
	v_pk_fma_f32 v[24:25], v[56:57], v[34:35], v[48:49] op_sel_hi:[1,0,1]
	s_waitcnt lgkmcnt(3)
; template <int CTRL> __device__ __forceinline__ float dpp_f(float x) { return __int_as_float(__builtin_amdgcn_update_dpp(0, __float_as_int(x), CTRL, 0xf, 0xf, false)); }
; __device__ __forceinline__ void p8_scan(const Args& a, LAS unsigned char* lds) {
;     ...
;                 for (int tt = 0; tt < TC; ++tt) {
;                     ScanOps n; scan_ld(n, bt + (tt + 1 < TC ? tt + 1 : tt) * SPITCH, jq4, myrow);
;                     __builtin_amdgcn_sched_barrier(0);
;                     f32x2 ta = S01 * o.al.lo, ty = S01 * o.wr.lo; ta = S23 * o.al.hi + ta; ty = S23 * o.wr.hi + ty;
;                     float pa = ta.x + ta.y, py = ty.x + ty.y;
;                     f32x2 kv01 = o.kv.lo * o.vi, kv23 = o.kv.hi * o.vi;
;     ...
;                     asm volatile("" : "+v"(kv01), "+v"(kv23), "+v"(vc));
;                     pa += dpp_f<0x121>(pa); py += dpp_f<0x121>(py); pa += dpp_f<0x122>(pa); py += dpp_f<0x122>(py);
;                     pa += dpp_f<0x124>(pa); pa += dpp_f<0x128>(pa);
;                     S01 = S01 * o.wv.lo + (o.be.lo * pa + kv01);
;                     S23 = S23 * o.wv.hi + (o.be.hi * pa + kv23);
;     ...
;                     __builtin_amdgcn_sched_barrier(0);
;                     o = n;
	v_pk_mul_f32 v[34:35], v[22:23], v[10:11]
	v_pk_mul_f32 v[66:67], v[22:23], v[58:59]
	v_pk_fma_f32 v[34:35], v[24:25], v[12:13], v[34:35]
	v_pk_fma_f32 v[66:67], v[24:25], v[60:61], v[66:67]
	ds_read_b128 v[50:53], v38 offset:20896
	ds_read_b128 v[46:49], v38 offset:20640
	ds_read_b32 v62, v39 offset:21664
	ds_read_b128 v[42:45], v38 offset:20384
	ds_read_b128 v[54:57], v38 offset:21152
	ds_read_b128 v[58:61], v38 offset:21408
	v_add_f32_e32 v34, v34, v35
	v_add_f32_e32 v66, v66, v67
	v_pk_mul_f32 v[6:7], v[6:7], v[28:29] op_sel_hi:[1,0]
	v_add_f32_dpp v34, v34, v34 row_ror:1 row_mask:0xf bank_mask:0xf bound_ctrl:1
	v_add_f32_dpp v66, v66, v66 row_ror:1 row_mask:0xf bank_mask:0xf bound_ctrl:1
	s_waitcnt lgkmcnt(7)
	v_pk_fma_f32 v[6:7], v[22:23], v[2:3], v[6:7]
	v_add_f32_dpp v34, v34, v34 row_ror:2 row_mask:0xf bank_mask:0xf bound_ctrl:1
	v_add_f32_dpp v66, v66, v66 row_ror:2 row_mask:0xf bank_mask:0xf bound_ctrl:1
	v_pk_mul_f32 v[8:9], v[8:9], v[28:29] op_sel_hi:[1,0]
	v_add_f32_dpp v34, v34, v34 row_ror:4 row_mask:0xf bank_mask:0xf bound_ctrl:1
	v_pk_fma_f32 v[8:9], v[24:25], v[4:5], v[8:9]
	ds_write2st64_b32 v41, v36, v66 offset0:10 offset1:11
	v_add_f32_dpp v34, v34, v34 row_ror:8 row_mask:0xf bank_mask:0xf bound_ctrl:1
	v_pk_fma_f32 v[22:23], v[14:15], v[34:35], v[6:7] op_sel_hi:[1,0,1]
	v_pk_fma_f32 v[24:25], v[16:17], v[34:35], v[8:9] op_sel_hi:[1,0,1]
	s_waitcnt lgkmcnt(4)
	v_pk_mul_f32 v[34:35], v[22:23], v[50:51]
	v_pk_mul_f32 v[36:37], v[22:23], v[18:19]
	v_pk_fma_f32 v[34:35], v[24:25], v[52:53], v[34:35]
	v_pk_fma_f32 v[36:37], v[24:25], v[20:21], v[36:37]
	ds_read_b128 v[10:13], v38 offset:22464
	ds_read_b128 v[6:9], v38 offset:22208
	ds_read_b32 v28, v39 offset:23232
	ds_read_b128 v[2:5], v38 offset:21952
	ds_read_b128 v[14:17], v38 offset:22720
	ds_read_b128 v[18:21], v38 offset:22976
	v_add_f32_e32 v34, v34, v35
	v_add_f32_e32 v36, v36, v37
	v_pk_mul_f32 v[46:47], v[46:47], v[62:63] op_sel_hi:[1,0]
	v_add_f32_dpp v34, v34, v34 row_ror:1 row_mask:0xf bank_mask:0xf bound_ctrl:1
	v_add_f32_dpp v36, v36, v36 row_ror:1 row_mask:0xf bank_mask:0xf bound_ctrl:1
	s_waitcnt lgkmcnt(8)
	v_pk_fma_f32 v[46:47], v[22:23], v[42:43], v[46:47]
	v_add_f32_dpp v34, v34, v34 row_ror:2 row_mask:0xf bank_mask:0xf bound_ctrl:1
	v_add_f32_dpp v36, v36, v36 row_ror:2 row_mask:0xf bank_mask:0xf bound_ctrl:1
	v_pk_mul_f32 v[48:49], v[48:49], v[62:63] op_sel_hi:[1,0]
	v_add_f32_dpp v34, v34, v34 row_ror:4 row_mask:0xf bank_mask:0xf bound_ctrl:1
	v_pk_fma_f32 v[48:49], v[24:25], v[44:45], v[48:49]
	s_nop 0
	v_add_f32_dpp v34, v34, v34 row_ror:8 row_mask:0xf bank_mask:0xf bound_ctrl:1
	v_pk_fma_f32 v[22:23], v[54:55], v[34:35], v[46:47] op_sel_hi:[1,0,1]
	v_pk_fma_f32 v[24:25], v[56:57], v[34:35], v[48:49] op_sel_hi:[1,0,1]
	s_waitcnt lgkmcnt(3)
	v_pk_mul_f32 v[34:35], v[22:23], v[10:11]
	v_pk_mul_f32 v[66:67], v[22:23], v[58:59]
	v_pk_fma_f32 v[34:35], v[24:25], v[12:13], v[34:35]
	v_pk_fma_f32 v[66:67], v[24:25], v[60:61], v[66:67]
	ds_read_b128 v[50:53], v38 offset:24032
	ds_read_b128 v[46:49], v38 offset:23776
	ds_read_b32 v62, v39 offset:24800
	ds_read_b128 v[42:45], v38 offset:23520
	ds_read_b128 v[54:57], v38 offset:24288
	ds_read_b128 v[58:61], v38 offset:24544
	v_add_f32_e32 v34, v34, v35
	v_add_f32_e32 v66, v66, v67
	v_pk_mul_f32 v[6:7], v[6:7], v[28:29] op_sel_hi:[1,0]
	v_add_f32_dpp v34, v34, v34 row_ror:1 row_mask:0xf bank_mask:0xf bound_ctrl:1
	v_add_f32_dpp v66, v66, v66 row_ror:1 row_mask:0xf bank_mask:0xf bound_ctrl:1
	s_waitcnt lgkmcnt(7)
	v_pk_fma_f32 v[6:7], v[22:23], v[2:3], v[6:7]
	v_add_f32_dpp v34, v34, v34 row_ror:2 row_mask:0xf bank_mask:0xf bound_ctrl:1
	v_add_f32_dpp v66, v66, v66 row_ror:2 row_mask:0xf bank_mask:0xf bound_ctrl:1
	v_pk_mul_f32 v[8:9], v[8:9], v[28:29] op_sel_hi:[1,0]
	v_add_f32_dpp v34, v34, v34 row_ror:4 row_mask:0xf bank_mask:0xf bound_ctrl:1
	v_pk_fma_f32 v[8:9], v[24:25], v[4:5], v[8:9]
	ds_write2st64_b32 v41, v36, v66 offset0:12 offset1:13
	v_add_f32_dpp v34, v34, v34 row_ror:8 row_mask:0xf bank_mask:0xf bound_ctrl:1
	v_pk_fma_f32 v[22:23], v[14:15], v[34:35], v[6:7] op_sel_hi:[1,0,1]
	v_pk_fma_f32 v[24:25], v[16:17], v[34:35], v[8:9] op_sel_hi:[1,0,1]
	s_waitcnt lgkmcnt(4)
	v_pk_mul_f32 v[34:35], v[22:23], v[50:51]
	v_pk_mul_f32 v[36:37], v[22:23], v[18:19]
	v_pk_fma_f32 v[34:35], v[24:25], v[52:53], v[34:35]
	v_pk_fma_f32 v[36:37], v[24:25], v[20:21], v[36:37]
	ds_read_b128 v[10:13], v38 offset:25600
	ds_read_b128 v[6:9], v38 offset:25344
	ds_read_b32 v28, v39 offset:26368
	ds_read_b128 v[2:5], v38 offset:25088
	ds_read_b128 v[14:17], v38 offset:25856
	ds_read_b128 v[18:21], v38 offset:26112
	v_add_f32_e32 v34, v34, v35
	v_add_f32_e32 v36, v36, v37
	v_pk_mul_f32 v[46:47], v[46:47], v[62:63] op_sel_hi:[1,0]
	v_add_f32_dpp v34, v34, v34 row_ror:1 row_mask:0xf bank_mask:0xf bound_ctrl:1
	v_add_f32_dpp v36, v36, v36 row_ror:1 row_mask:0xf bank_mask:0xf bound_ctrl:1
	s_waitcnt lgkmcnt(8)
	v_pk_fma_f32 v[46:47], v[22:23], v[42:43], v[46:47]
	v_add_f32_dpp v34, v34, v34 row_ror:2 row_mask:0xf bank_mask:0xf bound_ctrl:1
	v_add_f32_dpp v36, v36, v36 row_ror:2 row_mask:0xf bank_mask:0xf bound_ctrl:1
	v_pk_mul_f32 v[48:49], v[48:49], v[62:63] op_sel_hi:[1,0]
	v_add_f32_dpp v34, v34, v34 row_ror:4 row_mask:0xf bank_mask:0xf bound_ctrl:1
	v_pk_fma_f32 v[48:49], v[24:25], v[44:45], v[48:49]
	s_nop 0
	v_add_f32_dpp v34, v34, v34 row_ror:8 row_mask:0xf bank_mask:0xf bound_ctrl:1
	v_pk_fma_f32 v[22:23], v[54:55], v[34:35], v[46:47] op_sel_hi:[1,0,1]
	v_pk_fma_f32 v[24:25], v[56:57], v[34:35], v[48:49] op_sel_hi:[1,0,1]
	s_waitcnt lgkmcnt(3)
; template <int CTRL> __device__ __forceinline__ float dpp_f(float x) { return __int_as_float(__builtin_amdgcn_update_dpp(0, __float_as_int(x), CTRL, 0xf, 0xf, false)); }
; __device__ __forceinline__ void p8_scan(const Args& a, LAS unsigned char* lds) {
;     ...
;                 for (int tt = 0; tt < TC; ++tt) {
;                     ScanOps n; scan_ld(n, bt + (tt + 1 < TC ? tt + 1 : tt) * SPITCH, jq4, myrow);
;                     __builtin_amdgcn_sched_barrier(0);
;                     f32x2 ta = S01 * o.al.lo, ty = S01 * o.wr.lo; ta = S23 * o.al.hi + ta; ty = S23 * o.wr.hi + ty;
;                     float pa = ta.x + ta.y, py = ty.x + ty.y;
;                     f32x2 kv01 = o.kv.lo * o.vi, kv23 = o.kv.hi * o.vi;
;     ...
;                     asm volatile("" : "+v"(kv01), "+v"(kv23), "+v"(vc));
;                     pa += dpp_f<0x121>(pa); py += dpp_f<0x121>(py); pa += dpp_f<0x122>(pa); py += dpp_f<0x122>(py);
;                     pa += dpp_f<0x124>(pa); pa += dpp_f<0x128>(pa);
;                     S01 = S01 * o.wv.lo + (o.be.lo * pa + kv01);
;                     S23 = S23 * o.wv.hi + (o.be.hi * pa + kv23);
;     ...
;                     __builtin_amdgcn_sched_barrier(0);
;                     o = n;
	v_pk_mul_f32 v[34:35], v[22:23], v[10:11]
	v_pk_mul_f32 v[66:67], v[22:23], v[58:59]
	v_pk_fma_f32 v[34:35], v[24:25], v[12:13], v[34:35]
	v_pk_fma_f32 v[66:67], v[24:25], v[60:61], v[66:67]
	ds_read_b128 v[50:53], v38 offset:27168
	ds_read_b128 v[46:49], v38 offset:26912
	ds_read_b32 v62, v39 offset:27936
	ds_read_b128 v[42:45], v38 offset:26656
	ds_read_b128 v[54:57], v38 offset:27424
	ds_read_b128 v[58:61], v38 offset:27680
	v_add_f32_e32 v34, v34, v35
	v_add_f32_e32 v66, v66, v67
	v_pk_mul_f32 v[6:7], v[6:7], v[28:29] op_sel_hi:[1,0]
	v_add_f32_dpp v34, v34, v34 row_ror:1 row_mask:0xf bank_mask:0xf bound_ctrl:1
	v_add_f32_dpp v66, v66, v66 row_ror:1 row_mask:0xf bank_mask:0xf bound_ctrl:1
	s_waitcnt lgkmcnt(7)
	v_pk_fma_f32 v[6:7], v[22:23], v[2:3], v[6:7]
	v_add_f32_dpp v34, v34, v34 row_ror:2 row_mask:0xf bank_mask:0xf bound_ctrl:1
	v_add_f32_dpp v66, v66, v66 row_ror:2 row_mask:0xf bank_mask:0xf bound_ctrl:1
	v_pk_mul_f32 v[8:9], v[8:9], v[28:29] op_sel_hi:[1,0]
	v_add_f32_dpp v34, v34, v34 row_ror:4 row_mask:0xf bank_mask:0xf bound_ctrl:1
	v_pk_fma_f32 v[8:9], v[24:25], v[4:5], v[8:9]
	ds_write2st64_b32 v41, v36, v66 offset0:14 offset1:15
	v_add_f32_dpp v34, v34, v34 row_ror:8 row_mask:0xf bank_mask:0xf bound_ctrl:1
	v_pk_fma_f32 v[22:23], v[14:15], v[34:35], v[6:7] op_sel_hi:[1,0,1]
	v_pk_fma_f32 v[24:25], v[16:17], v[34:35], v[8:9] op_sel_hi:[1,0,1]
	s_waitcnt lgkmcnt(4)
	v_pk_mul_f32 v[34:35], v[22:23], v[50:51]
	v_pk_mul_f32 v[36:37], v[22:23], v[18:19]
	v_pk_fma_f32 v[34:35], v[24:25], v[52:53], v[34:35]
	v_pk_fma_f32 v[36:37], v[24:25], v[20:21], v[36:37]
	ds_read_b128 v[10:13], v38 offset:28736
	ds_read_b128 v[6:9], v38 offset:28480
	ds_read_b32 v28, v39 offset:29504
	ds_read_b128 v[2:5], v38 offset:28224
	ds_read_b128 v[14:17], v38 offset:28992
	ds_read_b128 v[18:21], v38 offset:29248
	v_add_f32_e32 v34, v34, v35
	v_add_f32_e32 v36, v36, v37
	v_pk_mul_f32 v[46:47], v[46:47], v[62:63] op_sel_hi:[1,0]
	v_add_f32_dpp v34, v34, v34 row_ror:1 row_mask:0xf bank_mask:0xf bound_ctrl:1
	v_add_f32_dpp v36, v36, v36 row_ror:1 row_mask:0xf bank_mask:0xf bound_ctrl:1
	s_waitcnt lgkmcnt(8)
	v_pk_fma_f32 v[46:47], v[22:23], v[42:43], v[46:47]
	v_add_f32_dpp v34, v34, v34 row_ror:2 row_mask:0xf bank_mask:0xf bound_ctrl:1
	v_add_f32_dpp v36, v36, v36 row_ror:2 row_mask:0xf bank_mask:0xf bound_ctrl:1
	v_pk_mul_f32 v[48:49], v[48:49], v[62:63] op_sel_hi:[1,0]
	v_add_f32_dpp v34, v34, v34 row_ror:4 row_mask:0xf bank_mask:0xf bound_ctrl:1
	v_pk_fma_f32 v[48:49], v[24:25], v[44:45], v[48:49]
	s_nop 0
	v_add_f32_dpp v34, v34, v34 row_ror:8 row_mask:0xf bank_mask:0xf bound_ctrl:1
	v_pk_fma_f32 v[22:23], v[54:55], v[34:35], v[46:47] op_sel_hi:[1,0,1]
	v_pk_fma_f32 v[24:25], v[56:57], v[34:35], v[48:49] op_sel_hi:[1,0,1]
	s_waitcnt lgkmcnt(3)
	v_pk_mul_f32 v[34:35], v[22:23], v[10:11]
	v_pk_mul_f32 v[66:67], v[22:23], v[58:59]
	v_pk_fma_f32 v[34:35], v[24:25], v[12:13], v[34:35]
	v_pk_fma_f32 v[66:67], v[24:25], v[60:61], v[66:67]
	ds_read_b128 v[50:53], v38 offset:30304
	ds_read_b128 v[46:49], v38 offset:30048
	ds_read_b32 v62, v39 offset:31072
	ds_read_b128 v[42:45], v38 offset:29792
	ds_read_b128 v[54:57], v38 offset:30560
	ds_read_b128 v[58:61], v38 offset:30816
	v_add_f32_e32 v34, v34, v35
	v_add_f32_e32 v66, v66, v67
	v_pk_mul_f32 v[6:7], v[6:7], v[28:29] op_sel_hi:[1,0]
	v_add_f32_dpp v34, v34, v34 row_ror:1 row_mask:0xf bank_mask:0xf bound_ctrl:1
	v_add_f32_dpp v66, v66, v66 row_ror:1 row_mask:0xf bank_mask:0xf bound_ctrl:1
	s_waitcnt lgkmcnt(7)
	v_pk_fma_f32 v[6:7], v[22:23], v[2:3], v[6:7]
	v_add_f32_dpp v34, v34, v34 row_ror:2 row_mask:0xf bank_mask:0xf bound_ctrl:1
	v_add_f32_dpp v66, v66, v66 row_ror:2 row_mask:0xf bank_mask:0xf bound_ctrl:1
	v_pk_mul_f32 v[8:9], v[8:9], v[28:29] op_sel_hi:[1,0]
	v_add_f32_dpp v34, v34, v34 row_ror:4 row_mask:0xf bank_mask:0xf bound_ctrl:1
	v_pk_fma_f32 v[8:9], v[24:25], v[4:5], v[8:9]
	ds_write2st64_b32 v41, v36, v66 offset0:16 offset1:17
	v_add_f32_dpp v34, v34, v34 row_ror:8 row_mask:0xf bank_mask:0xf bound_ctrl:1
	v_pk_fma_f32 v[22:23], v[14:15], v[34:35], v[6:7] op_sel_hi:[1,0,1]
	v_pk_fma_f32 v[24:25], v[16:17], v[34:35], v[8:9] op_sel_hi:[1,0,1]
	s_waitcnt lgkmcnt(4)
	v_pk_mul_f32 v[34:35], v[22:23], v[50:51]
	v_pk_mul_f32 v[36:37], v[22:23], v[18:19]
	v_pk_fma_f32 v[34:35], v[24:25], v[52:53], v[34:35]
	v_pk_fma_f32 v[36:37], v[24:25], v[20:21], v[36:37]
	ds_read_b128 v[10:13], v38 offset:31872
	ds_read_b128 v[6:9], v38 offset:31616
	ds_read_b32 v28, v39 offset:32640
	ds_read_b128 v[2:5], v38 offset:31360
	ds_read_b128 v[14:17], v38 offset:32128
	ds_read_b128 v[18:21], v38 offset:32384
	v_add_f32_e32 v34, v34, v35
	v_add_f32_e32 v36, v36, v37
	v_pk_mul_f32 v[46:47], v[46:47], v[62:63] op_sel_hi:[1,0]
	v_add_f32_dpp v34, v34, v34 row_ror:1 row_mask:0xf bank_mask:0xf bound_ctrl:1
	v_add_f32_dpp v36, v36, v36 row_ror:1 row_mask:0xf bank_mask:0xf bound_ctrl:1
	s_waitcnt lgkmcnt(8)
	v_pk_fma_f32 v[46:47], v[22:23], v[42:43], v[46:47]
	v_add_f32_dpp v34, v34, v34 row_ror:2 row_mask:0xf bank_mask:0xf bound_ctrl:1
	v_add_f32_dpp v36, v36, v36 row_ror:2 row_mask:0xf bank_mask:0xf bound_ctrl:1
	v_pk_mul_f32 v[48:49], v[48:49], v[62:63] op_sel_hi:[1,0]
	v_add_f32_dpp v34, v34, v34 row_ror:4 row_mask:0xf bank_mask:0xf bound_ctrl:1
	v_pk_fma_f32 v[48:49], v[24:25], v[44:45], v[48:49]
	s_nop 0
	v_add_f32_dpp v34, v34, v34 row_ror:8 row_mask:0xf bank_mask:0xf bound_ctrl:1
	v_pk_fma_f32 v[22:23], v[54:55], v[34:35], v[46:47] op_sel_hi:[1,0,1]
	v_pk_fma_f32 v[24:25], v[56:57], v[34:35], v[48:49] op_sel_hi:[1,0,1]
	s_waitcnt lgkmcnt(3)
; template <int CTRL> __device__ __forceinline__ float dpp_f(float x) { return __int_as_float(__builtin_amdgcn_update_dpp(0, __float_as_int(x), CTRL, 0xf, 0xf, false)); }
; __device__ __forceinline__ void p8_scan(const Args& a, LAS unsigned char* lds) {
;     ...
;                 for (int tt = 0; tt < TC; ++tt) {
;                     ScanOps n; scan_ld(n, bt + (tt + 1 < TC ? tt + 1 : tt) * SPITCH, jq4, myrow);
;                     __builtin_amdgcn_sched_barrier(0);
;                     f32x2 ta = S01 * o.al.lo, ty = S01 * o.wr.lo; ta = S23 * o.al.hi + ta; ty = S23 * o.wr.hi + ty;
;                     float pa = ta.x + ta.y, py = ty.x + ty.y;
;                     f32x2 kv01 = o.kv.lo * o.vi, kv23 = o.kv.hi * o.vi;
;     ...
;                     asm volatile("" : "+v"(kv01), "+v"(kv23), "+v"(vc));
;                     pa += dpp_f<0x121>(pa); py += dpp_f<0x121>(py); pa += dpp_f<0x122>(pa); py += dpp_f<0x122>(py);
;                     pa += dpp_f<0x124>(pa); pa += dpp_f<0x128>(pa);
;                     S01 = S01 * o.wv.lo + (o.be.lo * pa + kv01);
;                     S23 = S23 * o.wv.hi + (o.be.hi * pa + kv23);
;     ...
;                     __builtin_amdgcn_sched_barrier(0);
;                     o = n;
	v_pk_mul_f32 v[34:35], v[22:23], v[10:11]
	v_pk_mul_f32 v[66:67], v[22:23], v[58:59]
	v_pk_fma_f32 v[34:35], v[24:25], v[12:13], v[34:35]
	v_pk_fma_f32 v[66:67], v[24:25], v[60:61], v[66:67]
	ds_read_b128 v[50:53], v38 offset:33440
	ds_read_b128 v[46:49], v38 offset:33184
	ds_read_b32 v62, v39 offset:34208
	ds_read_b128 v[42:45], v38 offset:32928
	ds_read_b128 v[54:57], v38 offset:33696
	ds_read_b128 v[58:61], v38 offset:33952
	v_add_f32_e32 v34, v34, v35
	v_add_f32_e32 v66, v66, v67
	v_pk_mul_f32 v[6:7], v[6:7], v[28:29] op_sel_hi:[1,0]
	v_add_f32_dpp v34, v34, v34 row_ror:1 row_mask:0xf bank_mask:0xf bound_ctrl:1
	v_add_f32_dpp v66, v66, v66 row_ror:1 row_mask:0xf bank_mask:0xf bound_ctrl:1
	s_waitcnt lgkmcnt(7)
	v_pk_fma_f32 v[6:7], v[22:23], v[2:3], v[6:7]
	v_add_f32_dpp v34, v34, v34 row_ror:2 row_mask:0xf bank_mask:0xf bound_ctrl:1
	v_add_f32_dpp v66, v66, v66 row_ror:2 row_mask:0xf bank_mask:0xf bound_ctrl:1
	v_pk_mul_f32 v[8:9], v[8:9], v[28:29] op_sel_hi:[1,0]
	v_add_f32_dpp v34, v34, v34 row_ror:4 row_mask:0xf bank_mask:0xf bound_ctrl:1
	v_pk_fma_f32 v[8:9], v[24:25], v[4:5], v[8:9]
	ds_write2st64_b32 v41, v36, v66 offset0:18 offset1:19
	v_add_f32_dpp v34, v34, v34 row_ror:8 row_mask:0xf bank_mask:0xf bound_ctrl:1
	v_pk_fma_f32 v[22:23], v[14:15], v[34:35], v[6:7] op_sel_hi:[1,0,1]
	v_pk_fma_f32 v[24:25], v[16:17], v[34:35], v[8:9] op_sel_hi:[1,0,1]
	s_waitcnt lgkmcnt(4)
	v_pk_mul_f32 v[34:35], v[22:23], v[50:51]
	v_pk_mul_f32 v[36:37], v[22:23], v[18:19]
	v_pk_fma_f32 v[34:35], v[24:25], v[52:53], v[34:35]
	v_pk_fma_f32 v[36:37], v[24:25], v[20:21], v[36:37]
	ds_read_b128 v[10:13], v38 offset:35008
	ds_read_b128 v[6:9], v38 offset:34752
	ds_read_b32 v28, v39 offset:35776
	ds_read_b128 v[2:5], v38 offset:34496
	ds_read_b128 v[14:17], v38 offset:35264
	ds_read_b128 v[18:21], v38 offset:35520
	v_add_f32_e32 v34, v34, v35
	v_add_f32_e32 v36, v36, v37
	v_pk_mul_f32 v[46:47], v[46:47], v[62:63] op_sel_hi:[1,0]
	v_add_f32_dpp v34, v34, v34 row_ror:1 row_mask:0xf bank_mask:0xf bound_ctrl:1
	v_add_f32_dpp v36, v36, v36 row_ror:1 row_mask:0xf bank_mask:0xf bound_ctrl:1
	s_waitcnt lgkmcnt(8)
	v_pk_fma_f32 v[46:47], v[22:23], v[42:43], v[46:47]
	v_add_f32_dpp v34, v34, v34 row_ror:2 row_mask:0xf bank_mask:0xf bound_ctrl:1
	v_add_f32_dpp v36, v36, v36 row_ror:2 row_mask:0xf bank_mask:0xf bound_ctrl:1
	v_pk_mul_f32 v[48:49], v[48:49], v[62:63] op_sel_hi:[1,0]
	v_add_f32_dpp v34, v34, v34 row_ror:4 row_mask:0xf bank_mask:0xf bound_ctrl:1
	v_pk_fma_f32 v[48:49], v[24:25], v[44:45], v[48:49]
	s_nop 0
	v_add_f32_dpp v34, v34, v34 row_ror:8 row_mask:0xf bank_mask:0xf bound_ctrl:1
	v_pk_fma_f32 v[22:23], v[54:55], v[34:35], v[46:47] op_sel_hi:[1,0,1]
	v_pk_fma_f32 v[24:25], v[56:57], v[34:35], v[48:49] op_sel_hi:[1,0,1]
	s_waitcnt lgkmcnt(3)
	v_pk_mul_f32 v[34:35], v[22:23], v[10:11]
	v_pk_mul_f32 v[66:67], v[22:23], v[58:59]
	v_pk_fma_f32 v[34:35], v[24:25], v[12:13], v[34:35]
	v_pk_fma_f32 v[66:67], v[24:25], v[60:61], v[66:67]
	ds_read_b128 v[50:53], v38 offset:36576
	ds_read_b128 v[46:49], v38 offset:36320
	ds_read_b32 v62, v39 offset:37344
	ds_read_b128 v[42:45], v38 offset:36064
	ds_read_b128 v[54:57], v38 offset:36832
	ds_read_b128 v[58:61], v38 offset:37088
	v_add_f32_e32 v34, v34, v35
	v_add_f32_e32 v66, v66, v67
	v_pk_mul_f32 v[6:7], v[6:7], v[28:29] op_sel_hi:[1,0]
	v_add_f32_dpp v34, v34, v34 row_ror:1 row_mask:0xf bank_mask:0xf bound_ctrl:1
	v_add_f32_dpp v66, v66, v66 row_ror:1 row_mask:0xf bank_mask:0xf bound_ctrl:1
	s_waitcnt lgkmcnt(7)
	v_pk_fma_f32 v[6:7], v[22:23], v[2:3], v[6:7]
	v_add_f32_dpp v34, v34, v34 row_ror:2 row_mask:0xf bank_mask:0xf bound_ctrl:1
	v_add_f32_dpp v66, v66, v66 row_ror:2 row_mask:0xf bank_mask:0xf bound_ctrl:1
	v_pk_mul_f32 v[8:9], v[8:9], v[28:29] op_sel_hi:[1,0]
	v_add_f32_dpp v34, v34, v34 row_ror:4 row_mask:0xf bank_mask:0xf bound_ctrl:1
	v_pk_fma_f32 v[8:9], v[24:25], v[4:5], v[8:9]
	ds_write2st64_b32 v41, v36, v66 offset0:20 offset1:21
	v_add_f32_dpp v34, v34, v34 row_ror:8 row_mask:0xf bank_mask:0xf bound_ctrl:1
	v_pk_fma_f32 v[22:23], v[14:15], v[34:35], v[6:7] op_sel_hi:[1,0,1]
	v_pk_fma_f32 v[24:25], v[16:17], v[34:35], v[8:9] op_sel_hi:[1,0,1]
	s_waitcnt lgkmcnt(4)
	v_pk_mul_f32 v[34:35], v[22:23], v[50:51]
	v_pk_mul_f32 v[36:37], v[22:23], v[18:19]
	v_pk_fma_f32 v[34:35], v[24:25], v[52:53], v[34:35]
	v_pk_fma_f32 v[36:37], v[24:25], v[20:21], v[36:37]
	ds_read_b128 v[10:13], v38 offset:38144
	ds_read_b128 v[6:9], v38 offset:37888
	ds_read_b32 v28, v39 offset:38912
	ds_read_b128 v[2:5], v38 offset:37632
	ds_read_b128 v[14:17], v38 offset:38400
	ds_read_b128 v[18:21], v38 offset:38656
	v_add_f32_e32 v34, v34, v35
	v_add_f32_e32 v36, v36, v37
	v_pk_mul_f32 v[46:47], v[46:47], v[62:63] op_sel_hi:[1,0]
	v_add_f32_dpp v34, v34, v34 row_ror:1 row_mask:0xf bank_mask:0xf bound_ctrl:1
	v_add_f32_dpp v36, v36, v36 row_ror:1 row_mask:0xf bank_mask:0xf bound_ctrl:1
	s_waitcnt lgkmcnt(8)
	v_pk_fma_f32 v[46:47], v[22:23], v[42:43], v[46:47]
	v_add_f32_dpp v34, v34, v34 row_ror:2 row_mask:0xf bank_mask:0xf bound_ctrl:1
	v_add_f32_dpp v36, v36, v36 row_ror:2 row_mask:0xf bank_mask:0xf bound_ctrl:1
	v_pk_mul_f32 v[48:49], v[48:49], v[62:63] op_sel_hi:[1,0]
	v_add_f32_dpp v34, v34, v34 row_ror:4 row_mask:0xf bank_mask:0xf bound_ctrl:1
	v_pk_fma_f32 v[48:49], v[24:25], v[44:45], v[48:49]
	s_nop 0
	v_add_f32_dpp v34, v34, v34 row_ror:8 row_mask:0xf bank_mask:0xf bound_ctrl:1
	v_pk_fma_f32 v[22:23], v[54:55], v[34:35], v[46:47] op_sel_hi:[1,0,1]
	v_pk_fma_f32 v[24:25], v[56:57], v[34:35], v[48:49] op_sel_hi:[1,0,1]
	s_waitcnt lgkmcnt(3)
; template <int CTRL> __device__ __forceinline__ float dpp_f(float x) { return __int_as_float(__builtin_amdgcn_update_dpp(0, __float_as_int(x), CTRL, 0xf, 0xf, false)); }
; __device__ __forceinline__ void p8_scan(const Args& a, LAS unsigned char* lds) {
;     ...
;                 for (int tt = 0; tt < TC; ++tt) {
;                     ScanOps n; scan_ld(n, bt + (tt + 1 < TC ? tt + 1 : tt) * SPITCH, jq4, myrow);
;                     __builtin_amdgcn_sched_barrier(0);
;                     f32x2 ta = S01 * o.al.lo, ty = S01 * o.wr.lo; ta = S23 * o.al.hi + ta; ty = S23 * o.wr.hi + ty;
;                     float pa = ta.x + ta.y, py = ty.x + ty.y;
;                     f32x2 kv01 = o.kv.lo * o.vi, kv23 = o.kv.hi * o.vi;
;     ...
;                     asm volatile("" : "+v"(kv01), "+v"(kv23), "+v"(vc));
;                     pa += dpp_f<0x121>(pa); py += dpp_f<0x121>(py); pa += dpp_f<0x122>(pa); py += dpp_f<0x122>(py);
;                     pa += dpp_f<0x124>(pa); pa += dpp_f<0x128>(pa);
;                     S01 = S01 * o.wv.lo + (o.be.lo * pa + kv01);
;                     S23 = S23 * o.wv.hi + (o.be.hi * pa + kv23);
;     ...
;                     __builtin_amdgcn_sched_barrier(0);
;                     o = n;
	v_pk_mul_f32 v[34:35], v[22:23], v[10:11]
	v_pk_mul_f32 v[66:67], v[22:23], v[58:59]
	v_pk_fma_f32 v[34:35], v[24:25], v[12:13], v[34:35]
	v_pk_fma_f32 v[66:67], v[24:25], v[60:61], v[66:67]
	ds_read_b128 v[50:53], v38 offset:39712
	ds_read_b128 v[46:49], v38 offset:39456
	ds_read_b32 v62, v39 offset:40480
	ds_read_b128 v[42:45], v38 offset:39200
	ds_read_b128 v[54:57], v38 offset:39968
	ds_read_b128 v[58:61], v38 offset:40224
	v_add_f32_e32 v34, v34, v35
	v_add_f32_e32 v66, v66, v67
	v_pk_mul_f32 v[6:7], v[6:7], v[28:29] op_sel_hi:[1,0]
	v_add_f32_dpp v34, v34, v34 row_ror:1 row_mask:0xf bank_mask:0xf bound_ctrl:1
	v_add_f32_dpp v66, v66, v66 row_ror:1 row_mask:0xf bank_mask:0xf bound_ctrl:1
	s_waitcnt lgkmcnt(7)
	v_pk_fma_f32 v[6:7], v[22:23], v[2:3], v[6:7]
	v_add_f32_dpp v34, v34, v34 row_ror:2 row_mask:0xf bank_mask:0xf bound_ctrl:1
	v_add_f32_dpp v66, v66, v66 row_ror:2 row_mask:0xf bank_mask:0xf bound_ctrl:1
	v_pk_mul_f32 v[8:9], v[8:9], v[28:29] op_sel_hi:[1,0]
	v_add_f32_dpp v34, v34, v34 row_ror:4 row_mask:0xf bank_mask:0xf bound_ctrl:1
	v_pk_fma_f32 v[8:9], v[24:25], v[4:5], v[8:9]
	ds_write2st64_b32 v41, v36, v66 offset0:22 offset1:23
	v_add_f32_dpp v34, v34, v34 row_ror:8 row_mask:0xf bank_mask:0xf bound_ctrl:1
	v_pk_fma_f32 v[22:23], v[14:15], v[34:35], v[6:7] op_sel_hi:[1,0,1]
	v_pk_fma_f32 v[24:25], v[16:17], v[34:35], v[8:9] op_sel_hi:[1,0,1]
	s_waitcnt lgkmcnt(4)
	v_pk_mul_f32 v[34:35], v[22:23], v[50:51]
	v_pk_mul_f32 v[36:37], v[22:23], v[18:19]
	v_pk_fma_f32 v[34:35], v[24:25], v[52:53], v[34:35]
	v_pk_fma_f32 v[36:37], v[24:25], v[20:21], v[36:37]
	ds_read_b128 v[10:13], v38 offset:41280
	ds_read_b128 v[6:9], v38 offset:41024
	ds_read_b32 v28, v39 offset:42048
	ds_read_b128 v[2:5], v38 offset:40768
	ds_read_b128 v[14:17], v38 offset:41536
	ds_read_b128 v[18:21], v38 offset:41792
	v_add_f32_e32 v34, v34, v35
	v_add_f32_e32 v36, v36, v37
	v_pk_mul_f32 v[46:47], v[46:47], v[62:63] op_sel_hi:[1,0]
	v_add_f32_dpp v34, v34, v34 row_ror:1 row_mask:0xf bank_mask:0xf bound_ctrl:1
	v_add_f32_dpp v36, v36, v36 row_ror:1 row_mask:0xf bank_mask:0xf bound_ctrl:1
	s_waitcnt lgkmcnt(8)
	v_pk_fma_f32 v[46:47], v[22:23], v[42:43], v[46:47]
	v_add_f32_dpp v34, v34, v34 row_ror:2 row_mask:0xf bank_mask:0xf bound_ctrl:1
	v_add_f32_dpp v36, v36, v36 row_ror:2 row_mask:0xf bank_mask:0xf bound_ctrl:1
	v_pk_mul_f32 v[48:49], v[48:49], v[62:63] op_sel_hi:[1,0]
	v_add_f32_dpp v34, v34, v34 row_ror:4 row_mask:0xf bank_mask:0xf bound_ctrl:1
	v_pk_fma_f32 v[48:49], v[24:25], v[44:45], v[48:49]
	s_nop 0
	v_add_f32_dpp v34, v34, v34 row_ror:8 row_mask:0xf bank_mask:0xf bound_ctrl:1
	v_pk_fma_f32 v[22:23], v[54:55], v[34:35], v[46:47] op_sel_hi:[1,0,1]
	v_pk_fma_f32 v[24:25], v[56:57], v[34:35], v[48:49] op_sel_hi:[1,0,1]
	s_waitcnt lgkmcnt(3)
	v_pk_mul_f32 v[34:35], v[22:23], v[10:11]
	v_pk_mul_f32 v[66:67], v[22:23], v[58:59]
	v_pk_fma_f32 v[34:35], v[24:25], v[12:13], v[34:35]
	v_pk_fma_f32 v[66:67], v[24:25], v[60:61], v[66:67]
	ds_read_b128 v[50:53], v38 offset:42848
	ds_read_b128 v[46:49], v38 offset:42592
	ds_read_b32 v62, v39 offset:43616
	ds_read_b128 v[42:45], v38 offset:42336
	ds_read_b128 v[54:57], v38 offset:43104
	ds_read_b128 v[58:61], v38 offset:43360
	v_add_f32_e32 v34, v34, v35
	v_add_f32_e32 v66, v66, v67
	v_pk_mul_f32 v[6:7], v[6:7], v[28:29] op_sel_hi:[1,0]
	v_add_f32_dpp v34, v34, v34 row_ror:1 row_mask:0xf bank_mask:0xf bound_ctrl:1
	v_add_f32_dpp v66, v66, v66 row_ror:1 row_mask:0xf bank_mask:0xf bound_ctrl:1
	s_waitcnt lgkmcnt(7)
	v_pk_fma_f32 v[6:7], v[22:23], v[2:3], v[6:7]
	v_add_f32_dpp v34, v34, v34 row_ror:2 row_mask:0xf bank_mask:0xf bound_ctrl:1
	v_add_f32_dpp v66, v66, v66 row_ror:2 row_mask:0xf bank_mask:0xf bound_ctrl:1
	v_pk_mul_f32 v[8:9], v[8:9], v[28:29] op_sel_hi:[1,0]
	v_add_f32_dpp v34, v34, v34 row_ror:4 row_mask:0xf bank_mask:0xf bound_ctrl:1
	v_pk_fma_f32 v[8:9], v[24:25], v[4:5], v[8:9]
	ds_write2st64_b32 v41, v36, v66 offset0:24 offset1:25
	v_add_f32_dpp v34, v34, v34 row_ror:8 row_mask:0xf bank_mask:0xf bound_ctrl:1
	v_pk_fma_f32 v[22:23], v[14:15], v[34:35], v[6:7] op_sel_hi:[1,0,1]
	v_pk_fma_f32 v[24:25], v[16:17], v[34:35], v[8:9] op_sel_hi:[1,0,1]
	s_waitcnt lgkmcnt(4)
	v_pk_mul_f32 v[34:35], v[22:23], v[50:51]
	v_pk_mul_f32 v[36:37], v[22:23], v[18:19]
	v_pk_fma_f32 v[34:35], v[24:25], v[52:53], v[34:35]
	v_pk_fma_f32 v[36:37], v[24:25], v[20:21], v[36:37]
	ds_read_b128 v[10:13], v38 offset:44416
	ds_read_b128 v[6:9], v38 offset:44160
	ds_read_b32 v28, v39 offset:45184
	ds_read_b128 v[2:5], v38 offset:43904
	ds_read_b128 v[14:17], v38 offset:44672
	ds_read_b128 v[18:21], v38 offset:44928
	v_add_f32_e32 v34, v34, v35
	v_add_f32_e32 v36, v36, v37
	v_pk_mul_f32 v[46:47], v[46:47], v[62:63] op_sel_hi:[1,0]
	v_add_f32_dpp v34, v34, v34 row_ror:1 row_mask:0xf bank_mask:0xf bound_ctrl:1
	v_add_f32_dpp v36, v36, v36 row_ror:1 row_mask:0xf bank_mask:0xf bound_ctrl:1
	s_waitcnt lgkmcnt(8)
	v_pk_fma_f32 v[46:47], v[22:23], v[42:43], v[46:47]
	v_add_f32_dpp v34, v34, v34 row_ror:2 row_mask:0xf bank_mask:0xf bound_ctrl:1
	v_add_f32_dpp v36, v36, v36 row_ror:2 row_mask:0xf bank_mask:0xf bound_ctrl:1
	v_pk_mul_f32 v[48:49], v[48:49], v[62:63] op_sel_hi:[1,0]
	v_add_f32_dpp v34, v34, v34 row_ror:4 row_mask:0xf bank_mask:0xf bound_ctrl:1
	v_pk_fma_f32 v[48:49], v[24:25], v[44:45], v[48:49]
	s_nop 0
	v_add_f32_dpp v34, v34, v34 row_ror:8 row_mask:0xf bank_mask:0xf bound_ctrl:1
	v_pk_fma_f32 v[22:23], v[54:55], v[34:35], v[46:47] op_sel_hi:[1,0,1]
	v_pk_fma_f32 v[24:25], v[56:57], v[34:35], v[48:49] op_sel_hi:[1,0,1]
	s_waitcnt lgkmcnt(3)
; template <int CTRL> __device__ __forceinline__ float dpp_f(float x) { return __int_as_float(__builtin_amdgcn_update_dpp(0, __float_as_int(x), CTRL, 0xf, 0xf, false)); }
; __device__ __forceinline__ void p8_scan(const Args& a, LAS unsigned char* lds) {
;     ...
;                 for (int tt = 0; tt < TC; ++tt) {
;                     ScanOps n; scan_ld(n, bt + (tt + 1 < TC ? tt + 1 : tt) * SPITCH, jq4, myrow);
;                     __builtin_amdgcn_sched_barrier(0);
;                     f32x2 ta = S01 * o.al.lo, ty = S01 * o.wr.lo; ta = S23 * o.al.hi + ta; ty = S23 * o.wr.hi + ty;
;                     float pa = ta.x + ta.y, py = ty.x + ty.y;
;                     f32x2 kv01 = o.kv.lo * o.vi, kv23 = o.kv.hi * o.vi;
;     ...
;                     asm volatile("" : "+v"(kv01), "+v"(kv23), "+v"(vc));
;                     pa += dpp_f<0x121>(pa); py += dpp_f<0x121>(py); pa += dpp_f<0x122>(pa); py += dpp_f<0x122>(py);
;                     pa += dpp_f<0x124>(pa); pa += dpp_f<0x128>(pa);
;                     S01 = S01 * o.wv.lo + (o.be.lo * pa + kv01);
;                     S23 = S23 * o.wv.hi + (o.be.hi * pa + kv23);
;     ...
;                     __builtin_amdgcn_sched_barrier(0);
;                     o = n;
;                 }
;                 __syncthreads();
	v_pk_mul_f32 v[34:35], v[22:23], v[10:11]
	v_pk_mul_f32 v[66:67], v[22:23], v[58:59]
	v_pk_fma_f32 v[34:35], v[24:25], v[12:13], v[34:35]
	v_pk_fma_f32 v[66:67], v[24:25], v[60:61], v[66:67]
	ds_read_b128 v[50:53], v38 offset:45984
	ds_read_b128 v[46:49], v38 offset:45728
	ds_read_b32 v62, v39 offset:46752
	ds_read_b128 v[42:45], v38 offset:45472
	ds_read_b128 v[54:57], v38 offset:46240
	ds_read_b128 v[58:61], v38 offset:46496
	v_add_f32_e32 v34, v34, v35
	v_add_f32_e32 v66, v66, v67
	v_pk_mul_f32 v[6:7], v[6:7], v[28:29] op_sel_hi:[1,0]
	v_add_f32_dpp v34, v34, v34 row_ror:1 row_mask:0xf bank_mask:0xf bound_ctrl:1
	v_add_f32_dpp v66, v66, v66 row_ror:1 row_mask:0xf bank_mask:0xf bound_ctrl:1
	s_waitcnt lgkmcnt(7)
	v_pk_fma_f32 v[6:7], v[22:23], v[2:3], v[6:7]
	v_add_f32_dpp v34, v34, v34 row_ror:2 row_mask:0xf bank_mask:0xf bound_ctrl:1
	v_add_f32_dpp v66, v66, v66 row_ror:2 row_mask:0xf bank_mask:0xf bound_ctrl:1
	v_pk_mul_f32 v[8:9], v[8:9], v[28:29] op_sel_hi:[1,0]
	v_add_f32_dpp v34, v34, v34 row_ror:4 row_mask:0xf bank_mask:0xf bound_ctrl:1
	v_pk_fma_f32 v[8:9], v[24:25], v[4:5], v[8:9]
	ds_write2st64_b32 v41, v36, v66 offset0:26 offset1:27
	v_add_f32_dpp v34, v34, v34 row_ror:8 row_mask:0xf bank_mask:0xf bound_ctrl:1
	v_pk_fma_f32 v[22:23], v[14:15], v[34:35], v[6:7] op_sel_hi:[1,0,1]
	v_pk_fma_f32 v[24:25], v[16:17], v[34:35], v[8:9] op_sel_hi:[1,0,1]
	s_waitcnt lgkmcnt(4)
	v_pk_mul_f32 v[34:35], v[22:23], v[50:51]
	v_pk_mul_f32 v[36:37], v[22:23], v[18:19]
	v_pk_fma_f32 v[34:35], v[24:25], v[52:53], v[34:35]
	v_pk_fma_f32 v[36:37], v[24:25], v[20:21], v[36:37]
	ds_read_b128 v[10:13], v38 offset:47552
	ds_read_b128 v[6:9], v38 offset:47296
	ds_read_b32 v28, v39 offset:48320
	ds_read_b128 v[2:5], v38 offset:47040
	ds_read_b128 v[14:17], v38 offset:47808
	ds_read_b128 v[18:21], v38 offset:48064
	v_add_f32_e32 v34, v34, v35
	v_add_f32_e32 v36, v36, v37
	v_pk_mul_f32 v[46:47], v[46:47], v[62:63] op_sel_hi:[1,0]
	v_add_f32_dpp v34, v34, v34 row_ror:1 row_mask:0xf bank_mask:0xf bound_ctrl:1
	v_add_f32_dpp v36, v36, v36 row_ror:1 row_mask:0xf bank_mask:0xf bound_ctrl:1
	s_waitcnt lgkmcnt(8)
	v_pk_fma_f32 v[46:47], v[22:23], v[42:43], v[46:47]
	v_add_f32_dpp v34, v34, v34 row_ror:2 row_mask:0xf bank_mask:0xf bound_ctrl:1
	v_add_f32_dpp v36, v36, v36 row_ror:2 row_mask:0xf bank_mask:0xf bound_ctrl:1
	v_pk_mul_f32 v[48:49], v[48:49], v[62:63] op_sel_hi:[1,0]
	v_add_f32_dpp v34, v34, v34 row_ror:4 row_mask:0xf bank_mask:0xf bound_ctrl:1
	v_pk_fma_f32 v[48:49], v[24:25], v[44:45], v[48:49]
	s_nop 0
	v_add_f32_dpp v34, v34, v34 row_ror:8 row_mask:0xf bank_mask:0xf bound_ctrl:1
	v_pk_fma_f32 v[22:23], v[54:55], v[34:35], v[46:47] op_sel_hi:[1,0,1]
	v_pk_fma_f32 v[24:25], v[56:57], v[34:35], v[48:49] op_sel_hi:[1,0,1]
	s_waitcnt lgkmcnt(3)
	s_barrier
	v_pk_mul_f32 v[34:35], v[22:23], v[10:11]
	v_pk_mul_f32 v[66:67], v[22:23], v[58:59]
	v_pk_fma_f32 v[34:35], v[24:25], v[12:13], v[34:35]
	v_pk_fma_f32 v[66:67], v[24:25], v[60:61], v[66:67]
	ds_read_b128 v[50:53], v38 offset:49120
	ds_read_b128 v[46:49], v38 offset:48864
	ds_read_b32 v62, v39 offset:49888
	ds_read_b128 v[42:45], v38 offset:48608
	ds_read_b128 v[54:57], v38 offset:49376
	ds_read_b128 v[58:61], v38 offset:49632
	v_add_f32_e32 v34, v34, v35
	v_add_f32_e32 v66, v66, v67
	v_pk_mul_f32 v[6:7], v[6:7], v[28:29] op_sel_hi:[1,0]
	v_add_f32_dpp v34, v34, v34 row_ror:1 row_mask:0xf bank_mask:0xf bound_ctrl:1
	v_add_f32_dpp v66, v66, v66 row_ror:1 row_mask:0xf bank_mask:0xf bound_ctrl:1
	s_waitcnt lgkmcnt(7)
	v_pk_fma_f32 v[6:7], v[22:23], v[2:3], v[6:7]
	v_add_f32_dpp v34, v34, v34 row_ror:2 row_mask:0xf bank_mask:0xf bound_ctrl:1
	v_add_f32_dpp v66, v66, v66 row_ror:2 row_mask:0xf bank_mask:0xf bound_ctrl:1
	v_pk_mul_f32 v[8:9], v[8:9], v[28:29] op_sel_hi:[1,0]
	v_add_f32_dpp v34, v34, v34 row_ror:4 row_mask:0xf bank_mask:0xf bound_ctrl:1
	v_pk_fma_f32 v[8:9], v[24:25], v[4:5], v[8:9]
	ds_write2st64_b32 v41, v36, v66 offset0:28 offset1:29
	v_add_f32_dpp v34, v34, v34 row_ror:8 row_mask:0xf bank_mask:0xf bound_ctrl:1
	v_pk_fma_f32 v[22:23], v[14:15], v[34:35], v[6:7] op_sel_hi:[1,0,1]
	v_pk_fma_f32 v[24:25], v[16:17], v[34:35], v[8:9] op_sel_hi:[1,0,1]
	s_waitcnt lgkmcnt(4)
	v_pk_mul_f32 v[34:35], v[22:23], v[50:51]
	v_pk_mul_f32 v[36:37], v[22:23], v[18:19]
	v_pk_fma_f32 v[34:35], v[24:25], v[52:53], v[34:35]
	v_pk_fma_f32 v[36:37], v[24:25], v[20:21], v[36:37]
	ds_read_b128 v[10:13], v68 offset:512
	ds_read_b128 v[6:9], v68 offset:256
	ds_read_b32 v28, v69 offset:1280
	ds_read_b128 v[2:5], v68 offset:0
	ds_read_b128 v[14:17], v68 offset:768
	ds_read_b128 v[18:21], v68 offset:1024
	v_add_f32_e32 v34, v34, v35
	v_add_f32_e32 v36, v36, v37
	v_pk_mul_f32 v[46:47], v[46:47], v[62:63] op_sel_hi:[1,0]
	v_add_f32_dpp v34, v34, v34 row_ror:1 row_mask:0xf bank_mask:0xf bound_ctrl:1
	v_add_f32_dpp v36, v36, v36 row_ror:1 row_mask:0xf bank_mask:0xf bound_ctrl:1
	s_waitcnt lgkmcnt(7)
	v_pk_fma_f32 v[46:47], v[22:23], v[42:43], v[46:47]
	v_add_f32_dpp v34, v34, v34 row_ror:2 row_mask:0xf bank_mask:0xf bound_ctrl:1
	v_add_f32_dpp v36, v36, v36 row_ror:2 row_mask:0xf bank_mask:0xf bound_ctrl:1
	v_pk_mul_f32 v[48:49], v[48:49], v[62:63] op_sel_hi:[1,0]
	v_add_f32_dpp v34, v34, v34 row_ror:4 row_mask:0xf bank_mask:0xf bound_ctrl:1
	v_pk_fma_f32 v[48:49], v[24:25], v[44:45], v[48:49]
	s_nop 0
	v_add_f32_dpp v34, v34, v34 row_ror:8 row_mask:0xf bank_mask:0xf bound_ctrl:1
	v_pk_fma_f32 v[22:23], v[54:55], v[34:35], v[46:47] op_sel_hi:[1,0,1]
	v_pk_fma_f32 v[24:25], v[56:57], v[34:35], v[48:49] op_sel_hi:[1,0,1]
	v_pk_mul_f32 v[66:67], v[22:23], v[58:59]
	v_pk_fma_f32 v[66:67], v[24:25], v[60:61], v[66:67]
	v_add_f32_e32 v66, v66, v67
	s_nop 1
	v_add_f32_dpp v66, v66, v66 row_ror:1 row_mask:0xf bank_mask:0xf bound_ctrl:1
	s_nop 1
	v_add_f32_dpp v66, v66, v66 row_ror:2 row_mask:0xf bank_mask:0xf bound_ctrl:1
	ds_write2st64_b32 v41, v36, v66 offset0:30 offset1:31
	s_waitcnt lgkmcnt(0)
	s_barrier
; template <int CTRL> __device__ __forceinline__ float dpp_f(float x) { return __int_as_float(__builtin_amdgcn_update_dpp(0, __float_as_int(x), CTRL, 0xf, 0xf, false)); }
; __device__ __forceinline__ void p8_scan(const Args& a, LAS unsigned char* lds) {
;     ...
;                 for (int tt = 0; tt < TC; ++tt) {
;                     ScanOps n; scan_ld(n, bt + (tt + 1 < TC ? tt + 1 : tt) * SPITCH, jq4, myrow);
;                     __builtin_amdgcn_sched_barrier(0);
;                     f32x2 ta = S01 * o.al.lo, ty = S01 * o.wr.lo; ta = S23 * o.al.hi + ta; ty = S23 * o.wr.hi + ty;
;                     float pa = ta.x + ta.y, py = ty.x + ty.y;
;                     f32x2 kv01 = o.kv.lo * o.vi, kv23 = o.kv.hi * o.vi;
;     ...
;                     asm volatile("" : "+v"(kv01), "+v"(kv23), "+v"(vc));
;                     pa += dpp_f<0x121>(pa); py += dpp_f<0x121>(py); pa += dpp_f<0x122>(pa); py += dpp_f<0x122>(py);
;                     pa += dpp_f<0x124>(pa); pa += dpp_f<0x128>(pa);
;                     S01 = S01 * o.wv.lo + (o.be.lo * pa + kv01);
;                     S23 = S23 * o.wv.hi + (o.be.hi * pa + kv23);
;     ...
;                     __builtin_amdgcn_sched_barrier(0);
;                     o = n;
	v_pk_mul_f32 v[34:35], v[22:23], v[10:11]
	v_pk_fma_f32 v[34:35], v[24:25], v[12:13], v[34:35]
	ds_read_b128 v[50:53], v68 offset:2080
	ds_read_b128 v[46:49], v68 offset:1824
	ds_read_b32 v62, v69 offset:2848
	ds_read_b128 v[42:45], v68 offset:1568
	ds_read_b128 v[54:57], v68 offset:2336
	ds_read_b128 v[58:61], v68 offset:2592
	v_add_f32_e32 v34, v34, v35
	v_pk_mul_f32 v[6:7], v[6:7], v[28:29] op_sel_hi:[1,0]
	v_pk_mul_f32 v[8:9], v[8:9], v[28:29] op_sel_hi:[1,0]
	v_add_f32_dpp v34, v34, v34 row_ror:1 row_mask:0xf bank_mask:0xf bound_ctrl:1
	v_pk_fma_f32 v[6:7], v[22:23], v[2:3], v[6:7]
	v_pk_fma_f32 v[8:9], v[24:25], v[4:5], v[8:9]
	v_add_f32_dpp v34, v34, v34 row_ror:2 row_mask:0xf bank_mask:0xf bound_ctrl:1
	s_nop 0
	s_nop 0
	v_add_f32_dpp v34, v34, v34 row_ror:4 row_mask:0xf bank_mask:0xf bound_ctrl:1
	s_nop 0
	s_nop 0
	v_add_f32_dpp v34, v34, v34 row_ror:8 row_mask:0xf bank_mask:0xf bound_ctrl:1
	v_pk_fma_f32 v[22:23], v[14:15], v[34:35], v[6:7] op_sel_hi:[1,0,1]
	v_pk_fma_f32 v[24:25], v[16:17], v[34:35], v[8:9] op_sel_hi:[1,0,1]
	s_waitcnt lgkmcnt(3)
	v_pk_mul_f32 v[34:35], v[22:23], v[50:51]
	v_pk_mul_f32 v[36:37], v[22:23], v[18:19]
	v_pk_fma_f32 v[34:35], v[24:25], v[52:53], v[34:35]
	v_pk_fma_f32 v[36:37], v[24:25], v[20:21], v[36:37]
	ds_read_b128 v[10:13], v68 offset:3648
	ds_read_b128 v[6:9], v68 offset:3392
	ds_read_b32 v28, v69 offset:4416
	ds_read_b128 v[2:5], v68 offset:3136
	ds_read_b128 v[14:17], v68 offset:3904
	ds_read_b128 v[18:21], v68 offset:4160
	v_add_f32_e32 v34, v34, v35
	v_add_f32_e32 v36, v36, v37
	v_pk_mul_f32 v[46:47], v[46:47], v[62:63] op_sel_hi:[1,0]
	v_add_f32_dpp v34, v34, v34 row_ror:1 row_mask:0xf bank_mask:0xf bound_ctrl:1
	v_add_f32_dpp v36, v36, v36 row_ror:1 row_mask:0xf bank_mask:0xf bound_ctrl:1
	s_waitcnt lgkmcnt(7)
	v_pk_fma_f32 v[46:47], v[22:23], v[42:43], v[46:47]
	v_add_f32_dpp v34, v34, v34 row_ror:2 row_mask:0xf bank_mask:0xf bound_ctrl:1
	v_add_f32_dpp v36, v36, v36 row_ror:2 row_mask:0xf bank_mask:0xf bound_ctrl:1
	v_pk_mul_f32 v[48:49], v[48:49], v[62:63] op_sel_hi:[1,0]
	v_add_f32_dpp v34, v34, v34 row_ror:4 row_mask:0xf bank_mask:0xf bound_ctrl:1
	v_pk_fma_f32 v[48:49], v[24:25], v[44:45], v[48:49]
	s_nop 0
	v_add_f32_dpp v34, v34, v34 row_ror:8 row_mask:0xf bank_mask:0xf bound_ctrl:1
	v_pk_fma_f32 v[22:23], v[54:55], v[34:35], v[46:47] op_sel_hi:[1,0,1]
	v_pk_fma_f32 v[24:25], v[56:57], v[34:35], v[48:49] op_sel_hi:[1,0,1]
	s_waitcnt lgkmcnt(3)
	v_pk_mul_f32 v[34:35], v[22:23], v[10:11]
	v_pk_mul_f32 v[66:67], v[22:23], v[58:59]
	v_pk_fma_f32 v[34:35], v[24:25], v[12:13], v[34:35]
	v_pk_fma_f32 v[66:67], v[24:25], v[60:61], v[66:67]
	ds_read_b128 v[50:53], v68 offset:5216
	ds_read_b128 v[46:49], v68 offset:4960
	ds_read_b32 v62, v69 offset:5984
	ds_read_b128 v[42:45], v68 offset:4704
	ds_read_b128 v[54:57], v68 offset:5472
	ds_read_b128 v[58:61], v68 offset:5728
	v_add_f32_e32 v34, v34, v35
	v_add_f32_e32 v66, v66, v67
	v_pk_mul_f32 v[6:7], v[6:7], v[28:29] op_sel_hi:[1,0]
	v_add_f32_dpp v34, v34, v34 row_ror:1 row_mask:0xf bank_mask:0xf bound_ctrl:1
	v_add_f32_dpp v66, v66, v66 row_ror:1 row_mask:0xf bank_mask:0xf bound_ctrl:1
	s_waitcnt lgkmcnt(7)
	v_pk_fma_f32 v[6:7], v[22:23], v[2:3], v[6:7]
	v_add_f32_dpp v34, v34, v34 row_ror:2 row_mask:0xf bank_mask:0xf bound_ctrl:1
	v_add_f32_dpp v66, v66, v66 row_ror:2 row_mask:0xf bank_mask:0xf bound_ctrl:1
	v_pk_mul_f32 v[8:9], v[8:9], v[28:29] op_sel_hi:[1,0]
	v_add_f32_dpp v34, v34, v34 row_ror:4 row_mask:0xf bank_mask:0xf bound_ctrl:1
	v_pk_fma_f32 v[8:9], v[24:25], v[4:5], v[8:9]
	ds_write2st64_b32 v71, v36, v66 offset0:0 offset1:1
	v_add_f32_dpp v34, v34, v34 row_ror:8 row_mask:0xf bank_mask:0xf bound_ctrl:1
	v_pk_fma_f32 v[22:23], v[14:15], v[34:35], v[6:7] op_sel_hi:[1,0,1]
	v_pk_fma_f32 v[24:25], v[16:17], v[34:35], v[8:9] op_sel_hi:[1,0,1]
	s_waitcnt lgkmcnt(4)
	v_pk_mul_f32 v[34:35], v[22:23], v[50:51]
	v_pk_mul_f32 v[36:37], v[22:23], v[18:19]
	v_pk_fma_f32 v[34:35], v[24:25], v[52:53], v[34:35]
	v_pk_fma_f32 v[36:37], v[24:25], v[20:21], v[36:37]
	ds_read_b128 v[10:13], v68 offset:6784
	ds_read_b128 v[6:9], v68 offset:6528
	ds_read_b32 v28, v69 offset:7552
	ds_read_b128 v[2:5], v68 offset:6272
	ds_read_b128 v[14:17], v68 offset:7040
	ds_read_b128 v[18:21], v68 offset:7296
	v_add_f32_e32 v34, v34, v35
	v_add_f32_e32 v36, v36, v37
	v_pk_mul_f32 v[46:47], v[46:47], v[62:63] op_sel_hi:[1,0]
	v_add_f32_dpp v34, v34, v34 row_ror:1 row_mask:0xf bank_mask:0xf bound_ctrl:1
	v_add_f32_dpp v36, v36, v36 row_ror:1 row_mask:0xf bank_mask:0xf bound_ctrl:1
	s_waitcnt lgkmcnt(8)
	v_pk_fma_f32 v[46:47], v[22:23], v[42:43], v[46:47]
	v_add_f32_dpp v34, v34, v34 row_ror:2 row_mask:0xf bank_mask:0xf bound_ctrl:1
	v_add_f32_dpp v36, v36, v36 row_ror:2 row_mask:0xf bank_mask:0xf bound_ctrl:1
	v_pk_mul_f32 v[48:49], v[48:49], v[62:63] op_sel_hi:[1,0]
	v_add_f32_dpp v34, v34, v34 row_ror:4 row_mask:0xf bank_mask:0xf bound_ctrl:1
	v_pk_fma_f32 v[48:49], v[24:25], v[44:45], v[48:49]
	s_nop 0
	v_add_f32_dpp v34, v34, v34 row_ror:8 row_mask:0xf bank_mask:0xf bound_ctrl:1
	v_pk_fma_f32 v[22:23], v[54:55], v[34:35], v[46:47] op_sel_hi:[1,0,1]
	v_pk_fma_f32 v[24:25], v[56:57], v[34:35], v[48:49] op_sel_hi:[1,0,1]
	s_waitcnt lgkmcnt(3)
	v_pk_mul_f32 v[34:35], v[22:23], v[10:11]
	v_pk_mul_f32 v[66:67], v[22:23], v[58:59]
	v_pk_fma_f32 v[34:35], v[24:25], v[12:13], v[34:35]
	v_pk_fma_f32 v[66:67], v[24:25], v[60:61], v[66:67]
	ds_read_b128 v[50:53], v68 offset:8352
	ds_read_b128 v[46:49], v68 offset:8096
	ds_read_b32 v62, v69 offset:9120
	ds_read_b128 v[42:45], v68 offset:7840
	ds_read_b128 v[54:57], v68 offset:8608
	ds_read_b128 v[58:61], v68 offset:8864
	v_add_f32_e32 v34, v34, v35
	v_add_f32_e32 v66, v66, v67
	v_pk_mul_f32 v[6:7], v[6:7], v[28:29] op_sel_hi:[1,0]
	v_add_f32_dpp v34, v34, v34 row_ror:1 row_mask:0xf bank_mask:0xf bound_ctrl:1
	v_add_f32_dpp v66, v66, v66 row_ror:1 row_mask:0xf bank_mask:0xf bound_ctrl:1
	s_waitcnt lgkmcnt(7)
; template <int CTRL> __device__ __forceinline__ float dpp_f(float x) { return __int_as_float(__builtin_amdgcn_update_dpp(0, __float_as_int(x), CTRL, 0xf, 0xf, false)); }
; __device__ __forceinline__ void p8_scan(const Args& a, LAS unsigned char* lds) {
;     ...
;                 for (int tt = 0; tt < TC; ++tt) {
;                     ScanOps n; scan_ld(n, bt + (tt + 1 < TC ? tt + 1 : tt) * SPITCH, jq4, myrow);
;                     __builtin_amdgcn_sched_barrier(0);
;                     f32x2 ta = S01 * o.al.lo, ty = S01 * o.wr.lo; ta = S23 * o.al.hi + ta; ty = S23 * o.wr.hi + ty;
;                     float pa = ta.x + ta.y, py = ty.x + ty.y;
;                     f32x2 kv01 = o.kv.lo * o.vi, kv23 = o.kv.hi * o.vi;
;     ...
;                     asm volatile("" : "+v"(kv01), "+v"(kv23), "+v"(vc));
;                     pa += dpp_f<0x121>(pa); py += dpp_f<0x121>(py); pa += dpp_f<0x122>(pa); py += dpp_f<0x122>(py);
;                     pa += dpp_f<0x124>(pa); pa += dpp_f<0x128>(pa);
;                     S01 = S01 * o.wv.lo + (o.be.lo * pa + kv01);
;                     S23 = S23 * o.wv.hi + (o.be.hi * pa + kv23);
;     ...
;                     __builtin_amdgcn_sched_barrier(0);
;                     o = n;
	v_pk_fma_f32 v[6:7], v[22:23], v[2:3], v[6:7]
	v_add_f32_dpp v34, v34, v34 row_ror:2 row_mask:0xf bank_mask:0xf bound_ctrl:1
	v_add_f32_dpp v66, v66, v66 row_ror:2 row_mask:0xf bank_mask:0xf bound_ctrl:1
	v_pk_mul_f32 v[8:9], v[8:9], v[28:29] op_sel_hi:[1,0]
	v_add_f32_dpp v34, v34, v34 row_ror:4 row_mask:0xf bank_mask:0xf bound_ctrl:1
	v_pk_fma_f32 v[8:9], v[24:25], v[4:5], v[8:9]
	ds_write2st64_b32 v71, v36, v66 offset0:2 offset1:3
	v_add_f32_dpp v34, v34, v34 row_ror:8 row_mask:0xf bank_mask:0xf bound_ctrl:1
	v_pk_fma_f32 v[22:23], v[14:15], v[34:35], v[6:7] op_sel_hi:[1,0,1]
	v_pk_fma_f32 v[24:25], v[16:17], v[34:35], v[8:9] op_sel_hi:[1,0,1]
	s_waitcnt lgkmcnt(4)
	v_pk_mul_f32 v[34:35], v[22:23], v[50:51]
	v_pk_mul_f32 v[36:37], v[22:23], v[18:19]
	v_pk_fma_f32 v[34:35], v[24:25], v[52:53], v[34:35]
	v_pk_fma_f32 v[36:37], v[24:25], v[20:21], v[36:37]
	ds_read_b128 v[10:13], v68 offset:9920
	ds_read_b128 v[6:9], v68 offset:9664
	ds_read_b32 v28, v69 offset:10688
	ds_read_b128 v[2:5], v68 offset:9408
	ds_read_b128 v[14:17], v68 offset:10176
	ds_read_b128 v[18:21], v68 offset:10432
	v_add_f32_e32 v34, v34, v35
	v_add_f32_e32 v36, v36, v37
	v_pk_mul_f32 v[46:47], v[46:47], v[62:63] op_sel_hi:[1,0]
	v_add_f32_dpp v34, v34, v34 row_ror:1 row_mask:0xf bank_mask:0xf bound_ctrl:1
	v_add_f32_dpp v36, v36, v36 row_ror:1 row_mask:0xf bank_mask:0xf bound_ctrl:1
	s_waitcnt lgkmcnt(8)
	v_pk_fma_f32 v[46:47], v[22:23], v[42:43], v[46:47]
	v_add_f32_dpp v34, v34, v34 row_ror:2 row_mask:0xf bank_mask:0xf bound_ctrl:1
	v_add_f32_dpp v36, v36, v36 row_ror:2 row_mask:0xf bank_mask:0xf bound_ctrl:1
	v_pk_mul_f32 v[48:49], v[48:49], v[62:63] op_sel_hi:[1,0]
	v_add_f32_dpp v34, v34, v34 row_ror:4 row_mask:0xf bank_mask:0xf bound_ctrl:1
	v_pk_fma_f32 v[48:49], v[24:25], v[44:45], v[48:49]
	s_nop 0
	v_add_f32_dpp v34, v34, v34 row_ror:8 row_mask:0xf bank_mask:0xf bound_ctrl:1
	v_pk_fma_f32 v[22:23], v[54:55], v[34:35], v[46:47] op_sel_hi:[1,0,1]
	v_pk_fma_f32 v[24:25], v[56:57], v[34:35], v[48:49] op_sel_hi:[1,0,1]
	s_waitcnt lgkmcnt(3)
	v_pk_mul_f32 v[34:35], v[22:23], v[10:11]
	v_pk_mul_f32 v[66:67], v[22:23], v[58:59]
	v_pk_fma_f32 v[34:35], v[24:25], v[12:13], v[34:35]
	v_pk_fma_f32 v[66:67], v[24:25], v[60:61], v[66:67]
	ds_read_b128 v[50:53], v68 offset:11488
	ds_read_b128 v[46:49], v68 offset:11232
	ds_read_b32 v62, v69 offset:12256
	ds_read_b128 v[42:45], v68 offset:10976
	ds_read_b128 v[54:57], v68 offset:11744
	ds_read_b128 v[58:61], v68 offset:12000
	v_add_f32_e32 v34, v34, v35
	v_add_f32_e32 v66, v66, v67
	v_pk_mul_f32 v[6:7], v[6:7], v[28:29] op_sel_hi:[1,0]
	v_add_f32_dpp v34, v34, v34 row_ror:1 row_mask:0xf bank_mask:0xf bound_ctrl:1
	v_add_f32_dpp v66, v66, v66 row_ror:1 row_mask:0xf bank_mask:0xf bound_ctrl:1
	s_waitcnt lgkmcnt(7)
	v_pk_fma_f32 v[6:7], v[22:23], v[2:3], v[6:7]
	v_add_f32_dpp v34, v34, v34 row_ror:2 row_mask:0xf bank_mask:0xf bound_ctrl:1
	v_add_f32_dpp v66, v66, v66 row_ror:2 row_mask:0xf bank_mask:0xf bound_ctrl:1
	v_pk_mul_f32 v[8:9], v[8:9], v[28:29] op_sel_hi:[1,0]
	v_add_f32_dpp v34, v34, v34 row_ror:4 row_mask:0xf bank_mask:0xf bound_ctrl:1
	v_pk_fma_f32 v[8:9], v[24:25], v[4:5], v[8:9]
	ds_write2st64_b32 v71, v36, v66 offset0:4 offset1:5
	v_add_f32_dpp v34, v34, v34 row_ror:8 row_mask:0xf bank_mask:0xf bound_ctrl:1
	v_pk_fma_f32 v[22:23], v[14:15], v[34:35], v[6:7] op_sel_hi:[1,0,1]
	v_pk_fma_f32 v[24:25], v[16:17], v[34:35], v[8:9] op_sel_hi:[1,0,1]
	s_waitcnt lgkmcnt(4)
	v_pk_mul_f32 v[34:35], v[22:23], v[50:51]
	v_pk_mul_f32 v[36:37], v[22:23], v[18:19]
	v_pk_fma_f32 v[34:35], v[24:25], v[52:53], v[34:35]
	v_pk_fma_f32 v[36:37], v[24:25], v[20:21], v[36:37]
	ds_read_b128 v[10:13], v68 offset:13056
	ds_read_b128 v[6:9], v68 offset:12800
	ds_read_b32 v28, v69 offset:13824
	ds_read_b128 v[2:5], v68 offset:12544
	ds_read_b128 v[14:17], v68 offset:13312
	ds_read_b128 v[18:21], v68 offset:13568
	v_add_f32_e32 v34, v34, v35
	v_add_f32_e32 v36, v36, v37
	v_pk_mul_f32 v[46:47], v[46:47], v[62:63] op_sel_hi:[1,0]
	v_add_f32_dpp v34, v34, v34 row_ror:1 row_mask:0xf bank_mask:0xf bound_ctrl:1
	v_add_f32_dpp v36, v36, v36 row_ror:1 row_mask:0xf bank_mask:0xf bound_ctrl:1
	s_waitcnt lgkmcnt(8)
	v_pk_fma_f32 v[46:47], v[22:23], v[42:43], v[46:47]
	v_add_f32_dpp v34, v34, v34 row_ror:2 row_mask:0xf bank_mask:0xf bound_ctrl:1
	v_add_f32_dpp v36, v36, v36 row_ror:2 row_mask:0xf bank_mask:0xf bound_ctrl:1
	v_pk_mul_f32 v[48:49], v[48:49], v[62:63] op_sel_hi:[1,0]
	v_add_f32_dpp v34, v34, v34 row_ror:4 row_mask:0xf bank_mask:0xf bound_ctrl:1
	v_pk_fma_f32 v[48:49], v[24:25], v[44:45], v[48:49]
	s_nop 0
	v_add_f32_dpp v34, v34, v34 row_ror:8 row_mask:0xf bank_mask:0xf bound_ctrl:1
	v_pk_fma_f32 v[22:23], v[54:55], v[34:35], v[46:47] op_sel_hi:[1,0,1]
	v_pk_fma_f32 v[24:25], v[56:57], v[34:35], v[48:49] op_sel_hi:[1,0,1]
	s_waitcnt lgkmcnt(3)
	v_pk_mul_f32 v[34:35], v[22:23], v[10:11]
	v_pk_mul_f32 v[66:67], v[22:23], v[58:59]
	v_pk_fma_f32 v[34:35], v[24:25], v[12:13], v[34:35]
	v_pk_fma_f32 v[66:67], v[24:25], v[60:61], v[66:67]
	ds_read_b128 v[50:53], v68 offset:14624
	ds_read_b128 v[46:49], v68 offset:14368
	ds_read_b32 v62, v69 offset:15392
	ds_read_b128 v[42:45], v68 offset:14112
	ds_read_b128 v[54:57], v68 offset:14880
	ds_read_b128 v[58:61], v68 offset:15136
	v_add_f32_e32 v34, v34, v35
	v_add_f32_e32 v66, v66, v67
	v_pk_mul_f32 v[6:7], v[6:7], v[28:29] op_sel_hi:[1,0]
	v_add_f32_dpp v34, v34, v34 row_ror:1 row_mask:0xf bank_mask:0xf bound_ctrl:1
	v_add_f32_dpp v66, v66, v66 row_ror:1 row_mask:0xf bank_mask:0xf bound_ctrl:1
	s_waitcnt lgkmcnt(7)
; template <int CTRL> __device__ __forceinline__ float dpp_f(float x) { return __int_as_float(__builtin_amdgcn_update_dpp(0, __float_as_int(x), CTRL, 0xf, 0xf, false)); }
; __device__ __forceinline__ void p8_scan(const Args& a, LAS unsigned char* lds) {
;     ...
;                 for (int tt = 0; tt < TC; ++tt) {
;                     ScanOps n; scan_ld(n, bt + (tt + 1 < TC ? tt + 1 : tt) * SPITCH, jq4, myrow);
;                     __builtin_amdgcn_sched_barrier(0);
;                     f32x2 ta = S01 * o.al.lo, ty = S01 * o.wr.lo; ta = S23 * o.al.hi + ta; ty = S23 * o.wr.hi + ty;
;                     float pa = ta.x + ta.y, py = ty.x + ty.y;
;                     f32x2 kv01 = o.kv.lo * o.vi, kv23 = o.kv.hi * o.vi;
;     ...
;                     asm volatile("" : "+v"(kv01), "+v"(kv23), "+v"(vc));
;                     pa += dpp_f<0x121>(pa); py += dpp_f<0x121>(py); pa += dpp_f<0x122>(pa); py += dpp_f<0x122>(py);
;                     pa += dpp_f<0x124>(pa); pa += dpp_f<0x128>(pa);
;                     S01 = S01 * o.wv.lo + (o.be.lo * pa + kv01);
;                     S23 = S23 * o.wv.hi + (o.be.hi * pa + kv23);
;     ...
;                     __builtin_amdgcn_sched_barrier(0);
;                     o = n;
	v_pk_fma_f32 v[6:7], v[22:23], v[2:3], v[6:7]
	v_add_f32_dpp v34, v34, v34 row_ror:2 row_mask:0xf bank_mask:0xf bound_ctrl:1
	v_add_f32_dpp v66, v66, v66 row_ror:2 row_mask:0xf bank_mask:0xf bound_ctrl:1
	v_pk_mul_f32 v[8:9], v[8:9], v[28:29] op_sel_hi:[1,0]
	v_add_f32_dpp v34, v34, v34 row_ror:4 row_mask:0xf bank_mask:0xf bound_ctrl:1
	v_pk_fma_f32 v[8:9], v[24:25], v[4:5], v[8:9]
	ds_write2st64_b32 v71, v36, v66 offset0:6 offset1:7
	v_add_f32_dpp v34, v34, v34 row_ror:8 row_mask:0xf bank_mask:0xf bound_ctrl:1
	v_pk_fma_f32 v[22:23], v[14:15], v[34:35], v[6:7] op_sel_hi:[1,0,1]
	v_pk_fma_f32 v[24:25], v[16:17], v[34:35], v[8:9] op_sel_hi:[1,0,1]
	s_waitcnt lgkmcnt(4)
	v_pk_mul_f32 v[34:35], v[22:23], v[50:51]
	v_pk_mul_f32 v[36:37], v[22:23], v[18:19]
	v_pk_fma_f32 v[34:35], v[24:25], v[52:53], v[34:35]
	v_pk_fma_f32 v[36:37], v[24:25], v[20:21], v[36:37]
	ds_read_b128 v[10:13], v68 offset:16192
	ds_read_b128 v[6:9], v68 offset:15936
	ds_read_b32 v28, v69 offset:16960
	ds_read_b128 v[2:5], v68 offset:15680
	ds_read_b128 v[14:17], v68 offset:16448
	ds_read_b128 v[18:21], v68 offset:16704
	v_add_f32_e32 v34, v34, v35
	v_add_f32_e32 v36, v36, v37
	v_pk_mul_f32 v[46:47], v[46:47], v[62:63] op_sel_hi:[1,0]
	v_add_f32_dpp v34, v34, v34 row_ror:1 row_mask:0xf bank_mask:0xf bound_ctrl:1
	v_add_f32_dpp v36, v36, v36 row_ror:1 row_mask:0xf bank_mask:0xf bound_ctrl:1
	s_waitcnt lgkmcnt(8)
	v_pk_fma_f32 v[46:47], v[22:23], v[42:43], v[46:47]
	v_add_f32_dpp v34, v34, v34 row_ror:2 row_mask:0xf bank_mask:0xf bound_ctrl:1
	v_add_f32_dpp v36, v36, v36 row_ror:2 row_mask:0xf bank_mask:0xf bound_ctrl:1
	v_pk_mul_f32 v[48:49], v[48:49], v[62:63] op_sel_hi:[1,0]
	v_add_f32_dpp v34, v34, v34 row_ror:4 row_mask:0xf bank_mask:0xf bound_ctrl:1
	v_pk_fma_f32 v[48:49], v[24:25], v[44:45], v[48:49]
	s_nop 0
	v_add_f32_dpp v34, v34, v34 row_ror:8 row_mask:0xf bank_mask:0xf bound_ctrl:1
	v_pk_fma_f32 v[22:23], v[54:55], v[34:35], v[46:47] op_sel_hi:[1,0,1]
	v_pk_fma_f32 v[24:25], v[56:57], v[34:35], v[48:49] op_sel_hi:[1,0,1]
	s_waitcnt lgkmcnt(3)
	v_pk_mul_f32 v[34:35], v[22:23], v[10:11]
	v_pk_mul_f32 v[66:67], v[22:23], v[58:59]
	v_pk_fma_f32 v[34:35], v[24:25], v[12:13], v[34:35]
	v_pk_fma_f32 v[66:67], v[24:25], v[60:61], v[66:67]
	ds_read_b128 v[50:53], v68 offset:17760
	ds_read_b128 v[46:49], v68 offset:17504
	ds_read_b32 v62, v69 offset:18528
	ds_read_b128 v[42:45], v68 offset:17248
	ds_read_b128 v[54:57], v68 offset:18016
	ds_read_b128 v[58:61], v68 offset:18272
	v_add_f32_e32 v34, v34, v35
	v_add_f32_e32 v66, v66, v67
	v_pk_mul_f32 v[6:7], v[6:7], v[28:29] op_sel_hi:[1,0]
	v_add_f32_dpp v34, v34, v34 row_ror:1 row_mask:0xf bank_mask:0xf bound_ctrl:1
	v_add_f32_dpp v66, v66, v66 row_ror:1 row_mask:0xf bank_mask:0xf bound_ctrl:1
	s_waitcnt lgkmcnt(7)
	v_pk_fma_f32 v[6:7], v[22:23], v[2:3], v[6:7]
	v_add_f32_dpp v34, v34, v34 row_ror:2 row_mask:0xf bank_mask:0xf bound_ctrl:1
	v_add_f32_dpp v66, v66, v66 row_ror:2 row_mask:0xf bank_mask:0xf bound_ctrl:1
	v_pk_mul_f32 v[8:9], v[8:9], v[28:29] op_sel_hi:[1,0]
	v_add_f32_dpp v34, v34, v34 row_ror:4 row_mask:0xf bank_mask:0xf bound_ctrl:1
	v_pk_fma_f32 v[8:9], v[24:25], v[4:5], v[8:9]
	ds_write2st64_b32 v71, v36, v66 offset0:8 offset1:9
	v_add_f32_dpp v34, v34, v34 row_ror:8 row_mask:0xf bank_mask:0xf bound_ctrl:1
	v_pk_fma_f32 v[22:23], v[14:15], v[34:35], v[6:7] op_sel_hi:[1,0,1]
	v_pk_fma_f32 v[24:25], v[16:17], v[34:35], v[8:9] op_sel_hi:[1,0,1]
	s_waitcnt lgkmcnt(4)
	v_pk_mul_f32 v[34:35], v[22:23], v[50:51]
	v_pk_mul_f32 v[36:37], v[22:23], v[18:19]
	v_pk_fma_f32 v[34:35], v[24:25], v[52:53], v[34:35]
	v_pk_fma_f32 v[36:37], v[24:25], v[20:21], v[36:37]
	ds_read_b128 v[10:13], v68 offset:19328
	ds_read_b128 v[6:9], v68 offset:19072
	ds_read_b32 v28, v69 offset:20096
	ds_read_b128 v[2:5], v68 offset:18816
	ds_read_b128 v[14:17], v68 offset:19584
	ds_read_b128 v[18:21], v68 offset:19840
	v_add_f32_e32 v34, v34, v35
	v_add_f32_e32 v36, v36, v37
	v_pk_mul_f32 v[46:47], v[46:47], v[62:63] op_sel_hi:[1,0]
	v_add_f32_dpp v34, v34, v34 row_ror:1 row_mask:0xf bank_mask:0xf bound_ctrl:1
	v_add_f32_dpp v36, v36, v36 row_ror:1 row_mask:0xf bank_mask:0xf bound_ctrl:1
	s_waitcnt lgkmcnt(8)
	v_pk_fma_f32 v[46:47], v[22:23], v[42:43], v[46:47]
	v_add_f32_dpp v34, v34, v34 row_ror:2 row_mask:0xf bank_mask:0xf bound_ctrl:1
	v_add_f32_dpp v36, v36, v36 row_ror:2 row_mask:0xf bank_mask:0xf bound_ctrl:1
	v_pk_mul_f32 v[48:49], v[48:49], v[62:63] op_sel_hi:[1,0]
	v_add_f32_dpp v34, v34, v34 row_ror:4 row_mask:0xf bank_mask:0xf bound_ctrl:1
	v_pk_fma_f32 v[48:49], v[24:25], v[44:45], v[48:49]
	s_nop 0
	v_add_f32_dpp v34, v34, v34 row_ror:8 row_mask:0xf bank_mask:0xf bound_ctrl:1
	v_pk_fma_f32 v[22:23], v[54:55], v[34:35], v[46:47] op_sel_hi:[1,0,1]
	v_pk_fma_f32 v[24:25], v[56:57], v[34:35], v[48:49] op_sel_hi:[1,0,1]
	s_waitcnt lgkmcnt(3)
	v_pk_mul_f32 v[34:35], v[22:23], v[10:11]
	v_pk_mul_f32 v[66:67], v[22:23], v[58:59]
	v_pk_fma_f32 v[34:35], v[24:25], v[12:13], v[34:35]
	v_pk_fma_f32 v[66:67], v[24:25], v[60:61], v[66:67]
	ds_read_b128 v[50:53], v68 offset:20896
	ds_read_b128 v[46:49], v68 offset:20640
	ds_read_b32 v62, v69 offset:21664
	ds_read_b128 v[42:45], v68 offset:20384
	ds_read_b128 v[54:57], v68 offset:21152
	ds_read_b128 v[58:61], v68 offset:21408
	v_add_f32_e32 v34, v34, v35
	v_add_f32_e32 v66, v66, v67
	v_pk_mul_f32 v[6:7], v[6:7], v[28:29] op_sel_hi:[1,0]
	v_add_f32_dpp v34, v34, v34 row_ror:1 row_mask:0xf bank_mask:0xf bound_ctrl:1
	v_add_f32_dpp v66, v66, v66 row_ror:1 row_mask:0xf bank_mask:0xf bound_ctrl:1
	s_waitcnt lgkmcnt(7)
; template <int CTRL> __device__ __forceinline__ float dpp_f(float x) { return __int_as_float(__builtin_amdgcn_update_dpp(0, __float_as_int(x), CTRL, 0xf, 0xf, false)); }
; __device__ __forceinline__ void p8_scan(const Args& a, LAS unsigned char* lds) {
;     ...
;                 for (int tt = 0; tt < TC; ++tt) {
;                     ScanOps n; scan_ld(n, bt + (tt + 1 < TC ? tt + 1 : tt) * SPITCH, jq4, myrow);
;                     __builtin_amdgcn_sched_barrier(0);
;                     f32x2 ta = S01 * o.al.lo, ty = S01 * o.wr.lo; ta = S23 * o.al.hi + ta; ty = S23 * o.wr.hi + ty;
;                     float pa = ta.x + ta.y, py = ty.x + ty.y;
;                     f32x2 kv01 = o.kv.lo * o.vi, kv23 = o.kv.hi * o.vi;
;     ...
;                     asm volatile("" : "+v"(kv01), "+v"(kv23), "+v"(vc));
;                     pa += dpp_f<0x121>(pa); py += dpp_f<0x121>(py); pa += dpp_f<0x122>(pa); py += dpp_f<0x122>(py);
;                     pa += dpp_f<0x124>(pa); pa += dpp_f<0x128>(pa);
;                     S01 = S01 * o.wv.lo + (o.be.lo * pa + kv01);
;                     S23 = S23 * o.wv.hi + (o.be.hi * pa + kv23);
;     ...
;                     __builtin_amdgcn_sched_barrier(0);
;                     o = n;
	v_pk_fma_f32 v[6:7], v[22:23], v[2:3], v[6:7]
	v_add_f32_dpp v34, v34, v34 row_ror:2 row_mask:0xf bank_mask:0xf bound_ctrl:1
	v_add_f32_dpp v66, v66, v66 row_ror:2 row_mask:0xf bank_mask:0xf bound_ctrl:1
	v_pk_mul_f32 v[8:9], v[8:9], v[28:29] op_sel_hi:[1,0]
	v_add_f32_dpp v34, v34, v34 row_ror:4 row_mask:0xf bank_mask:0xf bound_ctrl:1
	v_pk_fma_f32 v[8:9], v[24:25], v[4:5], v[8:9]
	ds_write2st64_b32 v71, v36, v66 offset0:10 offset1:11
	v_add_f32_dpp v34, v34, v34 row_ror:8 row_mask:0xf bank_mask:0xf bound_ctrl:1
	v_pk_fma_f32 v[22:23], v[14:15], v[34:35], v[6:7] op_sel_hi:[1,0,1]
	v_pk_fma_f32 v[24:25], v[16:17], v[34:35], v[8:9] op_sel_hi:[1,0,1]
	s_waitcnt lgkmcnt(4)
	v_pk_mul_f32 v[34:35], v[22:23], v[50:51]
	v_pk_mul_f32 v[36:37], v[22:23], v[18:19]
	v_pk_fma_f32 v[34:35], v[24:25], v[52:53], v[34:35]
	v_pk_fma_f32 v[36:37], v[24:25], v[20:21], v[36:37]
	ds_read_b128 v[10:13], v68 offset:22464
	ds_read_b128 v[6:9], v68 offset:22208
	ds_read_b32 v28, v69 offset:23232
	ds_read_b128 v[2:5], v68 offset:21952
	ds_read_b128 v[14:17], v68 offset:22720
	ds_read_b128 v[18:21], v68 offset:22976
	v_add_f32_e32 v34, v34, v35
	v_add_f32_e32 v36, v36, v37
	v_pk_mul_f32 v[46:47], v[46:47], v[62:63] op_sel_hi:[1,0]
	v_add_f32_dpp v34, v34, v34 row_ror:1 row_mask:0xf bank_mask:0xf bound_ctrl:1
	v_add_f32_dpp v36, v36, v36 row_ror:1 row_mask:0xf bank_mask:0xf bound_ctrl:1
	s_waitcnt lgkmcnt(8)
	v_pk_fma_f32 v[46:47], v[22:23], v[42:43], v[46:47]
	v_add_f32_dpp v34, v34, v34 row_ror:2 row_mask:0xf bank_mask:0xf bound_ctrl:1
	v_add_f32_dpp v36, v36, v36 row_ror:2 row_mask:0xf bank_mask:0xf bound_ctrl:1
	v_pk_mul_f32 v[48:49], v[48:49], v[62:63] op_sel_hi:[1,0]
	v_add_f32_dpp v34, v34, v34 row_ror:4 row_mask:0xf bank_mask:0xf bound_ctrl:1
	v_pk_fma_f32 v[48:49], v[24:25], v[44:45], v[48:49]
	s_nop 0
	v_add_f32_dpp v34, v34, v34 row_ror:8 row_mask:0xf bank_mask:0xf bound_ctrl:1
	v_pk_fma_f32 v[22:23], v[54:55], v[34:35], v[46:47] op_sel_hi:[1,0,1]
	v_pk_fma_f32 v[24:25], v[56:57], v[34:35], v[48:49] op_sel_hi:[1,0,1]
	s_waitcnt lgkmcnt(3)
	v_pk_mul_f32 v[34:35], v[22:23], v[10:11]
	v_pk_mul_f32 v[66:67], v[22:23], v[58:59]
	v_pk_fma_f32 v[34:35], v[24:25], v[12:13], v[34:35]
	v_pk_fma_f32 v[66:67], v[24:25], v[60:61], v[66:67]
	ds_read_b128 v[50:53], v68 offset:24032
	ds_read_b128 v[46:49], v68 offset:23776
	ds_read_b32 v62, v69 offset:24800
	ds_read_b128 v[42:45], v68 offset:23520
	ds_read_b128 v[54:57], v68 offset:24288
	ds_read_b128 v[58:61], v68 offset:24544
	v_add_f32_e32 v34, v34, v35
	v_add_f32_e32 v66, v66, v67
	v_pk_mul_f32 v[6:7], v[6:7], v[28:29] op_sel_hi:[1,0]
	v_add_f32_dpp v34, v34, v34 row_ror:1 row_mask:0xf bank_mask:0xf bound_ctrl:1
	v_add_f32_dpp v66, v66, v66 row_ror:1 row_mask:0xf bank_mask:0xf bound_ctrl:1
	s_waitcnt lgkmcnt(7)
	v_pk_fma_f32 v[6:7], v[22:23], v[2:3], v[6:7]
	v_add_f32_dpp v34, v34, v34 row_ror:2 row_mask:0xf bank_mask:0xf bound_ctrl:1
	v_add_f32_dpp v66, v66, v66 row_ror:2 row_mask:0xf bank_mask:0xf bound_ctrl:1
	v_pk_mul_f32 v[8:9], v[8:9], v[28:29] op_sel_hi:[1,0]
	v_add_f32_dpp v34, v34, v34 row_ror:4 row_mask:0xf bank_mask:0xf bound_ctrl:1
	v_pk_fma_f32 v[8:9], v[24:25], v[4:5], v[8:9]
	ds_write2st64_b32 v71, v36, v66 offset0:12 offset1:13
	v_add_f32_dpp v34, v34, v34 row_ror:8 row_mask:0xf bank_mask:0xf bound_ctrl:1
	v_pk_fma_f32 v[22:23], v[14:15], v[34:35], v[6:7] op_sel_hi:[1,0,1]
	v_pk_fma_f32 v[24:25], v[16:17], v[34:35], v[8:9] op_sel_hi:[1,0,1]
	s_waitcnt lgkmcnt(4)
	v_pk_mul_f32 v[34:35], v[22:23], v[50:51]
	v_pk_mul_f32 v[36:37], v[22:23], v[18:19]
	v_pk_fma_f32 v[34:35], v[24:25], v[52:53], v[34:35]
	v_pk_fma_f32 v[36:37], v[24:25], v[20:21], v[36:37]
	ds_read_b128 v[10:13], v68 offset:25600
	ds_read_b128 v[6:9], v68 offset:25344
	ds_read_b32 v28, v69 offset:26368
	ds_read_b128 v[2:5], v68 offset:25088
	ds_read_b128 v[14:17], v68 offset:25856
	ds_read_b128 v[18:21], v68 offset:26112
	v_add_f32_e32 v34, v34, v35
	v_add_f32_e32 v36, v36, v37
	v_pk_mul_f32 v[46:47], v[46:47], v[62:63] op_sel_hi:[1,0]
	v_add_f32_dpp v34, v34, v34 row_ror:1 row_mask:0xf bank_mask:0xf bound_ctrl:1
	v_add_f32_dpp v36, v36, v36 row_ror:1 row_mask:0xf bank_mask:0xf bound_ctrl:1
	s_waitcnt lgkmcnt(8)
	v_pk_fma_f32 v[46:47], v[22:23], v[42:43], v[46:47]
	v_add_f32_dpp v34, v34, v34 row_ror:2 row_mask:0xf bank_mask:0xf bound_ctrl:1
	v_add_f32_dpp v36, v36, v36 row_ror:2 row_mask:0xf bank_mask:0xf bound_ctrl:1
	v_pk_mul_f32 v[48:49], v[48:49], v[62:63] op_sel_hi:[1,0]
	v_add_f32_dpp v34, v34, v34 row_ror:4 row_mask:0xf bank_mask:0xf bound_ctrl:1
	v_pk_fma_f32 v[48:49], v[24:25], v[44:45], v[48:49]
	s_nop 0
	v_add_f32_dpp v34, v34, v34 row_ror:8 row_mask:0xf bank_mask:0xf bound_ctrl:1
	v_pk_fma_f32 v[22:23], v[54:55], v[34:35], v[46:47] op_sel_hi:[1,0,1]
	v_pk_fma_f32 v[24:25], v[56:57], v[34:35], v[48:49] op_sel_hi:[1,0,1]
	s_waitcnt lgkmcnt(3)
	v_pk_mul_f32 v[34:35], v[22:23], v[10:11]
	v_pk_mul_f32 v[66:67], v[22:23], v[58:59]
	v_pk_fma_f32 v[34:35], v[24:25], v[12:13], v[34:35]
	v_pk_fma_f32 v[66:67], v[24:25], v[60:61], v[66:67]
	ds_read_b128 v[50:53], v68 offset:27168
	ds_read_b128 v[46:49], v68 offset:26912
	ds_read_b32 v62, v69 offset:27936
	ds_read_b128 v[42:45], v68 offset:26656
	ds_read_b128 v[54:57], v68 offset:27424
	ds_read_b128 v[58:61], v68 offset:27680
	v_add_f32_e32 v34, v34, v35
	v_add_f32_e32 v66, v66, v67
	v_pk_mul_f32 v[6:7], v[6:7], v[28:29] op_sel_hi:[1,0]
	v_add_f32_dpp v34, v34, v34 row_ror:1 row_mask:0xf bank_mask:0xf bound_ctrl:1
	v_add_f32_dpp v66, v66, v66 row_ror:1 row_mask:0xf bank_mask:0xf bound_ctrl:1
	s_waitcnt lgkmcnt(7)
; template <int CTRL> __device__ __forceinline__ float dpp_f(float x) { return __int_as_float(__builtin_amdgcn_update_dpp(0, __float_as_int(x), CTRL, 0xf, 0xf, false)); }
; __device__ __forceinline__ void p8_scan(const Args& a, LAS unsigned char* lds) {
;     ...
;                 for (int tt = 0; tt < TC; ++tt) {
;                     ScanOps n; scan_ld(n, bt + (tt + 1 < TC ? tt + 1 : tt) * SPITCH, jq4, myrow);
;                     __builtin_amdgcn_sched_barrier(0);
;                     f32x2 ta = S01 * o.al.lo, ty = S01 * o.wr.lo; ta = S23 * o.al.hi + ta; ty = S23 * o.wr.hi + ty;
;                     float pa = ta.x + ta.y, py = ty.x + ty.y;
;                     f32x2 kv01 = o.kv.lo * o.vi, kv23 = o.kv.hi * o.vi;
;     ...
;                     asm volatile("" : "+v"(kv01), "+v"(kv23), "+v"(vc));
;                     pa += dpp_f<0x121>(pa); py += dpp_f<0x121>(py); pa += dpp_f<0x122>(pa); py += dpp_f<0x122>(py);
;                     pa += dpp_f<0x124>(pa); pa += dpp_f<0x128>(pa);
;                     S01 = S01 * o.wv.lo + (o.be.lo * pa + kv01);
;                     S23 = S23 * o.wv.hi + (o.be.hi * pa + kv23);
;     ...
;                     __builtin_amdgcn_sched_barrier(0);
;                     o = n;
	v_pk_fma_f32 v[6:7], v[22:23], v[2:3], v[6:7]
	v_add_f32_dpp v34, v34, v34 row_ror:2 row_mask:0xf bank_mask:0xf bound_ctrl:1
	v_add_f32_dpp v66, v66, v66 row_ror:2 row_mask:0xf bank_mask:0xf bound_ctrl:1
	v_pk_mul_f32 v[8:9], v[8:9], v[28:29] op_sel_hi:[1,0]
	v_add_f32_dpp v34, v34, v34 row_ror:4 row_mask:0xf bank_mask:0xf bound_ctrl:1
	v_pk_fma_f32 v[8:9], v[24:25], v[4:5], v[8:9]
	ds_write2st64_b32 v71, v36, v66 offset0:14 offset1:15
	v_add_f32_dpp v34, v34, v34 row_ror:8 row_mask:0xf bank_mask:0xf bound_ctrl:1
	v_pk_fma_f32 v[22:23], v[14:15], v[34:35], v[6:7] op_sel_hi:[1,0,1]
	v_pk_fma_f32 v[24:25], v[16:17], v[34:35], v[8:9] op_sel_hi:[1,0,1]
	s_waitcnt lgkmcnt(4)
	v_pk_mul_f32 v[34:35], v[22:23], v[50:51]
	v_pk_mul_f32 v[36:37], v[22:23], v[18:19]
	v_pk_fma_f32 v[34:35], v[24:25], v[52:53], v[34:35]
	v_pk_fma_f32 v[36:37], v[24:25], v[20:21], v[36:37]
	ds_read_b128 v[10:13], v68 offset:28736
	ds_read_b128 v[6:9], v68 offset:28480
	ds_read_b32 v28, v69 offset:29504
	ds_read_b128 v[2:5], v68 offset:28224
	ds_read_b128 v[14:17], v68 offset:28992
	ds_read_b128 v[18:21], v68 offset:29248
	v_add_f32_e32 v34, v34, v35
	v_add_f32_e32 v36, v36, v37
	v_pk_mul_f32 v[46:47], v[46:47], v[62:63] op_sel_hi:[1,0]
	v_add_f32_dpp v34, v34, v34 row_ror:1 row_mask:0xf bank_mask:0xf bound_ctrl:1
	v_add_f32_dpp v36, v36, v36 row_ror:1 row_mask:0xf bank_mask:0xf bound_ctrl:1
	s_waitcnt lgkmcnt(8)
	v_pk_fma_f32 v[46:47], v[22:23], v[42:43], v[46:47]
	v_add_f32_dpp v34, v34, v34 row_ror:2 row_mask:0xf bank_mask:0xf bound_ctrl:1
	v_add_f32_dpp v36, v36, v36 row_ror:2 row_mask:0xf bank_mask:0xf bound_ctrl:1
	v_pk_mul_f32 v[48:49], v[48:49], v[62:63] op_sel_hi:[1,0]
	v_add_f32_dpp v34, v34, v34 row_ror:4 row_mask:0xf bank_mask:0xf bound_ctrl:1
	v_pk_fma_f32 v[48:49], v[24:25], v[44:45], v[48:49]
	s_nop 0
	v_add_f32_dpp v34, v34, v34 row_ror:8 row_mask:0xf bank_mask:0xf bound_ctrl:1
	v_pk_fma_f32 v[22:23], v[54:55], v[34:35], v[46:47] op_sel_hi:[1,0,1]
	v_pk_fma_f32 v[24:25], v[56:57], v[34:35], v[48:49] op_sel_hi:[1,0,1]
	s_waitcnt lgkmcnt(3)
	v_pk_mul_f32 v[34:35], v[22:23], v[10:11]
	v_pk_mul_f32 v[66:67], v[22:23], v[58:59]
	v_pk_fma_f32 v[34:35], v[24:25], v[12:13], v[34:35]
	v_pk_fma_f32 v[66:67], v[24:25], v[60:61], v[66:67]
	ds_read_b128 v[50:53], v68 offset:30304
	ds_read_b128 v[46:49], v68 offset:30048
	ds_read_b32 v62, v69 offset:31072
	ds_read_b128 v[42:45], v68 offset:29792
	ds_read_b128 v[54:57], v68 offset:30560
	ds_read_b128 v[58:61], v68 offset:30816
	v_add_f32_e32 v34, v34, v35
	v_add_f32_e32 v66, v66, v67
	v_pk_mul_f32 v[6:7], v[6:7], v[28:29] op_sel_hi:[1,0]
	v_add_f32_dpp v34, v34, v34 row_ror:1 row_mask:0xf bank_mask:0xf bound_ctrl:1
	v_add_f32_dpp v66, v66, v66 row_ror:1 row_mask:0xf bank_mask:0xf bound_ctrl:1
	s_waitcnt lgkmcnt(7)
	v_pk_fma_f32 v[6:7], v[22:23], v[2:3], v[6:7]
	v_add_f32_dpp v34, v34, v34 row_ror:2 row_mask:0xf bank_mask:0xf bound_ctrl:1
	v_add_f32_dpp v66, v66, v66 row_ror:2 row_mask:0xf bank_mask:0xf bound_ctrl:1
	v_pk_mul_f32 v[8:9], v[8:9], v[28:29] op_sel_hi:[1,0]
	v_add_f32_dpp v34, v34, v34 row_ror:4 row_mask:0xf bank_mask:0xf bound_ctrl:1
	v_pk_fma_f32 v[8:9], v[24:25], v[4:5], v[8:9]
	ds_write2st64_b32 v71, v36, v66 offset0:16 offset1:17
	v_add_f32_dpp v34, v34, v34 row_ror:8 row_mask:0xf bank_mask:0xf bound_ctrl:1
	v_pk_fma_f32 v[22:23], v[14:15], v[34:35], v[6:7] op_sel_hi:[1,0,1]
	v_pk_fma_f32 v[24:25], v[16:17], v[34:35], v[8:9] op_sel_hi:[1,0,1]
	s_waitcnt lgkmcnt(4)
	v_pk_mul_f32 v[34:35], v[22:23], v[50:51]
	v_pk_mul_f32 v[36:37], v[22:23], v[18:19]
	v_pk_fma_f32 v[34:35], v[24:25], v[52:53], v[34:35]
	v_pk_fma_f32 v[36:37], v[24:25], v[20:21], v[36:37]
	ds_read_b128 v[10:13], v68 offset:31872
	ds_read_b128 v[6:9], v68 offset:31616
	ds_read_b32 v28, v69 offset:32640
	ds_read_b128 v[2:5], v68 offset:31360
	ds_read_b128 v[14:17], v68 offset:32128
	ds_read_b128 v[18:21], v68 offset:32384
	v_add_f32_e32 v34, v34, v35
	v_add_f32_e32 v36, v36, v37
	v_pk_mul_f32 v[46:47], v[46:47], v[62:63] op_sel_hi:[1,0]
	v_add_f32_dpp v34, v34, v34 row_ror:1 row_mask:0xf bank_mask:0xf bound_ctrl:1
	v_add_f32_dpp v36, v36, v36 row_ror:1 row_mask:0xf bank_mask:0xf bound_ctrl:1
	s_waitcnt lgkmcnt(8)
	v_pk_fma_f32 v[46:47], v[22:23], v[42:43], v[46:47]
	v_add_f32_dpp v34, v34, v34 row_ror:2 row_mask:0xf bank_mask:0xf bound_ctrl:1
	v_add_f32_dpp v36, v36, v36 row_ror:2 row_mask:0xf bank_mask:0xf bound_ctrl:1
	v_pk_mul_f32 v[48:49], v[48:49], v[62:63] op_sel_hi:[1,0]
	v_add_f32_dpp v34, v34, v34 row_ror:4 row_mask:0xf bank_mask:0xf bound_ctrl:1
	v_pk_fma_f32 v[48:49], v[24:25], v[44:45], v[48:49]
	s_nop 0
	v_add_f32_dpp v34, v34, v34 row_ror:8 row_mask:0xf bank_mask:0xf bound_ctrl:1
	v_pk_fma_f32 v[22:23], v[54:55], v[34:35], v[46:47] op_sel_hi:[1,0,1]
	v_pk_fma_f32 v[24:25], v[56:57], v[34:35], v[48:49] op_sel_hi:[1,0,1]
	s_waitcnt lgkmcnt(3)
	v_pk_mul_f32 v[34:35], v[22:23], v[10:11]
	v_pk_mul_f32 v[66:67], v[22:23], v[58:59]
	v_pk_fma_f32 v[34:35], v[24:25], v[12:13], v[34:35]
	v_pk_fma_f32 v[66:67], v[24:25], v[60:61], v[66:67]
	ds_read_b128 v[50:53], v68 offset:33440
	ds_read_b128 v[46:49], v68 offset:33184
	ds_read_b32 v62, v69 offset:34208
	ds_read_b128 v[42:45], v68 offset:32928
	ds_read_b128 v[54:57], v68 offset:33696
	ds_read_b128 v[58:61], v68 offset:33952
	v_add_f32_e32 v34, v34, v35
	v_add_f32_e32 v66, v66, v67
	v_pk_mul_f32 v[6:7], v[6:7], v[28:29] op_sel_hi:[1,0]
	v_add_f32_dpp v34, v34, v34 row_ror:1 row_mask:0xf bank_mask:0xf bound_ctrl:1
	v_add_f32_dpp v66, v66, v66 row_ror:1 row_mask:0xf bank_mask:0xf bound_ctrl:1
	s_waitcnt lgkmcnt(7)
; template <int CTRL> __device__ __forceinline__ float dpp_f(float x) { return __int_as_float(__builtin_amdgcn_update_dpp(0, __float_as_int(x), CTRL, 0xf, 0xf, false)); }
; __device__ __forceinline__ void p8_scan(const Args& a, LAS unsigned char* lds) {
;     ...
;                 for (int tt = 0; tt < TC; ++tt) {
;                     ScanOps n; scan_ld(n, bt + (tt + 1 < TC ? tt + 1 : tt) * SPITCH, jq4, myrow);
;                     __builtin_amdgcn_sched_barrier(0);
;                     f32x2 ta = S01 * o.al.lo, ty = S01 * o.wr.lo; ta = S23 * o.al.hi + ta; ty = S23 * o.wr.hi + ty;
;                     float pa = ta.x + ta.y, py = ty.x + ty.y;
;                     f32x2 kv01 = o.kv.lo * o.vi, kv23 = o.kv.hi * o.vi;
;     ...
;                     asm volatile("" : "+v"(kv01), "+v"(kv23), "+v"(vc));
;                     pa += dpp_f<0x121>(pa); py += dpp_f<0x121>(py); pa += dpp_f<0x122>(pa); py += dpp_f<0x122>(py);
;                     pa += dpp_f<0x124>(pa); pa += dpp_f<0x128>(pa);
;                     S01 = S01 * o.wv.lo + (o.be.lo * pa + kv01);
;                     S23 = S23 * o.wv.hi + (o.be.hi * pa + kv23);
;     ...
;                     __builtin_amdgcn_sched_barrier(0);
;                     o = n;
	v_pk_fma_f32 v[6:7], v[22:23], v[2:3], v[6:7]
	v_add_f32_dpp v34, v34, v34 row_ror:2 row_mask:0xf bank_mask:0xf bound_ctrl:1
	v_add_f32_dpp v66, v66, v66 row_ror:2 row_mask:0xf bank_mask:0xf bound_ctrl:1
	v_pk_mul_f32 v[8:9], v[8:9], v[28:29] op_sel_hi:[1,0]
	v_add_f32_dpp v34, v34, v34 row_ror:4 row_mask:0xf bank_mask:0xf bound_ctrl:1
	v_pk_fma_f32 v[8:9], v[24:25], v[4:5], v[8:9]
	ds_write2st64_b32 v71, v36, v66 offset0:18 offset1:19
	v_add_f32_dpp v34, v34, v34 row_ror:8 row_mask:0xf bank_mask:0xf bound_ctrl:1
	v_pk_fma_f32 v[22:23], v[14:15], v[34:35], v[6:7] op_sel_hi:[1,0,1]
	v_pk_fma_f32 v[24:25], v[16:17], v[34:35], v[8:9] op_sel_hi:[1,0,1]
	s_waitcnt lgkmcnt(4)
	v_pk_mul_f32 v[34:35], v[22:23], v[50:51]
	v_pk_mul_f32 v[36:37], v[22:23], v[18:19]
	v_pk_fma_f32 v[34:35], v[24:25], v[52:53], v[34:35]
	v_pk_fma_f32 v[36:37], v[24:25], v[20:21], v[36:37]
	ds_read_b128 v[10:13], v68 offset:35008
	ds_read_b128 v[6:9], v68 offset:34752
	ds_read_b32 v28, v69 offset:35776
	ds_read_b128 v[2:5], v68 offset:34496
	ds_read_b128 v[14:17], v68 offset:35264
	ds_read_b128 v[18:21], v68 offset:35520
	v_add_f32_e32 v34, v34, v35
	v_add_f32_e32 v36, v36, v37
	v_pk_mul_f32 v[46:47], v[46:47], v[62:63] op_sel_hi:[1,0]
	v_add_f32_dpp v34, v34, v34 row_ror:1 row_mask:0xf bank_mask:0xf bound_ctrl:1
	v_add_f32_dpp v36, v36, v36 row_ror:1 row_mask:0xf bank_mask:0xf bound_ctrl:1
	s_waitcnt lgkmcnt(8)
	v_pk_fma_f32 v[46:47], v[22:23], v[42:43], v[46:47]
	v_add_f32_dpp v34, v34, v34 row_ror:2 row_mask:0xf bank_mask:0xf bound_ctrl:1
	v_add_f32_dpp v36, v36, v36 row_ror:2 row_mask:0xf bank_mask:0xf bound_ctrl:1
	v_pk_mul_f32 v[48:49], v[48:49], v[62:63] op_sel_hi:[1,0]
	v_add_f32_dpp v34, v34, v34 row_ror:4 row_mask:0xf bank_mask:0xf bound_ctrl:1
	v_pk_fma_f32 v[48:49], v[24:25], v[44:45], v[48:49]
	s_nop 0
	v_add_f32_dpp v34, v34, v34 row_ror:8 row_mask:0xf bank_mask:0xf bound_ctrl:1
	v_pk_fma_f32 v[22:23], v[54:55], v[34:35], v[46:47] op_sel_hi:[1,0,1]
	v_pk_fma_f32 v[24:25], v[56:57], v[34:35], v[48:49] op_sel_hi:[1,0,1]
	s_waitcnt lgkmcnt(3)
	v_pk_mul_f32 v[34:35], v[22:23], v[10:11]
	v_pk_mul_f32 v[66:67], v[22:23], v[58:59]
	v_pk_fma_f32 v[34:35], v[24:25], v[12:13], v[34:35]
	v_pk_fma_f32 v[66:67], v[24:25], v[60:61], v[66:67]
	ds_read_b128 v[50:53], v68 offset:36576
	ds_read_b128 v[46:49], v68 offset:36320
	ds_read_b32 v62, v69 offset:37344
	ds_read_b128 v[42:45], v68 offset:36064
	ds_read_b128 v[54:57], v68 offset:36832
	ds_read_b128 v[58:61], v68 offset:37088
	v_add_f32_e32 v34, v34, v35
	v_add_f32_e32 v66, v66, v67
	v_pk_mul_f32 v[6:7], v[6:7], v[28:29] op_sel_hi:[1,0]
	v_add_f32_dpp v34, v34, v34 row_ror:1 row_mask:0xf bank_mask:0xf bound_ctrl:1
	v_add_f32_dpp v66, v66, v66 row_ror:1 row_mask:0xf bank_mask:0xf bound_ctrl:1
	s_waitcnt lgkmcnt(7)
	v_pk_fma_f32 v[6:7], v[22:23], v[2:3], v[6:7]
	v_add_f32_dpp v34, v34, v34 row_ror:2 row_mask:0xf bank_mask:0xf bound_ctrl:1
	v_add_f32_dpp v66, v66, v66 row_ror:2 row_mask:0xf bank_mask:0xf bound_ctrl:1
	v_pk_mul_f32 v[8:9], v[8:9], v[28:29] op_sel_hi:[1,0]
	v_add_f32_dpp v34, v34, v34 row_ror:4 row_mask:0xf bank_mask:0xf bound_ctrl:1
	v_pk_fma_f32 v[8:9], v[24:25], v[4:5], v[8:9]
	ds_write2st64_b32 v71, v36, v66 offset0:20 offset1:21
	v_add_f32_dpp v34, v34, v34 row_ror:8 row_mask:0xf bank_mask:0xf bound_ctrl:1
	v_pk_fma_f32 v[22:23], v[14:15], v[34:35], v[6:7] op_sel_hi:[1,0,1]
	v_pk_fma_f32 v[24:25], v[16:17], v[34:35], v[8:9] op_sel_hi:[1,0,1]
	s_waitcnt lgkmcnt(4)
	v_pk_mul_f32 v[34:35], v[22:23], v[50:51]
	v_pk_mul_f32 v[36:37], v[22:23], v[18:19]
	v_pk_fma_f32 v[34:35], v[24:25], v[52:53], v[34:35]
	v_pk_fma_f32 v[36:37], v[24:25], v[20:21], v[36:37]
	ds_read_b128 v[10:13], v68 offset:38144
	ds_read_b128 v[6:9], v68 offset:37888
	ds_read_b32 v28, v69 offset:38912
	ds_read_b128 v[2:5], v68 offset:37632
	ds_read_b128 v[14:17], v68 offset:38400
	ds_read_b128 v[18:21], v68 offset:38656
	v_add_f32_e32 v34, v34, v35
	v_add_f32_e32 v36, v36, v37
	v_pk_mul_f32 v[46:47], v[46:47], v[62:63] op_sel_hi:[1,0]
	v_add_f32_dpp v34, v34, v34 row_ror:1 row_mask:0xf bank_mask:0xf bound_ctrl:1
	v_add_f32_dpp v36, v36, v36 row_ror:1 row_mask:0xf bank_mask:0xf bound_ctrl:1
	s_waitcnt lgkmcnt(8)
	v_pk_fma_f32 v[46:47], v[22:23], v[42:43], v[46:47]
	v_add_f32_dpp v34, v34, v34 row_ror:2 row_mask:0xf bank_mask:0xf bound_ctrl:1
	v_add_f32_dpp v36, v36, v36 row_ror:2 row_mask:0xf bank_mask:0xf bound_ctrl:1
	v_pk_mul_f32 v[48:49], v[48:49], v[62:63] op_sel_hi:[1,0]
	v_add_f32_dpp v34, v34, v34 row_ror:4 row_mask:0xf bank_mask:0xf bound_ctrl:1
	v_pk_fma_f32 v[48:49], v[24:25], v[44:45], v[48:49]
	s_nop 0
	v_add_f32_dpp v34, v34, v34 row_ror:8 row_mask:0xf bank_mask:0xf bound_ctrl:1
	v_pk_fma_f32 v[22:23], v[54:55], v[34:35], v[46:47] op_sel_hi:[1,0,1]
	v_pk_fma_f32 v[24:25], v[56:57], v[34:35], v[48:49] op_sel_hi:[1,0,1]
	s_waitcnt lgkmcnt(3)
	v_pk_mul_f32 v[34:35], v[22:23], v[10:11]
	v_pk_mul_f32 v[66:67], v[22:23], v[58:59]
	v_pk_fma_f32 v[34:35], v[24:25], v[12:13], v[34:35]
	v_pk_fma_f32 v[66:67], v[24:25], v[60:61], v[66:67]
	ds_read_b128 v[50:53], v68 offset:39712
	ds_read_b128 v[46:49], v68 offset:39456
	ds_read_b32 v62, v69 offset:40480
	ds_read_b128 v[42:45], v68 offset:39200
	ds_read_b128 v[54:57], v68 offset:39968
	ds_read_b128 v[58:61], v68 offset:40224
	v_add_f32_e32 v34, v34, v35
	v_add_f32_e32 v66, v66, v67
	v_pk_mul_f32 v[6:7], v[6:7], v[28:29] op_sel_hi:[1,0]
	v_add_f32_dpp v34, v34, v34 row_ror:1 row_mask:0xf bank_mask:0xf bound_ctrl:1
	v_add_f32_dpp v66, v66, v66 row_ror:1 row_mask:0xf bank_mask:0xf bound_ctrl:1
	s_waitcnt lgkmcnt(7)
; template <int CTRL> __device__ __forceinline__ float dpp_f(float x) { return __int_as_float(__builtin_amdgcn_update_dpp(0, __float_as_int(x), CTRL, 0xf, 0xf, false)); }
; __device__ __forceinline__ void p8_scan(const Args& a, LAS unsigned char* lds) {
;     ...
;                 for (int tt = 0; tt < TC; ++tt) {
;                     ScanOps n; scan_ld(n, bt + (tt + 1 < TC ? tt + 1 : tt) * SPITCH, jq4, myrow);
;                     __builtin_amdgcn_sched_barrier(0);
;                     f32x2 ta = S01 * o.al.lo, ty = S01 * o.wr.lo; ta = S23 * o.al.hi + ta; ty = S23 * o.wr.hi + ty;
;                     float pa = ta.x + ta.y, py = ty.x + ty.y;
;                     f32x2 kv01 = o.kv.lo * o.vi, kv23 = o.kv.hi * o.vi;
;     ...
;                     asm volatile("" : "+v"(kv01), "+v"(kv23), "+v"(vc));
;                     pa += dpp_f<0x121>(pa); py += dpp_f<0x121>(py); pa += dpp_f<0x122>(pa); py += dpp_f<0x122>(py);
;                     pa += dpp_f<0x124>(pa); pa += dpp_f<0x128>(pa);
;                     S01 = S01 * o.wv.lo + (o.be.lo * pa + kv01);
;                     S23 = S23 * o.wv.hi + (o.be.hi * pa + kv23);
;     ...
;                     __builtin_amdgcn_sched_barrier(0);
;                     o = n;
	v_pk_fma_f32 v[6:7], v[22:23], v[2:3], v[6:7]
	v_add_f32_dpp v34, v34, v34 row_ror:2 row_mask:0xf bank_mask:0xf bound_ctrl:1
	v_add_f32_dpp v66, v66, v66 row_ror:2 row_mask:0xf bank_mask:0xf bound_ctrl:1
	v_pk_mul_f32 v[8:9], v[8:9], v[28:29] op_sel_hi:[1,0]
	v_add_f32_dpp v34, v34, v34 row_ror:4 row_mask:0xf bank_mask:0xf bound_ctrl:1
	v_pk_fma_f32 v[8:9], v[24:25], v[4:5], v[8:9]
	ds_write2st64_b32 v71, v36, v66 offset0:22 offset1:23
	v_add_f32_dpp v34, v34, v34 row_ror:8 row_mask:0xf bank_mask:0xf bound_ctrl:1
	v_pk_fma_f32 v[22:23], v[14:15], v[34:35], v[6:7] op_sel_hi:[1,0,1]
	v_pk_fma_f32 v[24:25], v[16:17], v[34:35], v[8:9] op_sel_hi:[1,0,1]
	s_waitcnt lgkmcnt(4)
	v_pk_mul_f32 v[34:35], v[22:23], v[50:51]
	v_pk_mul_f32 v[36:37], v[22:23], v[18:19]
	v_pk_fma_f32 v[34:35], v[24:25], v[52:53], v[34:35]
	v_pk_fma_f32 v[36:37], v[24:25], v[20:21], v[36:37]
	ds_read_b128 v[10:13], v68 offset:41280
	ds_read_b128 v[6:9], v68 offset:41024
	ds_read_b32 v28, v69 offset:42048
	ds_read_b128 v[2:5], v68 offset:40768
	ds_read_b128 v[14:17], v68 offset:41536
	ds_read_b128 v[18:21], v68 offset:41792
	v_add_f32_e32 v34, v34, v35
	v_add_f32_e32 v36, v36, v37
	v_pk_mul_f32 v[46:47], v[46:47], v[62:63] op_sel_hi:[1,0]
	v_add_f32_dpp v34, v34, v34 row_ror:1 row_mask:0xf bank_mask:0xf bound_ctrl:1
	v_add_f32_dpp v36, v36, v36 row_ror:1 row_mask:0xf bank_mask:0xf bound_ctrl:1
	s_waitcnt lgkmcnt(8)
	v_pk_fma_f32 v[46:47], v[22:23], v[42:43], v[46:47]
	v_add_f32_dpp v34, v34, v34 row_ror:2 row_mask:0xf bank_mask:0xf bound_ctrl:1
	v_add_f32_dpp v36, v36, v36 row_ror:2 row_mask:0xf bank_mask:0xf bound_ctrl:1
	v_pk_mul_f32 v[48:49], v[48:49], v[62:63] op_sel_hi:[1,0]
	v_add_f32_dpp v34, v34, v34 row_ror:4 row_mask:0xf bank_mask:0xf bound_ctrl:1
	v_pk_fma_f32 v[48:49], v[24:25], v[44:45], v[48:49]
	s_nop 0
	v_add_f32_dpp v34, v34, v34 row_ror:8 row_mask:0xf bank_mask:0xf bound_ctrl:1
	v_pk_fma_f32 v[22:23], v[54:55], v[34:35], v[46:47] op_sel_hi:[1,0,1]
	v_pk_fma_f32 v[24:25], v[56:57], v[34:35], v[48:49] op_sel_hi:[1,0,1]
	s_waitcnt lgkmcnt(3)
	v_pk_mul_f32 v[34:35], v[22:23], v[10:11]
	v_pk_mul_f32 v[66:67], v[22:23], v[58:59]
	v_pk_fma_f32 v[34:35], v[24:25], v[12:13], v[34:35]
	v_pk_fma_f32 v[66:67], v[24:25], v[60:61], v[66:67]
	ds_read_b128 v[50:53], v68 offset:42848
	ds_read_b128 v[46:49], v68 offset:42592
	ds_read_b32 v62, v69 offset:43616
	ds_read_b128 v[42:45], v68 offset:42336
	ds_read_b128 v[54:57], v68 offset:43104
	ds_read_b128 v[58:61], v68 offset:43360
	v_add_f32_e32 v34, v34, v35
	v_add_f32_e32 v66, v66, v67
	v_pk_mul_f32 v[6:7], v[6:7], v[28:29] op_sel_hi:[1,0]
	v_add_f32_dpp v34, v34, v34 row_ror:1 row_mask:0xf bank_mask:0xf bound_ctrl:1
	v_add_f32_dpp v66, v66, v66 row_ror:1 row_mask:0xf bank_mask:0xf bound_ctrl:1
	s_waitcnt lgkmcnt(7)
	v_pk_fma_f32 v[6:7], v[22:23], v[2:3], v[6:7]
	v_add_f32_dpp v34, v34, v34 row_ror:2 row_mask:0xf bank_mask:0xf bound_ctrl:1
	v_add_f32_dpp v66, v66, v66 row_ror:2 row_mask:0xf bank_mask:0xf bound_ctrl:1
	v_pk_mul_f32 v[8:9], v[8:9], v[28:29] op_sel_hi:[1,0]
	v_add_f32_dpp v34, v34, v34 row_ror:4 row_mask:0xf bank_mask:0xf bound_ctrl:1
	v_pk_fma_f32 v[8:9], v[24:25], v[4:5], v[8:9]
	ds_write2st64_b32 v71, v36, v66 offset0:24 offset1:25
	v_add_f32_dpp v34, v34, v34 row_ror:8 row_mask:0xf bank_mask:0xf bound_ctrl:1
	v_pk_fma_f32 v[22:23], v[14:15], v[34:35], v[6:7] op_sel_hi:[1,0,1]
	v_pk_fma_f32 v[24:25], v[16:17], v[34:35], v[8:9] op_sel_hi:[1,0,1]
	s_waitcnt lgkmcnt(4)
	v_pk_mul_f32 v[34:35], v[22:23], v[50:51]
	v_pk_mul_f32 v[36:37], v[22:23], v[18:19]
	v_pk_fma_f32 v[34:35], v[24:25], v[52:53], v[34:35]
	v_pk_fma_f32 v[36:37], v[24:25], v[20:21], v[36:37]
	ds_read_b128 v[10:13], v68 offset:44416
	ds_read_b128 v[6:9], v68 offset:44160
	ds_read_b32 v28, v69 offset:45184
	ds_read_b128 v[2:5], v68 offset:43904
	ds_read_b128 v[14:17], v68 offset:44672
	ds_read_b128 v[18:21], v68 offset:44928
	v_add_f32_e32 v34, v34, v35
	v_add_f32_e32 v36, v36, v37
	v_pk_mul_f32 v[46:47], v[46:47], v[62:63] op_sel_hi:[1,0]
	v_add_f32_dpp v34, v34, v34 row_ror:1 row_mask:0xf bank_mask:0xf bound_ctrl:1
	v_add_f32_dpp v36, v36, v36 row_ror:1 row_mask:0xf bank_mask:0xf bound_ctrl:1
	s_waitcnt lgkmcnt(8)
	v_pk_fma_f32 v[46:47], v[22:23], v[42:43], v[46:47]
	v_add_f32_dpp v34, v34, v34 row_ror:2 row_mask:0xf bank_mask:0xf bound_ctrl:1
	v_add_f32_dpp v36, v36, v36 row_ror:2 row_mask:0xf bank_mask:0xf bound_ctrl:1
	v_pk_mul_f32 v[48:49], v[48:49], v[62:63] op_sel_hi:[1,0]
	v_add_f32_dpp v34, v34, v34 row_ror:4 row_mask:0xf bank_mask:0xf bound_ctrl:1
	v_pk_fma_f32 v[48:49], v[24:25], v[44:45], v[48:49]
	s_nop 0
	v_add_f32_dpp v34, v34, v34 row_ror:8 row_mask:0xf bank_mask:0xf bound_ctrl:1
	v_pk_fma_f32 v[22:23], v[54:55], v[34:35], v[46:47] op_sel_hi:[1,0,1]
	v_pk_fma_f32 v[24:25], v[56:57], v[34:35], v[48:49] op_sel_hi:[1,0,1]
	s_waitcnt lgkmcnt(3)
	v_pk_mul_f32 v[34:35], v[22:23], v[10:11]
	v_pk_mul_f32 v[66:67], v[22:23], v[58:59]
	v_pk_fma_f32 v[34:35], v[24:25], v[12:13], v[34:35]
	v_pk_fma_f32 v[66:67], v[24:25], v[60:61], v[66:67]
	ds_read_b128 v[50:53], v68 offset:45984
	ds_read_b128 v[46:49], v68 offset:45728
	ds_read_b32 v62, v69 offset:46752
	ds_read_b128 v[42:45], v68 offset:45472
	ds_read_b128 v[54:57], v68 offset:46240
	ds_read_b128 v[58:61], v68 offset:46496
	v_add_f32_e32 v34, v34, v35
	v_add_f32_e32 v66, v66, v67
	v_pk_mul_f32 v[6:7], v[6:7], v[28:29] op_sel_hi:[1,0]
	v_add_f32_dpp v34, v34, v34 row_ror:1 row_mask:0xf bank_mask:0xf bound_ctrl:1
	v_add_f32_dpp v66, v66, v66 row_ror:1 row_mask:0xf bank_mask:0xf bound_ctrl:1
	s_waitcnt lgkmcnt(7)
; template <int CTRL> __device__ __forceinline__ float dpp_f(float x) { return __int_as_float(__builtin_amdgcn_update_dpp(0, __float_as_int(x), CTRL, 0xf, 0xf, false)); }
; __device__ __forceinline__ void p8_scan(const Args& a, LAS unsigned char* lds) {
;     ...
;             for (int c = 0; c < T / TC; ++c) {
;     ...
;                 for (int tt = 0; tt < TC; ++tt) {
;                     ScanOps n; scan_ld(n, bt + (tt + 1 < TC ? tt + 1 : tt) * SPITCH, jq4, myrow);
;                     __builtin_amdgcn_sched_barrier(0);
;                     f32x2 ta = S01 * o.al.lo, ty = S01 * o.wr.lo; ta = S23 * o.al.hi + ta; ty = S23 * o.wr.hi + ty;
;                     float pa = ta.x + ta.y, py = ty.x + ty.y;
;                     f32x2 kv01 = o.kv.lo * o.vi, kv23 = o.kv.hi * o.vi;
;     ...
;                     asm volatile("" : "+v"(kv01), "+v"(kv23), "+v"(vc));
;                     pa += dpp_f<0x121>(pa); py += dpp_f<0x121>(py); pa += dpp_f<0x122>(pa); py += dpp_f<0x122>(py);
;                     pa += dpp_f<0x124>(pa); pa += dpp_f<0x128>(pa);
;                     S01 = S01 * o.wv.lo + (o.be.lo * pa + kv01);
;                     S23 = S23 * o.wv.hi + (o.be.hi * pa + kv23);
;     ...
;                     __builtin_amdgcn_sched_barrier(0);
;                     o = n;
;                 }
;                 __syncthreads();
	v_pk_fma_f32 v[6:7], v[22:23], v[2:3], v[6:7]
	v_add_f32_dpp v34, v34, v34 row_ror:2 row_mask:0xf bank_mask:0xf bound_ctrl:1
	v_add_f32_dpp v66, v66, v66 row_ror:2 row_mask:0xf bank_mask:0xf bound_ctrl:1
	v_pk_mul_f32 v[8:9], v[8:9], v[28:29] op_sel_hi:[1,0]
	v_add_f32_dpp v34, v34, v34 row_ror:4 row_mask:0xf bank_mask:0xf bound_ctrl:1
	v_pk_fma_f32 v[8:9], v[24:25], v[4:5], v[8:9]
	ds_write2st64_b32 v71, v36, v66 offset0:26 offset1:27
	v_add_f32_dpp v34, v34, v34 row_ror:8 row_mask:0xf bank_mask:0xf bound_ctrl:1
	v_pk_fma_f32 v[22:23], v[14:15], v[34:35], v[6:7] op_sel_hi:[1,0,1]
	v_pk_fma_f32 v[24:25], v[16:17], v[34:35], v[8:9] op_sel_hi:[1,0,1]
	s_waitcnt lgkmcnt(4)
	v_pk_mul_f32 v[34:35], v[22:23], v[50:51]
	v_pk_mul_f32 v[36:37], v[22:23], v[18:19]
	v_pk_fma_f32 v[34:35], v[24:25], v[52:53], v[34:35]
	v_pk_fma_f32 v[36:37], v[24:25], v[20:21], v[36:37]
	ds_read_b128 v[10:13], v68 offset:47552
	ds_read_b128 v[6:9], v68 offset:47296
	ds_read_b32 v28, v69 offset:48320
	ds_read_b128 v[2:5], v68 offset:47040
	ds_read_b128 v[14:17], v68 offset:47808
	ds_read_b128 v[18:21], v68 offset:48064
	v_add_f32_e32 v34, v34, v35
	v_add_f32_e32 v36, v36, v37
	v_pk_mul_f32 v[46:47], v[46:47], v[62:63] op_sel_hi:[1,0]
	v_add_f32_dpp v34, v34, v34 row_ror:1 row_mask:0xf bank_mask:0xf bound_ctrl:1
	v_add_f32_dpp v36, v36, v36 row_ror:1 row_mask:0xf bank_mask:0xf bound_ctrl:1
	s_waitcnt lgkmcnt(8)
	v_pk_fma_f32 v[46:47], v[22:23], v[42:43], v[46:47]
	v_add_f32_dpp v34, v34, v34 row_ror:2 row_mask:0xf bank_mask:0xf bound_ctrl:1
	v_add_f32_dpp v36, v36, v36 row_ror:2 row_mask:0xf bank_mask:0xf bound_ctrl:1
	v_pk_mul_f32 v[48:49], v[48:49], v[62:63] op_sel_hi:[1,0]
	v_add_f32_dpp v34, v34, v34 row_ror:4 row_mask:0xf bank_mask:0xf bound_ctrl:1
	v_pk_fma_f32 v[48:49], v[24:25], v[44:45], v[48:49]
	s_nop 0
	v_add_f32_dpp v34, v34, v34 row_ror:8 row_mask:0xf bank_mask:0xf bound_ctrl:1
	v_pk_fma_f32 v[22:23], v[54:55], v[34:35], v[46:47] op_sel_hi:[1,0,1]
	v_pk_fma_f32 v[24:25], v[56:57], v[34:35], v[48:49] op_sel_hi:[1,0,1]
	s_waitcnt lgkmcnt(3)
	s_barrier
	v_pk_mul_f32 v[34:35], v[22:23], v[10:11]
	v_pk_mul_f32 v[66:67], v[22:23], v[58:59]
	v_pk_fma_f32 v[34:35], v[24:25], v[12:13], v[34:35]
	v_pk_fma_f32 v[66:67], v[24:25], v[60:61], v[66:67]
	ds_read_b128 v[50:53], v68 offset:49120
	ds_read_b128 v[46:49], v68 offset:48864
	ds_read_b32 v62, v69 offset:49888
	ds_read_b128 v[42:45], v68 offset:48608
	ds_read_b128 v[54:57], v68 offset:49376
	ds_read_b128 v[58:61], v68 offset:49632
	v_add_f32_e32 v34, v34, v35
	v_add_f32_e32 v66, v66, v67
	v_pk_mul_f32 v[6:7], v[6:7], v[28:29] op_sel_hi:[1,0]
	v_add_f32_dpp v34, v34, v34 row_ror:1 row_mask:0xf bank_mask:0xf bound_ctrl:1
	v_add_f32_dpp v66, v66, v66 row_ror:1 row_mask:0xf bank_mask:0xf bound_ctrl:1
	s_waitcnt lgkmcnt(7)
	v_pk_fma_f32 v[6:7], v[22:23], v[2:3], v[6:7]
	v_add_f32_dpp v34, v34, v34 row_ror:2 row_mask:0xf bank_mask:0xf bound_ctrl:1
	v_add_f32_dpp v66, v66, v66 row_ror:2 row_mask:0xf bank_mask:0xf bound_ctrl:1
	v_pk_mul_f32 v[8:9], v[8:9], v[28:29] op_sel_hi:[1,0]
	v_add_f32_dpp v34, v34, v34 row_ror:4 row_mask:0xf bank_mask:0xf bound_ctrl:1
	v_pk_fma_f32 v[8:9], v[24:25], v[4:5], v[8:9]
	ds_write2st64_b32 v71, v36, v66 offset0:28 offset1:29
	v_add_f32_dpp v34, v34, v34 row_ror:8 row_mask:0xf bank_mask:0xf bound_ctrl:1
	v_pk_fma_f32 v[22:23], v[14:15], v[34:35], v[6:7] op_sel_hi:[1,0,1]
	v_pk_fma_f32 v[24:25], v[16:17], v[34:35], v[8:9] op_sel_hi:[1,0,1]
	s_waitcnt lgkmcnt(4)
	v_pk_mul_f32 v[34:35], v[22:23], v[50:51]
	v_pk_mul_f32 v[36:37], v[22:23], v[18:19]
	v_pk_fma_f32 v[34:35], v[24:25], v[52:53], v[34:35]
	v_pk_fma_f32 v[36:37], v[24:25], v[20:21], v[36:37]
	ds_read_b128 v[10:13], v38 offset:512
	ds_read_b128 v[6:9], v38 offset:256
	ds_read_b32 v28, v39 offset:1280
	ds_read_b128 v[2:5], v38 offset:0
	ds_read_b128 v[14:17], v38 offset:768
	ds_read_b128 v[18:21], v38 offset:1024
	v_add_f32_e32 v34, v34, v35
	v_add_f32_e32 v36, v36, v37
	v_pk_mul_f32 v[46:47], v[46:47], v[62:63] op_sel_hi:[1,0]
	v_add_f32_dpp v34, v34, v34 row_ror:1 row_mask:0xf bank_mask:0xf bound_ctrl:1
	v_add_f32_dpp v36, v36, v36 row_ror:1 row_mask:0xf bank_mask:0xf bound_ctrl:1
	s_waitcnt lgkmcnt(7)
	v_pk_fma_f32 v[46:47], v[22:23], v[42:43], v[46:47]
	v_add_f32_dpp v34, v34, v34 row_ror:2 row_mask:0xf bank_mask:0xf bound_ctrl:1
	v_add_f32_dpp v36, v36, v36 row_ror:2 row_mask:0xf bank_mask:0xf bound_ctrl:1
	v_pk_mul_f32 v[48:49], v[48:49], v[62:63] op_sel_hi:[1,0]
	v_add_f32_dpp v34, v34, v34 row_ror:4 row_mask:0xf bank_mask:0xf bound_ctrl:1
	v_pk_fma_f32 v[48:49], v[24:25], v[44:45], v[48:49]
	s_nop 0
	v_add_f32_dpp v34, v34, v34 row_ror:8 row_mask:0xf bank_mask:0xf bound_ctrl:1
	v_pk_fma_f32 v[22:23], v[54:55], v[34:35], v[46:47] op_sel_hi:[1,0,1]
	v_pk_fma_f32 v[24:25], v[56:57], v[34:35], v[48:49] op_sel_hi:[1,0,1]
	v_pk_mul_f32 v[66:67], v[22:23], v[58:59]
	v_pk_fma_f32 v[66:67], v[24:25], v[60:61], v[66:67]
	v_add_f32_e32 v66, v66, v67
	s_nop 1
	v_add_f32_dpp v66, v66, v66 row_ror:1 row_mask:0xf bank_mask:0xf bound_ctrl:1
	s_nop 1
	v_add_f32_dpp v66, v66, v66 row_ror:2 row_mask:0xf bank_mask:0xf bound_ctrl:1
	ds_write2st64_b32 v71, v36, v66 offset0:30 offset1:31
	s_waitcnt lgkmcnt(0)
	s_barrier
	s_add_i32 s14, s14, 2
	s_cmpk_eq_i32 s14, 0x100
	s_cbranch_scc0 .Lscan_chunk_pair
	s_setprio 0
	s_mov_b64 s[44:45], 0

; __device__ __forceinline__ void p8_scan(const Args& a, LAS unsigned char* lds) {
;     ...
;             for (int c = 0; c < T / TC; c += 2) { PROD_STEP(c, A0, A1); PROD_STEP(c + 1, B0, B1); }
.LBB0_1106:
	s_add_i32 s14, s14, 2
	v_lshl_add_u64 v[60:61], v[60:61], 0, s[34:35]
	v_lshl_add_u64 v[66:67], v[66:67], 0, s[28:29]
	v_lshl_add_u64 v[106:107], v[106:107], 0, s[18:19]
	v_lshl_add_u64 v[100:101], v[100:101], 0, s[34:35]
	v_lshl_add_u64 v[70:71], v[70:71], 0, s[34:35]
	s_add_i32 s73, s73, 64
	v_lshl_add_u64 v[74:75], v[74:75], 0, s[28:29]
	v_lshl_add_u64 v[78:79], v[78:79], 0, s[38:39]
	v_lshl_add_u64 v[104:105], v[104:105], 0, s[18:19]
	s_and_b64 vcc, exec, s[52:53]
	s_waitcnt lgkmcnt(0)
	s_barrier
	s_barrier
	s_cbranch_vccnz .LBB0_1086

; #define LAS __attribute__((address_space(3)))
; __device__ __forceinline__ float f16_to_f(unsigned short h) { return (float)__builtin_bit_cast(_Float16, h); }
; __device__ __forceinline__ float scan_prepare(const ScanRegs& R, const u32x2 qr_, const u32x2 qk_, const u32x2 qv_, LAS float* slot, int cq, const f32x4 mur, const f32x4 muk, const f32x4 muv, const f32x4 kkc, const f32x4 kac, const f32x4 rkc) {
;     float pr[4], pk[4], pv[4], qr[4], qk[4], qv[4], av[4], om[4];
;     unpack4(R.pr, pr); unpack4(R.pk, pk); unpack4(R.pv, pv); unpack4(qr_, qr); unpack4(qk_, qk); unpack4(qv_, qv); unpack4(R.as, av);
;     om[0] = f16_to_f((unsigned short)(R.wl.x & 0xffffu)); om[1] = f16_to_f((unsigned short)(R.wl.x >> 16)); om[2] = f16_to_f((unsigned short)(R.wl.y & 0xffffu)); om[3] = f16_to_f((unsigned short)(R.wl.y >> 16));
;     float rr[4], vv[4], kn[4], k2[4], dec[4], bu[4];
;     float ssq = 0.f, bon = 0.f, c1 = 0.f, c2 = 0.f;
; #pragma unroll
;     for (int j = 0; j < 4; ++j) {
;         rr[j] = pr[j] + (qr[j] - pr[j]) * mur[j]; const float kk0 = pk[j] + (qk[j] - pk[j]) * muk[j]; vv[j] = pv[j] + (qv[j] - pv[j]) * muv[j];
;         dec[j] = 1.0f - om[j];
;         kn[j] = kk0 * kkc[j]; ssq += kn[j] * kn[j];
;         k2[j] = kk0 * (1.0f + (av[j] - 1.0f) * kac[j]);
;         const float t = rr[j] * k2[j]; bon += t * rkc[j]; c2 += t;
;         bu[j] = kn[j] * av[j]; c1 += bu[j] * rr[j];
;     }
;     ssq += dpp_f<0x121>(ssq); bon += dpp_f<0x121>(bon); c1 += dpp_f<0x121>(c1); c2 += dpp_f<0x121>(c2);
;     ssq += dpp_f<0x122>(ssq); bon += dpp_f<0x122>(bon); c1 += dpp_f<0x122>(c1); c2 += dpp_f<0x122>(c2);
;     ssq += dpp_f<0x124>(ssq); bon += dpp_f<0x124>(bon); c1 += dpp_f<0x124>(c1); c2 += dpp_f<0x124>(c2);
;     ssq += dpp_f<0x128>(ssq); bon += dpp_f<0x128>(bon); c1 += dpp_f<0x128>(c1); c2 += dpp_f<0x128>(c2);
;     const float inv = __builtin_amdgcn_rsqf(fmaxf(ssq, 1e-24f));
;     f32x4 o_al, o_be, o_wr;
; #pragma unroll
;     for (int j = 0; j < 4; ++j) { o_al[j] = -(kn[j] * inv); o_be[j] = bu[j] * inv; o_wr[j] = dec[j] * rr[j]; }
;     LAS f32x4* s4 = (LAS f32x4*)slot;
;     s4[cq] = (f32x4){dec[0], dec[1], dec[2], dec[3]}; s4[16 + cq] = (f32x4){k2[0], k2[1], k2[2], k2[3]}; s4[32 + cq] = o_al; s4[48 + cq] = o_be; s4[64 + cq] = o_wr;
;     s4[80 + cq] = (f32x4){vv[0], vv[1], vv[2], vv[3]};
;     if (cq == 0) *(LAS f32x2*)(slot + 384) = (f32x2){c1 * inv, c2};
.LBB0_1115:
	v_add_u32_e32 v28, v120, v130
	s_waitcnt lgkmcnt(0)
	s_barrier
	s_barrier
	ds_read_b128 v[108:111], v28
	v_lshl_add_u64 v[112:113], s[92:93], 0, v[100:101]
	v_add_co_u32_e32 v112, vcc, s68, v112
	s_cmpk_gt_u32 s14, 0xfd
	s_waitcnt lgkmcnt(0)
	v_add_f32_e32 v28, v108, v109
	v_add_f32_e32 v33, v110, v111
	v_add_f32_e32 v28, v28, v33
	v_bfe_u32 v33, v28, 16, 1
	v_add3_u32 v28, v28, v33, s67
	v_addc_co_u32_e32 v113, vcc, 0, v113, vcc
	global_store_short_d16_hi v[112:113], v28, off
	v_add_u32_e32 v28, v120, v131
	ds_read_b128 v[108:111], v28
	s_cselect_b64 s[52:53], -1, 0
	s_and_b64 vcc, exec, s[52:53]
	s_waitcnt lgkmcnt(0)
	v_add_f32_e32 v28, v108, v109
	v_add_f32_e32 v33, v110, v111
	v_add_f32_e32 v28, v28, v33
	v_bfe_u32 v33, v28, 16, 1
	v_add3_u32 v28, v28, v33, s67
	global_store_short_d16_hi v[112:113], v28, off offset:2048
	s_cbranch_vccnz .LBB0_1106
	v_lshlrev_b32_e32 v108, 16, v76
	v_and_b32_e32 v109, 0xffff0000, v76
	v_lshlrev_b32_e32 v110, 16, v62
	v_and_b32_e32 v111, 0xffff0000, v62
	v_pk_add_f32 v[110:111], v[110:111], v[108:109] neg_lo:[0,1] neg_hi:[0,1]
	v_lshlrev_b32_e32 v140, 16, v63
	v_pk_fma_f32 v[144:145], v[6:7], v[110:111], v[108:109]
	v_lshlrev_b32_e32 v110, 16, v77
	v_and_b32_e32 v111, 0xffff0000, v77
	v_and_b32_e32 v141, 0xffff0000, v63
	v_pk_add_f32 v[140:141], v[140:141], v[110:111] neg_lo:[0,1] neg_hi:[0,1]
	v_lshlrev_b32_e32 v118, 16, v64
	v_and_b32_e32 v119, 0xffff0000, v64
	v_pk_fma_f32 v[146:147], v[8:9], v[140:141], v[110:111]
	v_lshlrev_b32_e32 v140, 16, v54
	v_and_b32_e32 v141, 0xffff0000, v54
	s_waitcnt vmcnt(3)
	v_lshlrev_b32_e32 v142, 16, v86
	v_and_b32_e32 v143, 0xffff0000, v86
	v_pk_add_f32 v[140:141], v[140:141], v[118:119] neg_lo:[0,1] neg_hi:[0,1]
	v_pk_add_f32 v[148:149], v[142:143], -1.0 op_sel_hi:[1,0]
	v_pk_fma_f32 v[140:141], v[2:3], v[140:141], v[118:119]
	v_pk_fma_f32 v[148:149], v[18:19], v[148:149], 1.0 op_sel_hi:[1,1,0]
	v_pk_mul_f32 v[154:155], v[14:15], v[140:141]
	v_pk_mul_f32 v[148:149], v[140:141], v[148:149]
	v_cvt_f32_f16_sdwa v141, v72 dst_sel:DWORD dst_unused:UNUSED_PAD src0_sel:WORD_1
	v_cvt_f32_f16_e32 v140, v72
	v_lshlrev_b32_e32 v114, 16, v56
	v_and_b32_e32 v115, 0xffff0000, v56
	v_lshlrev_b32_e32 v156, 16, v68
	v_and_b32_e32 v157, 0xffff0000, v68
	v_pk_add_f32 v[152:153], v[140:141], 1.0 op_sel_hi:[1,0] neg_lo:[1,0] neg_hi:[1,0]
	v_pk_add_f32 v[140:141], v[156:157], v[114:115] neg_lo:[0,1] neg_hi:[0,1]
	v_lshlrev_b32_e32 v116, 16, v65
	v_pk_fma_f32 v[164:165], v[10:11], v[140:141], v[114:115]
	v_and_b32_e32 v117, 0xffff0000, v65
	v_pk_mul_f32 v[140:141], v[164:165], v[148:149]
	v_pk_mul_f32 v[150:151], v[154:155], v[154:155]
	v_fma_f32 v33, v22, v140, 0
	v_add_f32_e32 v28, 0, v140
	v_fmac_f32_e32 v33, v23, v141
	v_add_f32_e32 v168, v141, v28
	v_lshlrev_b32_e32 v140, 16, v55
	v_and_b32_e32 v141, 0xffff0000, v55
	v_pk_add_f32 v[140:141], v[140:141], v[116:117] neg_lo:[0,1] neg_hi:[0,1]
	v_add_f32_e32 v28, v150, v151
	v_pk_fma_f32 v[140:141], v[4:5], v[140:141], v[116:117]
	v_pk_mul_f32 v[142:143], v[154:155], v[142:143]
	v_pk_mul_f32 v[158:159], v[16:17], v[140:141]
	v_pk_mul_f32 v[156:157], v[164:165], v[142:143]
	v_pk_mul_f32 v[160:161], v[158:159], v[158:159]
	v_add_f32_e32 v81, 0, v156
	v_add_f32_e32 v28, v160, v28
	v_add_f32_e32 v28, v161, v28
	v_add_f32_e32 v81, v157, v81
	v_lshlrev_b32_e32 v156, 16, v87
	v_add_f32_dpp v28, v28, v28 row_ror:1 row_mask:0xf bank_mask:0xf bound_ctrl:1
	v_and_b32_e32 v157, 0xffff0000, v87
	v_lshlrev_b32_e32 v112, 16, v57
	v_add_f32_dpp v28, v28, v28 row_ror:2 row_mask:0xf bank_mask:0xf bound_ctrl:1
	v_and_b32_e32 v113, 0xffff0000, v57
	v_pk_add_f32 v[162:163], v[156:157], -1.0 op_sel_hi:[1,0]
	v_add_f32_dpp v28, v28, v28 row_ror:4 row_mask:0xf bank_mask:0xf bound_ctrl:1
	v_pk_fma_f32 v[150:151], v[20:21], v[162:163], 1.0 op_sel_hi:[1,1,0]
	v_pk_mul_f32 v[164:165], v[164:165], 1.0 op_sel_hi:[1,0]
	v_add_f32_dpp v28, v28, v28 row_ror:8 row_mask:0xf bank_mask:0xf bound_ctrl:1
	v_max_f32_e32 v28, 0x179abe15, v28
	v_rsq_f32_e32 v28, v28
	v_pk_mul_f32 v[150:151], v[140:141], v[150:151]
	v_pk_mul_f32 v[140:141], v[158:159], v[156:157]
	v_pk_mul_f32 v[160:161], v[142:143], v[28:29] op_sel_hi:[1,0]
	v_lshlrev_b32_e32 v142, 16, v69
	v_and_b32_e32 v143, 0xffff0000, v69
	v_pk_add_f32 v[142:143], v[142:143], v[112:113] neg_lo:[0,1] neg_hi:[0,1]
	v_pk_mul_f32 v[162:163], v[140:141], v[28:29] op_sel_hi:[1,0]
	v_pk_fma_f32 v[166:167], v[12:13], v[142:143], v[112:113]
	v_pk_mul_f32 v[156:157], v[154:155], v[28:29] op_sel_hi:[1,0] neg_lo:[0,1] neg_hi:[0,1]
	v_pk_mul_f32 v[142:143], v[166:167], v[150:151]
	v_pk_mul_f32 v[140:141], v[166:167], v[140:141]
	v_fmac_f32_e32 v33, v24, v142
	v_add_f32_e32 v142, v142, v168
	v_add_f32_e32 v81, v140, v81
	v_cvt_f32_f16_sdwa v155, v73 dst_sel:DWORD dst_unused:UNUSED_PAD src0_sel:WORD_1
	v_cvt_f32_f16_e32 v154, v73
	v_fmac_f32_e32 v33, v25, v143
	v_add_f32_e32 v140, v143, v142
	v_add_f32_e32 v81, v141, v81
	v_add_f32_dpp v33, v33, v33 row_ror:1 row_mask:0xf bank_mask:0xf bound_ctrl:1
	v_add_f32_dpp v140, v140, v140 row_ror:1 row_mask:0xf bank_mask:0xf bound_ctrl:1
	v_add_f32_dpp v81, v81, v81 row_ror:1 row_mask:0xf bank_mask:0xf bound_ctrl:1
	v_add_f32_dpp v33, v33, v33 row_ror:2 row_mask:0xf bank_mask:0xf bound_ctrl:1
	v_add_f32_dpp v140, v140, v140 row_ror:2 row_mask:0xf bank_mask:0xf bound_ctrl:1
	v_add_f32_dpp v81, v81, v81 row_ror:2 row_mask:0xf bank_mask:0xf bound_ctrl:1
	v_add_f32_dpp v33, v33, v33 row_ror:4 row_mask:0xf bank_mask:0xf bound_ctrl:1
	v_add_f32_dpp v140, v140, v140 row_ror:4 row_mask:0xf bank_mask:0xf bound_ctrl:1
	v_add_f32_dpp v141, v81, v81 row_ror:4 row_mask:0xf bank_mask:0xf bound_ctrl:1
	v_mov_b32_e32 v142, 0
	v_mov_b32_e32 v143, 0
	v_mov_b32_e32 v81, 0
	v_pk_add_f32 v[154:155], v[154:155], 1.0 op_sel_hi:[1,0] neg_lo:[1,0] neg_hi:[1,0]
	v_mov_b32_dpp v142, v141 row_ror:8 row_mask:0xf bank_mask:0xf
	v_mov_b32_dpp v143, v140 row_ror:8 row_mask:0xf bank_mask:0xf
	v_mov_b32_dpp v81, v33 row_ror:8 row_mask:0xf bank_mask:0xf
	v_pk_mul_f32 v[158:159], v[158:159], v[28:29] op_sel_hi:[1,0] neg_lo:[0,1] neg_hi:[0,1]
	v_pk_mul_f32 v[166:167], v[166:167], 1.0 op_sel_hi:[1,0]
	ds_write_b128 v127, v[152:155]
	ds_write_b128 v127, v[148:151] offset:256
	ds_write_b128 v127, v[156:159] offset:512
	ds_write_b128 v127, v[160:163] offset:768
	ds_write_b128 v127, v[164:167] offset:1024
	ds_write_b128 v127, v[144:147] offset:1280
	s_and_saveexec_b64 s[56:57], s[4:5]
	v_add_f32_e32 v141, v141, v142
	v_mul_f32_e32 v142, v141, v28
	v_add_f32_e32 v143, v140, v143
	ds_write_b64 v126, v[142:143] offset:1536
	s_or_b64 exec, exec, s[56:57]
	s_waitcnt vmcnt(4)
; #define LAS __attribute__((address_space(3)))
; __device__ __forceinline__ float scan_prepare(const ScanRegs& R, const u32x2 qr_, const u32x2 qk_, const u32x2 qv_, LAS float* slot, int cq, const f32x4 mur, const f32x4 muk, const f32x4 muv, const f32x4 kkc, const f32x4 kac, const f32x4 rkc) {
;     float pr[4], pk[4], pv[4], qr[4], qk[4], qv[4], av[4], om[4];
;     unpack4(R.pr, pr); unpack4(R.pk, pk); unpack4(R.pv, pv); unpack4(qr_, qr); unpack4(qk_, qk); unpack4(qv_, qv); unpack4(R.as, av);
;     om[0] = f16_to_f((unsigned short)(R.wl.x & 0xffffu)); om[1] = f16_to_f((unsigned short)(R.wl.x >> 16)); om[2] = f16_to_f((unsigned short)(R.wl.y & 0xffffu)); om[3] = f16_to_f((unsigned short)(R.wl.y >> 16));
;     float rr[4], vv[4], kn[4], k2[4], dec[4], bu[4];
;     float ssq = 0.f, bon = 0.f, c1 = 0.f, c2 = 0.f;
; #pragma unroll
;     for (int j = 0; j < 4; ++j) {
;         rr[j] = pr[j] + (qr[j] - pr[j]) * mur[j]; const float kk0 = pk[j] + (qk[j] - pk[j]) * muk[j]; vv[j] = pv[j] + (qv[j] - pv[j]) * muv[j];
;         dec[j] = 1.0f - om[j];
;         kn[j] = kk0 * kkc[j]; ssq += kn[j] * kn[j];
;         k2[j] = kk0 * (1.0f + (av[j] - 1.0f) * kac[j]);
;         const float t = rr[j] * k2[j]; bon += t * rkc[j]; c2 += t;
;         bu[j] = kn[j] * av[j]; c1 += bu[j] * rr[j];
;     }
;     ssq += dpp_f<0x121>(ssq); bon += dpp_f<0x121>(bon); c1 += dpp_f<0x121>(c1); c2 += dpp_f<0x121>(c2);
;     ssq += dpp_f<0x122>(ssq); bon += dpp_f<0x122>(bon); c1 += dpp_f<0x122>(c1); c2 += dpp_f<0x122>(c2);
;     ssq += dpp_f<0x124>(ssq); bon += dpp_f<0x124>(bon); c1 += dpp_f<0x124>(c1); c2 += dpp_f<0x124>(c2);
;     ssq += dpp_f<0x128>(ssq); bon += dpp_f<0x128>(bon); c1 += dpp_f<0x128>(c1); c2 += dpp_f<0x128>(c2);
;     const float inv = __builtin_amdgcn_rsqf(fmaxf(ssq, 1e-24f));
;     f32x4 o_al, o_be, o_wr;
; #pragma unroll
;     for (int j = 0; j < 4; ++j) { o_al[j] = -(kn[j] * inv); o_be[j] = bu[j] * inv; o_wr[j] = dec[j] * rr[j]; }
;     LAS f32x4* s4 = (LAS f32x4*)slot;
;     s4[cq] = (f32x4){dec[0], dec[1], dec[2], dec[3]}; s4[16 + cq] = (f32x4){k2[0], k2[1], k2[2], k2[3]}; s4[32 + cq] = o_al; s4[48 + cq] = o_be; s4[64 + cq] = o_wr;
;     s4[80 + cq] = (f32x4){vv[0], vv[1], vv[2], vv[3]};
;     if (cq == 0) *(LAS f32x2*)(slot + 384) = (f32x2){c1 * inv, c2};
;     return bon;
; }
	v_lshlrev_b32_e32 v140, 16, v96
	v_and_b32_e32 v141, 0xffff0000, v96
	s_waitcnt vmcnt(2)
	v_lshlrev_b32_e32 v142, 16, v102
	v_and_b32_e32 v143, 0xffff0000, v102
	v_pk_add_f32 v[118:119], v[118:119], v[140:141] neg_lo:[0,1] neg_hi:[0,1]
	v_lshlrev_b32_e32 v150, 16, v103
	v_pk_fma_f32 v[118:119], v[2:3], v[118:119], v[140:141]
	v_pk_add_f32 v[140:141], v[142:143], -1.0 op_sel_hi:[1,0]
	v_pk_mul_f32 v[146:147], v[14:15], v[118:119]
	v_pk_fma_f32 v[140:141], v[18:19], v[140:141], 1.0 op_sel_hi:[1,1,0]
	v_pk_mul_f32 v[152:153], v[146:147], v[142:143]
	v_pk_mul_f32 v[140:141], v[140:141], v[118:119]
	v_cvt_f32_f16_sdwa v119, v98 dst_sel:DWORD dst_unused:UNUSED_PAD src0_sel:WORD_1
	v_cvt_f32_f16_e32 v118, v98
	v_lshlrev_b32_e32 v142, 16, v84
	v_and_b32_e32 v143, 0xffff0000, v84
	v_pk_add_f32 v[114:115], v[114:115], v[142:143] neg_lo:[0,1] neg_hi:[0,1]
	v_pk_add_f32 v[144:145], v[118:119], 1.0 op_sel_hi:[1,0] neg_lo:[1,0] neg_hi:[1,0]
	v_pk_fma_f32 v[118:119], v[10:11], v[114:115], v[142:143]
	v_pk_mul_f32 v[148:149], v[146:147], v[146:147]
	v_pk_mul_f32 v[114:115], v[118:119], v[140:141]
	v_pk_mul_f32 v[142:143], v[118:119], v[152:153]
	v_fma_f32 v156, v22, v114, 0
	v_add_f32_e32 v28, 0, v114
	v_add_f32_e32 v114, 0, v142
	v_fmac_f32_e32 v156, v23, v115
	v_add_f32_e32 v157, v115, v28
	v_add_f32_e32 v164, v143, v114
	v_lshlrev_b32_e32 v114, 16, v97
	v_and_b32_e32 v115, 0xffff0000, v97
	v_pk_add_f32 v[116:117], v[116:117], v[114:115] neg_lo:[0,1] neg_hi:[0,1]
	v_add_f32_e32 v28, v148, v149
	v_pk_fma_f32 v[114:115], v[4:5], v[116:117], v[114:115]
	v_and_b32_e32 v151, 0xffff0000, v103
	v_pk_mul_f32 v[116:117], v[16:17], v[114:115]
	v_pk_add_f32 v[154:155], v[150:151], -1.0 op_sel_hi:[1,0]
	v_pk_mul_f32 v[142:143], v[116:117], v[116:117]
	v_lshlrev_b32_e32 v160, 16, v94
	v_add_f32_e32 v28, v142, v28
	v_add_f32_e32 v28, v143, v28
	v_pk_fma_f32 v[142:143], v[20:21], v[154:155], 1.0 op_sel_hi:[1,1,0]
	v_and_b32_e32 v161, 0xffff0000, v94
	v_add_f32_dpp v28, v28, v28 row_ror:1 row_mask:0xf bank_mask:0xf bound_ctrl:1
	v_pk_mul_f32 v[142:143], v[142:143], v[114:115]
	v_pk_mul_f32 v[114:115], v[116:117], v[150:151]
	v_add_f32_dpp v28, v28, v28 row_ror:2 row_mask:0xf bank_mask:0xf bound_ctrl:1
	v_lshlrev_b32_e32 v162, 16, v95
	v_and_b32_e32 v163, 0xffff0000, v95
	v_add_f32_dpp v28, v28, v28 row_ror:4 row_mask:0xf bank_mask:0xf bound_ctrl:1
	v_pk_add_f32 v[108:109], v[108:109], v[160:161] neg_lo:[0,1] neg_hi:[0,1]
	v_pk_add_f32 v[110:111], v[110:111], v[162:163] neg_lo:[0,1] neg_hi:[0,1]
	v_add_f32_dpp v28, v28, v28 row_ror:8 row_mask:0xf bank_mask:0xf bound_ctrl:1
	v_max_f32_e32 v28, 0x179abe15, v28
	v_rsq_f32_e32 v28, v28
	v_pk_fma_f32 v[110:111], v[8:9], v[110:111], v[162:163]
	v_pk_fma_f32 v[108:109], v[6:7], v[108:109], v[160:161]
	v_pk_mul_f32 v[150:151], v[116:117], v[28:29] op_sel_hi:[1,0] neg_lo:[0,1] neg_hi:[0,1]
	v_lshlrev_b32_e32 v116, 16, v85
	v_and_b32_e32 v117, 0xffff0000, v85
	v_pk_add_f32 v[112:113], v[112:113], v[116:117] neg_lo:[0,1] neg_hi:[0,1]
	v_pk_mul_f32 v[154:155], v[114:115], v[28:29] op_sel_hi:[1,0]
	v_pk_fma_f32 v[158:159], v[12:13], v[112:113], v[116:117]
	v_pk_mul_f32 v[148:149], v[146:147], v[28:29] op_sel_hi:[1,0] neg_lo:[0,1] neg_hi:[0,1]
	v_pk_mul_f32 v[112:113], v[158:159], v[142:143]
	v_pk_mul_f32 v[114:115], v[158:159], v[114:115]
	v_fmac_f32_e32 v156, v24, v112
	v_add_f32_e32 v112, v112, v157
	v_add_f32_e32 v114, v114, v164
	v_cvt_f32_f16_sdwa v147, v99 dst_sel:DWORD dst_unused:UNUSED_PAD src0_sel:WORD_1
	v_cvt_f32_f16_e32 v146, v99
	v_fmac_f32_e32 v156, v25, v113
	v_add_f32_e32 v112, v113, v112
	v_add_f32_e32 v113, v115, v114
	v_add_f32_dpp v114, v156, v156 row_ror:1 row_mask:0xf bank_mask:0xf bound_ctrl:1
	v_add_f32_dpp v112, v112, v112 row_ror:1 row_mask:0xf bank_mask:0xf bound_ctrl:1
	v_add_f32_dpp v113, v113, v113 row_ror:1 row_mask:0xf bank_mask:0xf bound_ctrl:1
	v_add_f32_dpp v114, v114, v114 row_ror:2 row_mask:0xf bank_mask:0xf bound_ctrl:1
	v_add_f32_dpp v116, v112, v112 row_ror:2 row_mask:0xf bank_mask:0xf bound_ctrl:1
	v_add_f32_dpp v113, v113, v113 row_ror:2 row_mask:0xf bank_mask:0xf bound_ctrl:1
	v_add_f32_dpp v112, v114, v114 row_ror:4 row_mask:0xf bank_mask:0xf bound_ctrl:1
	v_add_f32_dpp v114, v116, v116 row_ror:4 row_mask:0xf bank_mask:0xf bound_ctrl:1
	v_add_f32_dpp v115, v113, v113 row_ror:4 row_mask:0xf bank_mask:0xf bound_ctrl:1
	v_mov_b32_e32 v116, 0
	v_mov_b32_e32 v117, 0
	v_mov_b32_e32 v113, 0
	v_pk_add_f32 v[146:147], v[146:147], 1.0 op_sel_hi:[1,0] neg_lo:[1,0] neg_hi:[1,0]
	v_mov_b32_dpp v116, v115 row_ror:8 row_mask:0xf bank_mask:0xf
	v_mov_b32_dpp v117, v114 row_ror:8 row_mask:0xf bank_mask:0xf
	v_mov_b32_dpp v113, v112 row_ror:8 row_mask:0xf bank_mask:0xf
	v_pk_mul_f32 v[152:153], v[152:153], v[28:29] op_sel_hi:[1,0]
	v_pk_mul_f32 v[156:157], v[118:119], 1.0 op_sel_hi:[1,0]
	v_pk_mul_f32 v[158:159], v[158:159], 1.0 op_sel_hi:[1,0]
	ds_write_b128 v129, v[144:147]
	ds_write_b128 v129, v[140:143] offset:256
	ds_write_b128 v129, v[148:151] offset:512
	ds_write_b128 v129, v[152:155] offset:768
	ds_write_b128 v129, v[156:159] offset:1024
	ds_write_b128 v129, v[108:111] offset:1280
	s_and_saveexec_b64 s[56:57], s[4:5]
	s_cbranch_execz .LBB0_1123
	v_add_f32_e32 v108, v115, v116
	v_mul_f32_e32 v108, v108, v28
	v_add_f32_e32 v109, v114, v117
	ds_write_b64 v128, v[108:109] offset:1536
	s_or_b64 exec, exec, s[56:57]
	s_and_saveexec_b64 s[56:57], s[44:45]
	s_cbranch_execnz .LBB0_1124
